# GEMM epilogues P4,P5,P7,P8,P9: packed output re-laid across lanes (ds_bpermute) so each lane quad stores 64 contiguous bytes; stores deferred one slot
# speedup vs baseline: 1.0098x; 1.0098x over previous
; #define PH(k) (IN(k) && ((MK_MASK >> (k)) & 1))
; #define REPS(k) for (int rep_ = 0; rep_ < (((MK_REP_MASK) >> (k)) & 1) + 1; ++rep_)
; __global__ void __launch_bounds__(NWAVES * 64, 2) mk_fwd(Params P) {
;     ...
;     if (PH(2)) REPS(2) {
;         for (int p = vcu; p < 1024; p += G) {
;             const int pp = p & 511, bh = pp >> 3, s = pp & 7, b = bh >> 3, hm = bh & 7;
;     ...
;             if (rep_ == 1 && !((MK_REP_ATT) & (p < 512 ? 1 : 2))) continue;
;     ...
;             for (int hh = 0; hh < 2; ++hh) {
;                 const int qb = hh ? s : 15 - s;
;                 if (p < 512) { if (!(MK_ATT_MASK & 1)) continue;
.LBB0_900:
	s_cmp_lt_i32 s74, 5
	s_cselect_b64 s[2:3], -1, 0
	s_and_b64 s[0:1], s[2:3], s[0:1]
	s_andn2_b64 vcc, exec, s[0:1]
	s_cbranch_vccnz .LBB0_939
	v_and_b32_e32 v248, 15, v212
	v_lshrrev_b32_e32 v249, 2, v212
	v_sub_u32_e32 v249, v249, v248
	v_lshrrev_b32_e32 v248, 4, v212
	v_and_b32_e32 v253, 3, v212
	v_sub_u32_e32 v248, v253, v248
	v_lshlrev_b32_e32 v248, 4, v248
	v_mul_i32_i24_e32 v250, 0x800, v249
	v_add_u32_e32 v250, v250, v248
	v_ashrrev_i32_e32 v251, 31, v250
	v_lshlrev_b32_e32 v253, 4, v253
	v_lshrrev_b32_e32 v248, 2, v212
	v_add_u32_e32 v253, v253, v248
	v_lshlrev_b32_e32 v253, 2, v253
	s_and_b32 s2, s93, 0xffffffc0
	v_mov_b32_e32 v8, v212
	s_cmpk_lt_i32 s88, 0x200
	s_cselect_b64 s[4:5], -1, 0
	v_add_u32_e32 v0, s2, v8
	s_cmpk_gt_i32 s88, 0x1ff
	v_readfirstlane_b32 s6, v0
	s_cbranch_scc1 .LBB0_903
	s_ashr_i32 s2, s88, 31
	s_lshr_b32 s2, s2, 29
	s_add_i32 s2, s88, s2
	s_and_b32 s3, s2, -8
	s_sub_i32 s3, s88, s3
	s_lshl_b32 s8, s3, 6
	s_ashr_i32 s2, s2, 3
	s_mul_i32 s7, s3, 0x41
	s_cmp_lt_i32 s3, 0
	s_cselect_b32 s3, s7, s8
	s_add_i32 s2, s3, s2
	s_ashr_i32 s3, s2, 31
	s_lshr_b32 s3, s3, 27
	s_add_i32 s3, s2, s3
	s_ashr_i32 s7, s3, 5
	s_andn2_b32 s3, s3, 31
	s_sub_i32 s2, s2, s3
	s_bfe_i32 s3, s2, 0x80000
	s_bfe_u32 s3, s3, 0x3000c
	s_add_i32 s3, s2, s3
	s_bfe_i32 s8, s3, 0x80000
	s_and_b32 s3, s3, 0xf8
	s_sub_i32 s2, s2, s3
	s_lshl_b32 s7, s7, 3
	s_sext_i32_i16 s8, s8
	s_sext_i32_i8 s2, s2
	s_add_i32 s30, s7, s2
	s_ashr_i32 s8, s8, 3

; __device__ __forceinline__ unsigned cvt_pk_bf16(float lo, float hi) { unsigned r; asm volatile("v_cvt_pk_bf16_f32 %0, %1, %2" : "=v"(r) : "v"(lo), "v"(hi)); return r; }
;     __device__ __forceinline__ void operator()(const f32x4 (&acc)[2][2][4][2], const Unit& u, int wr, int wc, int fr, int fq) const {
;     ...
;                 for (int bj = 0; bj < 2; ++bj) { const size_t off = (size_t)(row0 + ai * HALF + m * 16) * 1024 + col0 + bj * HALF;
;                     if (BASE_BF16) bw[m][bj] = *(const u32x4*)((const bf16_t*)base + off);
;                     else { bf[m][bj][0] = *(const f32x4*)((const float*)base + off); bf[m][bj][1] = *(const f32x4*)((const float*)base + off + 4); } }
; #pragma unroll
;             for (int m = 0; m < 4; ++m) {
;                 const int row = row0 + ai * HALF + m * 16; const size_t off = (size_t)row * 1024 + col0;
;                 float ss = 0.f;
; #pragma unroll
;                 for (int bj = 0; bj < 2; ++bj) {
;                     f32x4 b0, b1;
;                     if (BASE_BF16) { const u32x4 w = bw[m][bj];
;                         b0 = (f32x4){__builtin_bit_cast(float, w.x << 16), __builtin_bit_cast(float, w.x & 0xffff0000u), __builtin_bit_cast(float, w.y << 16), __builtin_bit_cast(float, w.y & 0xffff0000u)};
;                         b1 = (f32x4){__builtin_bit_cast(float, w.z << 16), __builtin_bit_cast(float, w.z & 0xffff0000u), __builtin_bit_cast(float, w.w << 16), __builtin_bit_cast(float, w.w & 0xffff0000u)}; }
;                     else { b0 = bf[m][bj][0]; b1 = bf[m][bj][1]; }
;                     const f32x4 v0 = acc[ai][bj][m][0] + b0, v1 = acc[ai][bj][m][1] + b1;
;                     ss += (v0[0] * v0[0] + v0[1] * v0[1]) + (v0[2] * v0[2] + v0[3] * v0[3]) + (v1[0] * v1[0] + v1[1] * v1[1]) + (v1[2] * v1[2] + v1[3] * v1[3]);
;                     if (OUT_BF16) { u32x4 w; w.x = cvt_pk_bf16(v0[0], v0[1]); w.y = cvt_pk_bf16(v0[2], v0[3]); w.z = cvt_pk_bf16(v1[0], v1[1]); w.w = cvt_pk_bf16(v1[2], v1[3]);
;                         *(u32x4*)((bf16_t*)out + off + bj * HALF) = w; }
;                     else { *(f32x4*)((float*)out + off + bj * HALF) = v0; *(f32x4*)((float*)out + off + bj * HALF + 4) = v1; }
;                 }
;                 ss += __shfl_xor(ss, 16); ss += __shfl_xor(ss, 32);
;                 if (fq == 0) sspart[(size_t)row * 16 + u.pn * 4 + wc] = ss;
.LBB0_919:
	v_lshl_or_b32 v168, s8, 8, v190
	v_lshl_add_u32 v172, s30, 8, v188
	v_ashrrev_i32_e32 v169, 31, v168
	v_lshlrev_b64 v[202:203], 1, v[168:169]
	v_ashrrev_i32_e32 v173, 31, v172
	v_lshl_add_u64 v[170:171], s[12:13], 0, v[202:203]
	v_lshlrev_b64 v[204:205], 11, v[172:173]
	v_lshl_add_u64 v[128:129], v[170:171], 0, v[204:205]
	global_load_dwordx4 v[194:197], v[128:129], off
	global_load_dwordx4 v[198:201], v[128:129], off offset:256
	v_or_b32_e32 v182, 16, v172
	v_or_b32_e32 v178, 32, v172
	v_or_b32_e32 v174, 48, v172
	v_ashrrev_i32_e32 v183, 31, v182
	v_ashrrev_i32_e32 v179, 31, v178
	v_ashrrev_i32_e32 v175, 31, v174
	v_lshlrev_b64 v[184:185], 11, v[182:183]
	v_lshlrev_b64 v[180:181], 11, v[178:179]
	v_lshlrev_b64 v[176:177], 11, v[174:175]
	v_lshl_add_u64 v[128:129], v[170:171], 0, v[184:185]
	v_lshl_add_u64 v[130:131], v[170:171], 0, v[180:181]
	v_lshl_add_u64 v[206:207], v[170:171], 0, v[176:177]
	global_load_dwordx4 v[148:151], v[128:129], off
	global_load_dwordx4 v[144:147], v[128:129], off offset:256
	global_load_dwordx4 v[140:143], v[130:131], off
	global_load_dwordx4 v[136:139], v[130:131], off offset:256
	global_load_dwordx4 v[132:135], v[206:207], off
	s_nop 0
	global_load_dwordx4 v[128:131], v[206:207], off offset:256
	s_lshl_b32 s30, s8, 2
	s_ashr_i32 s31, s30, 31
	s_waitcnt vmcnt(0)
	v_lshlrev_b32_e32 v206, 16, v194
	v_and_b32_e32 v207, 0xffff0000, v194
	v_lshlrev_b32_e32 v194, 16, v195
	v_and_b32_e32 v195, 0xffff0000, v195
	v_lshlrev_b32_e32 v208, 16, v196
	v_and_b32_e32 v209, 0xffff0000, v196
	v_lshlrev_b32_e32 v196, 16, v197
	v_and_b32_e32 v197, 0xffff0000, v197
	v_lshlrev_b32_e32 v210, 16, v198
	v_and_b32_e32 v211, 0xffff0000, v198
	v_lshlrev_b32_e32 v198, 16, v199
	v_and_b32_e32 v199, 0xffff0000, v199
	v_lshlrev_b32_e32 v214, 16, v200
	v_and_b32_e32 v215, 0xffff0000, v200
	v_lshlrev_b32_e32 v200, 16, v201
	v_and_b32_e32 v201, 0xffff0000, v201
	v_pk_add_f32 v[126:127], v[126:127], v[194:195]
	v_pk_add_f32 v[124:125], v[124:125], v[206:207]
	v_pk_add_f32 v[122:123], v[122:123], v[196:197]
	v_pk_add_f32 v[120:121], v[120:121], v[208:209]
	v_pk_add_f32 v[118:119], v[118:119], v[198:199]
	v_pk_add_f32 v[116:117], v[116:117], v[210:211]
	v_pk_add_f32 v[194:195], v[114:115], v[200:201]
	v_pk_add_f32 v[196:197], v[112:113], v[214:215]
	v_mul_f32_e32 v198, v125, v125
	v_mul_f32_e32 v199, v127, v127
	v_mul_f32_e32 v200, v121, v121
	v_mul_f32_e32 v201, v123, v123
	v_cvt_pk_bf16_f32 v112, v124, v125
	v_cvt_pk_bf16_f32 v113, v126, v127
	v_cvt_pk_bf16_f32 v114, v120, v121
	v_cvt_pk_bf16_f32 v115, v122, v123
	v_mul_f32_e32 v121, v117, v117
	v_mul_f32_e32 v123, v119, v119
	v_mul_f32_e32 v125, v197, v197
	v_fmac_f32_e32 v198, v124, v124
	v_fmac_f32_e32 v199, v126, v126
	v_fmac_f32_e32 v121, v116, v116
	v_fmac_f32_e32 v123, v118, v118
	v_mul_f32_e32 v127, v195, v195
	v_fmac_f32_e32 v200, v120, v120
	v_fmac_f32_e32 v125, v196, v196
	v_add_f32_e32 v120, v198, v199
	v_add_f32_e32 v121, v121, v123
	v_fmac_f32_e32 v201, v122, v122
	v_fmac_f32_e32 v127, v194, v194
	v_add_f32_e32 v120, v200, v120
	v_add_f32_e32 v121, v125, v121
	v_add_f32_e32 v120, v201, v120
	v_add_f32_e32 v121, v127, v121
	v_add_f32_e32 v122, v120, v121
	ds_bpermute_b32 v123, v186, v122
	v_lshl_add_u64 v[120:121], s[12:13], 0, v[204:205]
	v_lshl_add_u64 v[120:121], v[120:121], 0, v[202:203]
	ds_bpermute_b32 v240, v253, v112
	ds_bpermute_b32 v241, v253, v113
	ds_bpermute_b32 v242, v253, v114
	ds_bpermute_b32 v243, v253, v115
	v_lshl_add_u64 v[236:237], v[120:121], 0, v[250:251]
	s_waitcnt lgkmcnt(0)
	s_nop 0
	v_add_f32_e32 v112, v122, v123
	ds_bpermute_b32 v113, v187, v112
	v_cvt_pk_bf16_f32 v114, v116, v117
	v_cvt_pk_bf16_f32 v115, v118, v119
	v_cvt_pk_bf16_f32 v116, v196, v197
	v_cvt_pk_bf16_f32 v117, v194, v195
	ds_bpermute_b32 v244, v253, v114
	ds_bpermute_b32 v245, v253, v115
	ds_bpermute_b32 v246, v253, v116
	ds_bpermute_b32 v247, v253, v117
	v_lshl_add_u64 v[238:239], v[120:121], 0, v[250:251]
	s_waitcnt lgkmcnt(4)
	global_store_dwordx4 v[236:237], v[240:243], off
	s_and_saveexec_b64 s[34:35], s[4:5]
	s_cbranch_execz .LBB0_921
	v_lshlrev_b64 v[114:115], 6, v[172:173]
	v_lshl_add_u64 v[114:115], s[14:15], 0, v[114:115]
	v_lshl_add_u64 v[114:115], s[30:31], 2, v[114:115]
	s_lshl_b32 s8, s46, 2
	v_lshl_add_u64 v[114:115], v[114:115], 0, s[8:9]
	s_waitcnt lgkmcnt(0)
	v_add_f32_e32 v112, v112, v113
	global_store_dword v[114:115], v112, off
; __device__ __forceinline__ unsigned cvt_pk_bf16(float lo, float hi) { unsigned r; asm volatile("v_cvt_pk_bf16_f32 %0, %1, %2" : "=v"(r) : "v"(lo), "v"(hi)); return r; }
;     __device__ __forceinline__ void operator()(const f32x4 (&acc)[2][2][4][2], const Unit& u, int wr, int wc, int fr, int fq) const {
;     ...
;             for (int m = 0; m < 4; ++m) {
;                 const int row = row0 + ai * HALF + m * 16; const size_t off = (size_t)row * 1024 + col0;
;                 float ss = 0.f;
; #pragma unroll
;                 for (int bj = 0; bj < 2; ++bj) {
;                     f32x4 b0, b1;
;                     if (BASE_BF16) { const u32x4 w = bw[m][bj];
;                         b0 = (f32x4){__builtin_bit_cast(float, w.x << 16), __builtin_bit_cast(float, w.x & 0xffff0000u), __builtin_bit_cast(float, w.y << 16), __builtin_bit_cast(float, w.y & 0xffff0000u)};
;                         b1 = (f32x4){__builtin_bit_cast(float, w.z << 16), __builtin_bit_cast(float, w.z & 0xffff0000u), __builtin_bit_cast(float, w.w << 16), __builtin_bit_cast(float, w.w & 0xffff0000u)}; }
;                     else { b0 = bf[m][bj][0]; b1 = bf[m][bj][1]; }
;                     const f32x4 v0 = acc[ai][bj][m][0] + b0, v1 = acc[ai][bj][m][1] + b1;
;                     ss += (v0[0] * v0[0] + v0[1] * v0[1]) + (v0[2] * v0[2] + v0[3] * v0[3]) + (v1[0] * v1[0] + v1[1] * v1[1]) + (v1[2] * v1[2] + v1[3] * v1[3]);
;                     if (OUT_BF16) { u32x4 w; w.x = cvt_pk_bf16(v0[0], v0[1]); w.y = cvt_pk_bf16(v0[2], v0[3]); w.z = cvt_pk_bf16(v1[0], v1[1]); w.w = cvt_pk_bf16(v1[2], v1[3]);
;                         *(u32x4*)((bf16_t*)out + off + bj * HALF) = w; }
;                     else { *(f32x4*)((float*)out + off + bj * HALF) = v0; *(f32x4*)((float*)out + off + bj * HALF + 4) = v1; }
;                 }
;                 ss += __shfl_xor(ss, 16); ss += __shfl_xor(ss, 32);
;                 if (fq == 0) sspart[(size_t)row * 16 + u.pn * 4 + wc] = ss;
.LBB0_921:
	s_or_b64 exec, exec, s[34:35]
	v_lshlrev_b32_e32 v112, 16, v148
	s_waitcnt lgkmcnt(0)
	v_and_b32_e32 v113, 0xffff0000, v148
	v_lshlrev_b32_e32 v114, 16, v149
	v_and_b32_e32 v115, 0xffff0000, v149
	v_lshlrev_b32_e32 v116, 16, v150
	v_and_b32_e32 v117, 0xffff0000, v150
	v_lshlrev_b32_e32 v118, 16, v151
	v_and_b32_e32 v119, 0xffff0000, v151
	v_pk_add_f32 v[110:111], v[110:111], v[114:115]
	v_pk_add_f32 v[108:109], v[108:109], v[112:113]
	v_pk_add_f32 v[112:113], v[106:107], v[118:119]
	v_pk_add_f32 v[106:107], v[104:105], v[116:117]
	v_mul_f32_e32 v104, v109, v109
	v_mul_f32_e32 v105, v111, v111
	v_fmac_f32_e32 v104, v108, v108
	v_fmac_f32_e32 v105, v110, v110
	v_add_f32_e32 v104, v104, v105
	v_mul_f32_e32 v105, v107, v107
	v_fmac_f32_e32 v105, v106, v106
	v_add_f32_e32 v104, v105, v104
	v_mul_f32_e32 v105, v113, v113
	v_fmac_f32_e32 v105, v112, v112
	v_add_f32_e32 v116, v105, v104
	v_cvt_pk_bf16_f32 v104, v108, v109
	v_cvt_pk_bf16_f32 v105, v110, v111
	v_lshlrev_b32_e32 v108, 16, v144
	v_and_b32_e32 v109, 0xffff0000, v144
	v_lshlrev_b32_e32 v110, 16, v145
	v_and_b32_e32 v111, 0xffff0000, v145
	v_cvt_pk_bf16_f32 v106, v106, v107
	v_cvt_pk_bf16_f32 v107, v112, v113
	v_lshlrev_b32_e32 v112, 16, v146
	v_and_b32_e32 v113, 0xffff0000, v146
	v_pk_add_f32 v[102:103], v[102:103], v[110:111]
	v_pk_add_f32 v[100:101], v[100:101], v[108:109]
	v_pk_add_f32 v[110:111], v[96:97], v[112:113]
	v_mul_f32_e32 v96, v101, v101
	v_mul_f32_e32 v97, v103, v103
	v_fmac_f32_e32 v96, v100, v100
	v_fmac_f32_e32 v97, v102, v102
	v_lshlrev_b32_e32 v114, 16, v147
	v_and_b32_e32 v115, 0xffff0000, v147
	v_add_f32_e32 v96, v96, v97
	v_mul_f32_e32 v97, v111, v111
	v_pk_add_f32 v[108:109], v[98:99], v[114:115]
	v_fmac_f32_e32 v97, v110, v110
	v_add_f32_e32 v96, v97, v96
	v_mul_f32_e32 v97, v109, v109
	v_fmac_f32_e32 v97, v108, v108
	v_add_f32_e32 v96, v97, v96
	v_add_f32_e32 v99, v116, v96
	ds_bpermute_b32 v114, v186, v99
	v_lshl_add_u64 v[96:97], s[12:13], 0, v[184:185]
	v_lshl_add_u64 v[112:113], v[168:169], 1, v[96:97]
	ds_bpermute_b32 v240, v253, v104
	ds_bpermute_b32 v241, v253, v105
	ds_bpermute_b32 v242, v253, v106
	ds_bpermute_b32 v243, v253, v107
	v_lshl_add_u64 v[236:237], v[112:113], 0, v[250:251]
	s_waitcnt lgkmcnt(4)
	global_store_dwordx4 v[238:239], v[244:247], off offset:256
	v_cvt_pk_bf16_f32 v98, v100, v101
	s_waitcnt lgkmcnt(0)
	v_add_f32_e32 v96, v99, v114
	ds_bpermute_b32 v97, v187, v96
	v_cvt_pk_bf16_f32 v99, v102, v103
	v_cvt_pk_bf16_f32 v100, v110, v111
	v_cvt_pk_bf16_f32 v101, v108, v109
	ds_bpermute_b32 v244, v253, v98
	ds_bpermute_b32 v245, v253, v99
	ds_bpermute_b32 v246, v253, v100
	ds_bpermute_b32 v247, v253, v101
	v_lshl_add_u64 v[238:239], v[112:113], 0, v[250:251]
	s_waitcnt lgkmcnt(4)
	global_store_dwordx4 v[236:237], v[240:243], off
	s_and_saveexec_b64 s[34:35], s[4:5]
	s_cbranch_execz .LBB0_923
	v_lshlrev_b64 v[98:99], 6, v[182:183]
	v_lshl_add_u64 v[98:99], s[14:15], 0, v[98:99]
	v_lshl_add_u64 v[98:99], s[30:31], 2, v[98:99]
	s_lshl_b32 s8, s46, 2
	v_lshl_add_u64 v[98:99], v[98:99], 0, s[8:9]
	s_waitcnt lgkmcnt(0)
	v_add_f32_e32 v96, v96, v97
	global_store_dword v[98:99], v96, off
.LBB0_923:
	s_or_b64 exec, exec, s[34:35]
	v_lshlrev_b32_e32 v96, 16, v140
	s_waitcnt lgkmcnt(0)
	v_and_b32_e32 v97, 0xffff0000, v140
	v_lshlrev_b32_e32 v98, 16, v141
	v_and_b32_e32 v99, 0xffff0000, v141
	v_lshlrev_b32_e32 v100, 16, v142
	v_and_b32_e32 v101, 0xffff0000, v142
	v_lshlrev_b32_e32 v102, 16, v143
	v_and_b32_e32 v103, 0xffff0000, v143
	v_pk_add_f32 v[94:95], v[94:95], v[98:99]
	v_pk_add_f32 v[92:93], v[92:93], v[96:97]
	v_pk_add_f32 v[96:97], v[90:91], v[102:103]
	v_pk_add_f32 v[90:91], v[88:89], v[100:101]
	v_mul_f32_e32 v88, v93, v93
	v_mul_f32_e32 v89, v95, v95
	v_fmac_f32_e32 v88, v92, v92
	v_fmac_f32_e32 v89, v94, v94
	v_add_f32_e32 v88, v88, v89
	v_mul_f32_e32 v89, v91, v91
	v_fmac_f32_e32 v89, v90, v90
	v_add_f32_e32 v88, v89, v88
	v_mul_f32_e32 v89, v97, v97
	v_fmac_f32_e32 v89, v96, v96
	v_add_f32_e32 v100, v89, v88
	v_cvt_pk_bf16_f32 v88, v92, v93
	v_cvt_pk_bf16_f32 v89, v94, v95
	v_lshlrev_b32_e32 v92, 16, v136
	v_and_b32_e32 v93, 0xffff0000, v136
	v_lshlrev_b32_e32 v94, 16, v137
	v_and_b32_e32 v95, 0xffff0000, v137
	v_cvt_pk_bf16_f32 v90, v90, v91
	v_cvt_pk_bf16_f32 v91, v96, v97
	v_lshlrev_b32_e32 v96, 16, v138
	v_and_b32_e32 v97, 0xffff0000, v138
	v_pk_add_f32 v[86:87], v[86:87], v[94:95]
	v_pk_add_f32 v[84:85], v[84:85], v[92:93]
	v_pk_add_f32 v[94:95], v[80:81], v[96:97]
	v_mul_f32_e32 v80, v85, v85
	v_mul_f32_e32 v81, v87, v87
	v_fmac_f32_e32 v80, v84, v84
	v_fmac_f32_e32 v81, v86, v86
	v_lshlrev_b32_e32 v98, 16, v139
	v_and_b32_e32 v99, 0xffff0000, v139
	v_add_f32_e32 v80, v80, v81
	v_mul_f32_e32 v81, v95, v95
	v_pk_add_f32 v[92:93], v[82:83], v[98:99]
	v_fmac_f32_e32 v81, v94, v94
	v_add_f32_e32 v80, v81, v80
	v_mul_f32_e32 v81, v93, v93
	v_fmac_f32_e32 v81, v92, v92
	v_add_f32_e32 v80, v81, v80
	v_add_f32_e32 v83, v100, v80
	ds_bpermute_b32 v98, v186, v83
	v_lshl_add_u64 v[80:81], s[12:13], 0, v[180:181]
	v_lshl_add_u64 v[96:97], v[168:169], 1, v[80:81]
	ds_bpermute_b32 v240, v253, v88
	ds_bpermute_b32 v241, v253, v89
	ds_bpermute_b32 v242, v253, v90
	ds_bpermute_b32 v243, v253, v91
	v_lshl_add_u64 v[236:237], v[96:97], 0, v[250:251]
	s_waitcnt lgkmcnt(4)
	global_store_dwordx4 v[238:239], v[244:247], off offset:256
	v_cvt_pk_bf16_f32 v82, v84, v85
	s_waitcnt lgkmcnt(0)
	v_add_f32_e32 v80, v83, v98
	ds_bpermute_b32 v81, v187, v80
	v_cvt_pk_bf16_f32 v83, v86, v87
	v_cvt_pk_bf16_f32 v84, v94, v95
	v_cvt_pk_bf16_f32 v85, v92, v93
	ds_bpermute_b32 v244, v253, v82
	ds_bpermute_b32 v245, v253, v83
	ds_bpermute_b32 v246, v253, v84
	ds_bpermute_b32 v247, v253, v85
	v_lshl_add_u64 v[238:239], v[96:97], 0, v[250:251]
	s_waitcnt lgkmcnt(4)
	global_store_dwordx4 v[236:237], v[240:243], off
	s_and_saveexec_b64 s[34:35], s[4:5]
	s_cbranch_execz .LBB0_925
	v_lshlrev_b64 v[82:83], 6, v[178:179]
	v_lshl_add_u64 v[82:83], s[14:15], 0, v[82:83]
	v_lshl_add_u64 v[82:83], s[30:31], 2, v[82:83]
	s_lshl_b32 s8, s46, 2
	v_lshl_add_u64 v[82:83], v[82:83], 0, s[8:9]
	s_waitcnt lgkmcnt(0)
	v_add_f32_e32 v80, v80, v81
	global_store_dword v[82:83], v80, off
; __device__ __forceinline__ unsigned cvt_pk_bf16(float lo, float hi) { unsigned r; asm volatile("v_cvt_pk_bf16_f32 %0, %1, %2" : "=v"(r) : "v"(lo), "v"(hi)); return r; }
;     __device__ __forceinline__ void operator()(const f32x4 (&acc)[2][2][4][2], const Unit& u, int wr, int wc, int fr, int fq) const {
;     ...
;                 for (int bj = 0; bj < 2; ++bj) { const size_t off = (size_t)(row0 + ai * HALF + m * 16) * 1024 + col0 + bj * HALF;
;                     if (BASE_BF16) bw[m][bj] = *(const u32x4*)((const bf16_t*)base + off);
;                     else { bf[m][bj][0] = *(const f32x4*)((const float*)base + off); bf[m][bj][1] = *(const f32x4*)((const float*)base + off + 4); } }
; #pragma unroll
;             for (int m = 0; m < 4; ++m) {
;                 const int row = row0 + ai * HALF + m * 16; const size_t off = (size_t)row * 1024 + col0;
;                 float ss = 0.f;
; #pragma unroll
;                 for (int bj = 0; bj < 2; ++bj) {
;                     f32x4 b0, b1;
;                     if (BASE_BF16) { const u32x4 w = bw[m][bj];
;                         b0 = (f32x4){__builtin_bit_cast(float, w.x << 16), __builtin_bit_cast(float, w.x & 0xffff0000u), __builtin_bit_cast(float, w.y << 16), __builtin_bit_cast(float, w.y & 0xffff0000u)};
;                         b1 = (f32x4){__builtin_bit_cast(float, w.z << 16), __builtin_bit_cast(float, w.z & 0xffff0000u), __builtin_bit_cast(float, w.w << 16), __builtin_bit_cast(float, w.w & 0xffff0000u)}; }
;                     else { b0 = bf[m][bj][0]; b1 = bf[m][bj][1]; }
;                     const f32x4 v0 = acc[ai][bj][m][0] + b0, v1 = acc[ai][bj][m][1] + b1;
;                     ss += (v0[0] * v0[0] + v0[1] * v0[1]) + (v0[2] * v0[2] + v0[3] * v0[3]) + (v1[0] * v1[0] + v1[1] * v1[1]) + (v1[2] * v1[2] + v1[3] * v1[3]);
;                     if (OUT_BF16) { u32x4 w; w.x = cvt_pk_bf16(v0[0], v0[1]); w.y = cvt_pk_bf16(v0[2], v0[3]); w.z = cvt_pk_bf16(v1[0], v1[1]); w.w = cvt_pk_bf16(v1[2], v1[3]);
;                         *(u32x4*)((bf16_t*)out + off + bj * HALF) = w; }
;                     else { *(f32x4*)((float*)out + off + bj * HALF) = v0; *(f32x4*)((float*)out + off + bj * HALF + 4) = v1; }
;                 }
;                 ss += __shfl_xor(ss, 16); ss += __shfl_xor(ss, 32);
;                 if (fq == 0) sspart[(size_t)row * 16 + u.pn * 4 + wc] = ss;
.LBB0_925:
	s_or_b64 exec, exec, s[34:35]
	v_lshlrev_b32_e32 v80, 16, v132
	s_waitcnt lgkmcnt(0)
	v_and_b32_e32 v81, 0xffff0000, v132
	v_lshlrev_b32_e32 v82, 16, v133
	v_and_b32_e32 v83, 0xffff0000, v133
	v_lshlrev_b32_e32 v84, 16, v134
	v_and_b32_e32 v85, 0xffff0000, v134
	v_lshlrev_b32_e32 v86, 16, v135
	v_and_b32_e32 v87, 0xffff0000, v135
	v_pk_add_f32 v[78:79], v[78:79], v[82:83]
	v_pk_add_f32 v[76:77], v[76:77], v[80:81]
	v_pk_add_f32 v[80:81], v[74:75], v[86:87]
	v_pk_add_f32 v[74:75], v[72:73], v[84:85]
	v_mul_f32_e32 v72, v77, v77
	v_mul_f32_e32 v73, v79, v79
	v_fmac_f32_e32 v72, v76, v76
	v_fmac_f32_e32 v73, v78, v78
	v_add_f32_e32 v72, v72, v73
	v_mul_f32_e32 v73, v75, v75
	v_fmac_f32_e32 v73, v74, v74
	v_add_f32_e32 v72, v73, v72
	v_mul_f32_e32 v73, v81, v81
	v_fmac_f32_e32 v73, v80, v80
	v_add_f32_e32 v84, v73, v72
	v_cvt_pk_bf16_f32 v72, v76, v77
	v_cvt_pk_bf16_f32 v73, v78, v79
	v_lshlrev_b32_e32 v76, 16, v128
	v_and_b32_e32 v77, 0xffff0000, v128
	v_lshlrev_b32_e32 v78, 16, v129
	v_and_b32_e32 v79, 0xffff0000, v129
	v_cvt_pk_bf16_f32 v74, v74, v75
	v_cvt_pk_bf16_f32 v75, v80, v81
	v_lshlrev_b32_e32 v80, 16, v130
	v_and_b32_e32 v81, 0xffff0000, v130
	v_pk_add_f32 v[70:71], v[70:71], v[78:79]
	v_pk_add_f32 v[68:69], v[68:69], v[76:77]
	v_pk_add_f32 v[78:79], v[64:65], v[80:81]
	v_mul_f32_e32 v64, v69, v69
	v_mul_f32_e32 v65, v71, v71
	v_fmac_f32_e32 v64, v68, v68
	v_fmac_f32_e32 v65, v70, v70
	v_lshlrev_b32_e32 v82, 16, v131
	v_and_b32_e32 v83, 0xffff0000, v131
	v_add_f32_e32 v64, v64, v65
	v_mul_f32_e32 v65, v79, v79
	v_pk_add_f32 v[76:77], v[66:67], v[82:83]
	v_fmac_f32_e32 v65, v78, v78
	v_add_f32_e32 v64, v65, v64
	v_mul_f32_e32 v65, v77, v77
	v_fmac_f32_e32 v65, v76, v76
	v_add_f32_e32 v64, v65, v64
	v_add_f32_e32 v67, v84, v64
	ds_bpermute_b32 v82, v186, v67
	v_lshl_add_u64 v[64:65], s[12:13], 0, v[176:177]
	v_lshl_add_u64 v[80:81], v[168:169], 1, v[64:65]
	ds_bpermute_b32 v240, v253, v72
	ds_bpermute_b32 v241, v253, v73
	ds_bpermute_b32 v242, v253, v74
	ds_bpermute_b32 v243, v253, v75
	v_lshl_add_u64 v[236:237], v[80:81], 0, v[250:251]
	s_waitcnt lgkmcnt(4)
	global_store_dwordx4 v[238:239], v[244:247], off offset:256
	v_cvt_pk_bf16_f32 v66, v68, v69
	s_waitcnt lgkmcnt(0)
	v_add_f32_e32 v64, v67, v82
	ds_bpermute_b32 v65, v187, v64
	v_cvt_pk_bf16_f32 v67, v70, v71
	v_cvt_pk_bf16_f32 v68, v78, v79
	v_cvt_pk_bf16_f32 v69, v76, v77
	ds_bpermute_b32 v244, v253, v66
	ds_bpermute_b32 v245, v253, v67
	ds_bpermute_b32 v246, v253, v68
	ds_bpermute_b32 v247, v253, v69
	v_lshl_add_u64 v[238:239], v[80:81], 0, v[250:251]
	s_waitcnt lgkmcnt(4)
	global_store_dwordx4 v[236:237], v[240:243], off
	s_and_saveexec_b64 s[34:35], s[4:5]
	s_cbranch_execz .LBB0_927
	v_lshlrev_b64 v[66:67], 6, v[174:175]
	v_lshl_add_u64 v[66:67], s[14:15], 0, v[66:67]
	v_lshl_add_u64 v[66:67], s[30:31], 2, v[66:67]
	s_lshl_b32 s8, s46, 2
	v_lshl_add_u64 v[66:67], v[66:67], 0, s[8:9]
	s_waitcnt lgkmcnt(0)
	v_add_f32_e32 v64, v64, v65
	global_store_dword v[66:67], v64, off
.LBB0_927:
	s_or_b64 exec, exec, s[34:35]
	v_add_u32_e32 v100, 0x80, v172
	v_ashrrev_i32_e32 v101, 31, v100
	v_lshlrev_b64 v[110:111], 11, v[100:101]
	s_waitcnt lgkmcnt(0)
	v_lshl_add_u64 v[64:65], v[170:171], 0, v[110:111]
	global_load_dwordx4 v[102:105], v[64:65], off
	global_load_dwordx4 v[106:109], v[64:65], off offset:256
	v_add_u32_e32 v96, 0x90, v172
	v_add_u32_e32 v92, 0xa0, v172
	v_add_u32_e32 v88, 0xb0, v172
	v_ashrrev_i32_e32 v97, 31, v96
	v_ashrrev_i32_e32 v93, 31, v92
	v_ashrrev_i32_e32 v89, 31, v88
	v_lshlrev_b64 v[98:99], 11, v[96:97]
	v_lshlrev_b64 v[94:95], 11, v[92:93]
	v_lshlrev_b64 v[90:91], 11, v[88:89]
	v_lshl_add_u64 v[64:65], v[170:171], 0, v[98:99]
	v_lshl_add_u64 v[66:67], v[170:171], 0, v[94:95]
	v_lshl_add_u64 v[112:113], v[170:171], 0, v[90:91]
	global_load_dwordx4 v[84:87], v[64:65], off
	global_load_dwordx4 v[80:83], v[64:65], off offset:256
	global_load_dwordx4 v[76:79], v[66:67], off
	global_load_dwordx4 v[72:75], v[66:67], off offset:256
	global_load_dwordx4 v[68:71], v[112:113], off
	s_nop 0
	global_load_dwordx4 v[64:67], v[112:113], off offset:256
	s_waitcnt vmcnt(7)
	v_lshlrev_b32_e32 v112, 16, v102
	v_and_b32_e32 v113, 0xffff0000, v102
	v_lshlrev_b32_e32 v102, 16, v103
	v_and_b32_e32 v103, 0xffff0000, v103
	v_lshlrev_b32_e32 v114, 16, v104
	v_and_b32_e32 v115, 0xffff0000, v104
	v_lshlrev_b32_e32 v104, 16, v105
	v_and_b32_e32 v105, 0xffff0000, v105
	s_waitcnt vmcnt(6)
	v_lshlrev_b32_e32 v116, 16, v106
	v_and_b32_e32 v117, 0xffff0000, v106
	v_lshlrev_b32_e32 v106, 16, v107
	v_and_b32_e32 v107, 0xffff0000, v107
	v_lshlrev_b32_e32 v118, 16, v108
	v_and_b32_e32 v119, 0xffff0000, v108
	v_lshlrev_b32_e32 v108, 16, v109
	v_and_b32_e32 v109, 0xffff0000, v109
	v_pk_add_f32 v[62:63], v[62:63], v[102:103]
	v_pk_add_f32 v[60:61], v[60:61], v[112:113]
	v_pk_add_f32 v[58:59], v[58:59], v[104:105]
	v_pk_add_f32 v[56:57], v[56:57], v[114:115]
	v_pk_add_f32 v[54:55], v[54:55], v[106:107]
	v_pk_add_f32 v[52:53], v[52:53], v[116:117]
	v_pk_add_f32 v[102:103], v[50:51], v[108:109]
	v_pk_add_f32 v[104:105], v[48:49], v[118:119]
	v_mul_f32_e32 v106, v61, v61
	v_mul_f32_e32 v107, v63, v63
	v_mul_f32_e32 v108, v57, v57
	v_mul_f32_e32 v109, v59, v59
	v_cvt_pk_bf16_f32 v48, v60, v61
	v_cvt_pk_bf16_f32 v49, v62, v63
	v_cvt_pk_bf16_f32 v50, v56, v57
	v_cvt_pk_bf16_f32 v51, v58, v59
	v_mul_f32_e32 v57, v53, v53
	v_mul_f32_e32 v59, v55, v55
	v_mul_f32_e32 v61, v105, v105
	v_fmac_f32_e32 v106, v60, v60
	v_fmac_f32_e32 v107, v62, v62
	v_fmac_f32_e32 v57, v52, v52
	v_fmac_f32_e32 v59, v54, v54
	v_mul_f32_e32 v63, v103, v103
	v_fmac_f32_e32 v108, v56, v56
	v_fmac_f32_e32 v61, v104, v104
	v_add_f32_e32 v56, v106, v107
	v_add_f32_e32 v57, v57, v59
	v_fmac_f32_e32 v109, v58, v58
	v_fmac_f32_e32 v63, v102, v102
	v_add_f32_e32 v56, v108, v56
	v_add_f32_e32 v57, v61, v57
	v_add_f32_e32 v56, v109, v56
	v_add_f32_e32 v57, v63, v57
	v_add_f32_e32 v58, v56, v57
	ds_bpermute_b32 v59, v186, v58
	v_lshl_add_u64 v[56:57], s[12:13], 0, v[110:111]
	v_lshl_add_u64 v[56:57], v[168:169], 1, v[56:57]
	ds_bpermute_b32 v240, v253, v48
	ds_bpermute_b32 v241, v253, v49
	ds_bpermute_b32 v242, v253, v50
	ds_bpermute_b32 v243, v253, v51
	v_lshl_add_u64 v[236:237], v[56:57], 0, v[250:251]
	s_waitcnt lgkmcnt(4)
	global_store_dwordx4 v[238:239], v[244:247], off offset:256
	s_waitcnt lgkmcnt(0)
	s_nop 0
	v_add_f32_e32 v48, v58, v59
	ds_bpermute_b32 v49, v187, v48
	v_cvt_pk_bf16_f32 v50, v52, v53
	v_cvt_pk_bf16_f32 v51, v54, v55
	v_cvt_pk_bf16_f32 v52, v104, v105
	v_cvt_pk_bf16_f32 v53, v102, v103
	ds_bpermute_b32 v244, v253, v50
	ds_bpermute_b32 v245, v253, v51
	ds_bpermute_b32 v246, v253, v52
	ds_bpermute_b32 v247, v253, v53
	v_lshl_add_u64 v[238:239], v[56:57], 0, v[250:251]
	s_waitcnt lgkmcnt(4)
	global_store_dwordx4 v[236:237], v[240:243], off
	s_and_saveexec_b64 s[34:35], s[4:5]
	s_cbranch_execz .LBB0_929
; __device__ __forceinline__ unsigned cvt_pk_bf16(float lo, float hi) { unsigned r; asm volatile("v_cvt_pk_bf16_f32 %0, %1, %2" : "=v"(r) : "v"(lo), "v"(hi)); return r; }
;     __device__ __forceinline__ void operator()(const f32x4 (&acc)[2][2][4][2], const Unit& u, int wr, int wc, int fr, int fq) const {
;     ...
;             for (int m = 0; m < 4; ++m) {
;                 const int row = row0 + ai * HALF + m * 16; const size_t off = (size_t)row * 1024 + col0;
;                 float ss = 0.f;
; #pragma unroll
;                 for (int bj = 0; bj < 2; ++bj) {
;                     f32x4 b0, b1;
;                     if (BASE_BF16) { const u32x4 w = bw[m][bj];
;                         b0 = (f32x4){__builtin_bit_cast(float, w.x << 16), __builtin_bit_cast(float, w.x & 0xffff0000u), __builtin_bit_cast(float, w.y << 16), __builtin_bit_cast(float, w.y & 0xffff0000u)};
;                         b1 = (f32x4){__builtin_bit_cast(float, w.z << 16), __builtin_bit_cast(float, w.z & 0xffff0000u), __builtin_bit_cast(float, w.w << 16), __builtin_bit_cast(float, w.w & 0xffff0000u)}; }
;                     else { b0 = bf[m][bj][0]; b1 = bf[m][bj][1]; }
;                     const f32x4 v0 = acc[ai][bj][m][0] + b0, v1 = acc[ai][bj][m][1] + b1;
;                     ss += (v0[0] * v0[0] + v0[1] * v0[1]) + (v0[2] * v0[2] + v0[3] * v0[3]) + (v1[0] * v1[0] + v1[1] * v1[1]) + (v1[2] * v1[2] + v1[3] * v1[3]);
;                     if (OUT_BF16) { u32x4 w; w.x = cvt_pk_bf16(v0[0], v0[1]); w.y = cvt_pk_bf16(v0[2], v0[3]); w.z = cvt_pk_bf16(v1[0], v1[1]); w.w = cvt_pk_bf16(v1[2], v1[3]);
;                         *(u32x4*)((bf16_t*)out + off + bj * HALF) = w; }
;                     else { *(f32x4*)((float*)out + off + bj * HALF) = v0; *(f32x4*)((float*)out + off + bj * HALF + 4) = v1; }
;                 }
;                 ss += __shfl_xor(ss, 16); ss += __shfl_xor(ss, 32);
;                 if (fq == 0) sspart[(size_t)row * 16 + u.pn * 4 + wc] = ss;
	v_lshlrev_b64 v[50:51], 6, v[100:101]
	v_lshl_add_u64 v[50:51], s[14:15], 0, v[50:51]
	v_lshl_add_u64 v[50:51], s[30:31], 2, v[50:51]
	s_lshl_b32 s8, s46, 2
	v_lshl_add_u64 v[50:51], v[50:51], 0, s[8:9]
	s_waitcnt lgkmcnt(0)
	v_add_f32_e32 v48, v48, v49
	global_store_dword v[50:51], v48, off
.LBB0_929:
	s_or_b64 exec, exec, s[34:35]
	s_waitcnt vmcnt(7)
	v_lshlrev_b32_e32 v48, 16, v84
	s_waitcnt lgkmcnt(0)
	v_and_b32_e32 v49, 0xffff0000, v84
	v_lshlrev_b32_e32 v50, 16, v85
	v_and_b32_e32 v51, 0xffff0000, v85
	v_lshlrev_b32_e32 v52, 16, v86
	v_and_b32_e32 v53, 0xffff0000, v86
	v_lshlrev_b32_e32 v54, 16, v87
	v_and_b32_e32 v55, 0xffff0000, v87
	v_pk_add_f32 v[46:47], v[46:47], v[50:51]
	v_pk_add_f32 v[44:45], v[44:45], v[48:49]
	v_pk_add_f32 v[48:49], v[42:43], v[54:55]
	v_pk_add_f32 v[42:43], v[40:41], v[52:53]
	v_mul_f32_e32 v40, v45, v45
	v_mul_f32_e32 v41, v47, v47
	v_fmac_f32_e32 v40, v44, v44
	v_fmac_f32_e32 v41, v46, v46
	v_add_f32_e32 v40, v40, v41
	v_mul_f32_e32 v41, v43, v43
	v_fmac_f32_e32 v41, v42, v42
	v_add_f32_e32 v40, v41, v40
	v_mul_f32_e32 v41, v49, v49
	v_fmac_f32_e32 v41, v48, v48
	v_add_f32_e32 v52, v41, v40
	v_cvt_pk_bf16_f32 v40, v44, v45
	v_cvt_pk_bf16_f32 v41, v46, v47
	s_waitcnt vmcnt(6)
	v_lshlrev_b32_e32 v44, 16, v80
	v_and_b32_e32 v45, 0xffff0000, v80
	v_lshlrev_b32_e32 v46, 16, v81
	v_and_b32_e32 v47, 0xffff0000, v81
	v_cvt_pk_bf16_f32 v42, v42, v43
	v_cvt_pk_bf16_f32 v43, v48, v49
	v_lshlrev_b32_e32 v48, 16, v82
	v_and_b32_e32 v49, 0xffff0000, v82
	v_pk_add_f32 v[38:39], v[38:39], v[46:47]
	v_pk_add_f32 v[36:37], v[36:37], v[44:45]
	v_pk_add_f32 v[46:47], v[32:33], v[48:49]
	v_mul_f32_e32 v32, v37, v37
	v_mul_f32_e32 v33, v39, v39
	v_fmac_f32_e32 v32, v36, v36
	v_fmac_f32_e32 v33, v38, v38
	v_lshlrev_b32_e32 v50, 16, v83
	v_and_b32_e32 v51, 0xffff0000, v83
	v_add_f32_e32 v32, v32, v33
	v_mul_f32_e32 v33, v47, v47
	v_pk_add_f32 v[44:45], v[34:35], v[50:51]
	v_fmac_f32_e32 v33, v46, v46
	v_add_f32_e32 v32, v33, v32
	v_mul_f32_e32 v33, v45, v45
	v_fmac_f32_e32 v33, v44, v44
	v_add_f32_e32 v32, v33, v32
	v_add_f32_e32 v35, v52, v32
	ds_bpermute_b32 v50, v186, v35
	v_lshl_add_u64 v[32:33], s[12:13], 0, v[98:99]
	v_lshl_add_u64 v[48:49], v[168:169], 1, v[32:33]
	ds_bpermute_b32 v240, v253, v40
	ds_bpermute_b32 v241, v253, v41
	ds_bpermute_b32 v242, v253, v42
	ds_bpermute_b32 v243, v253, v43
	v_lshl_add_u64 v[236:237], v[48:49], 0, v[250:251]
	s_waitcnt lgkmcnt(4)
	global_store_dwordx4 v[238:239], v[244:247], off offset:256
	v_cvt_pk_bf16_f32 v34, v36, v37
	s_waitcnt lgkmcnt(0)
	v_add_f32_e32 v32, v35, v50
	ds_bpermute_b32 v33, v187, v32
	v_cvt_pk_bf16_f32 v35, v38, v39
	v_cvt_pk_bf16_f32 v36, v46, v47
	v_cvt_pk_bf16_f32 v37, v44, v45
	ds_bpermute_b32 v244, v253, v34
	ds_bpermute_b32 v245, v253, v35
	ds_bpermute_b32 v246, v253, v36
	ds_bpermute_b32 v247, v253, v37
	v_lshl_add_u64 v[238:239], v[48:49], 0, v[250:251]
	s_waitcnt lgkmcnt(4)
	global_store_dwordx4 v[236:237], v[240:243], off
	s_and_saveexec_b64 s[34:35], s[4:5]
	s_cbranch_execz .LBB0_931
	v_lshlrev_b64 v[34:35], 6, v[96:97]
	v_lshl_add_u64 v[34:35], s[14:15], 0, v[34:35]
	v_lshl_add_u64 v[34:35], s[30:31], 2, v[34:35]
	s_lshl_b32 s8, s46, 2
	v_lshl_add_u64 v[34:35], v[34:35], 0, s[8:9]
	s_waitcnt lgkmcnt(0)
	v_add_f32_e32 v32, v32, v33
	global_store_dword v[34:35], v32, off
; __device__ __forceinline__ unsigned cvt_pk_bf16(float lo, float hi) { unsigned r; asm volatile("v_cvt_pk_bf16_f32 %0, %1, %2" : "=v"(r) : "v"(lo), "v"(hi)); return r; }
;     __device__ __forceinline__ void operator()(const f32x4 (&acc)[2][2][4][2], const Unit& u, int wr, int wc, int fr, int fq) const {
;     ...
;             for (int m = 0; m < 4; ++m) {
;                 const int row = row0 + ai * HALF + m * 16; const size_t off = (size_t)row * 1024 + col0;
;                 float ss = 0.f;
; #pragma unroll
;                 for (int bj = 0; bj < 2; ++bj) {
;                     f32x4 b0, b1;
;                     if (BASE_BF16) { const u32x4 w = bw[m][bj];
;                         b0 = (f32x4){__builtin_bit_cast(float, w.x << 16), __builtin_bit_cast(float, w.x & 0xffff0000u), __builtin_bit_cast(float, w.y << 16), __builtin_bit_cast(float, w.y & 0xffff0000u)};
;                         b1 = (f32x4){__builtin_bit_cast(float, w.z << 16), __builtin_bit_cast(float, w.z & 0xffff0000u), __builtin_bit_cast(float, w.w << 16), __builtin_bit_cast(float, w.w & 0xffff0000u)}; }
;                     else { b0 = bf[m][bj][0]; b1 = bf[m][bj][1]; }
;                     const f32x4 v0 = acc[ai][bj][m][0] + b0, v1 = acc[ai][bj][m][1] + b1;
;                     ss += (v0[0] * v0[0] + v0[1] * v0[1]) + (v0[2] * v0[2] + v0[3] * v0[3]) + (v1[0] * v1[0] + v1[1] * v1[1]) + (v1[2] * v1[2] + v1[3] * v1[3]);
;                     if (OUT_BF16) { u32x4 w; w.x = cvt_pk_bf16(v0[0], v0[1]); w.y = cvt_pk_bf16(v0[2], v0[3]); w.z = cvt_pk_bf16(v1[0], v1[1]); w.w = cvt_pk_bf16(v1[2], v1[3]);
;                         *(u32x4*)((bf16_t*)out + off + bj * HALF) = w; }
;                     else { *(f32x4*)((float*)out + off + bj * HALF) = v0; *(f32x4*)((float*)out + off + bj * HALF + 4) = v1; }
;                 }
;                 ss += __shfl_xor(ss, 16); ss += __shfl_xor(ss, 32);
;                 if (fq == 0) sspart[(size_t)row * 16 + u.pn * 4 + wc] = ss;
.LBB0_931:
	s_or_b64 exec, exec, s[34:35]
	s_waitcnt vmcnt(7)
	v_lshlrev_b32_e32 v32, 16, v76
	s_waitcnt lgkmcnt(0)
	v_and_b32_e32 v33, 0xffff0000, v76
	v_lshlrev_b32_e32 v34, 16, v77
	v_and_b32_e32 v35, 0xffff0000, v77
	v_lshlrev_b32_e32 v36, 16, v78
	v_and_b32_e32 v37, 0xffff0000, v78
	v_lshlrev_b32_e32 v38, 16, v79
	v_and_b32_e32 v39, 0xffff0000, v79
	v_pk_add_f32 v[30:31], v[30:31], v[34:35]
	v_pk_add_f32 v[28:29], v[28:29], v[32:33]
	v_pk_add_f32 v[32:33], v[26:27], v[38:39]
	v_pk_add_f32 v[26:27], v[24:25], v[36:37]
	v_mul_f32_e32 v24, v29, v29
	v_mul_f32_e32 v25, v31, v31
	v_fmac_f32_e32 v24, v28, v28
	v_fmac_f32_e32 v25, v30, v30
	v_add_f32_e32 v24, v24, v25
	v_mul_f32_e32 v25, v27, v27
	v_fmac_f32_e32 v25, v26, v26
	v_add_f32_e32 v24, v25, v24
	v_mul_f32_e32 v25, v33, v33
	v_fmac_f32_e32 v25, v32, v32
	v_add_f32_e32 v36, v25, v24
	v_cvt_pk_bf16_f32 v24, v28, v29
	v_cvt_pk_bf16_f32 v25, v30, v31
	s_waitcnt vmcnt(6)
	v_lshlrev_b32_e32 v28, 16, v72
	v_and_b32_e32 v29, 0xffff0000, v72
	v_lshlrev_b32_e32 v30, 16, v73
	v_and_b32_e32 v31, 0xffff0000, v73
	v_cvt_pk_bf16_f32 v26, v26, v27
	v_cvt_pk_bf16_f32 v27, v32, v33
	v_lshlrev_b32_e32 v32, 16, v74
	v_and_b32_e32 v33, 0xffff0000, v74
	v_pk_add_f32 v[22:23], v[22:23], v[30:31]
	v_pk_add_f32 v[20:21], v[20:21], v[28:29]
	v_pk_add_f32 v[30:31], v[16:17], v[32:33]
	v_mul_f32_e32 v16, v21, v21
	v_mul_f32_e32 v17, v23, v23
	v_fmac_f32_e32 v16, v20, v20
	v_fmac_f32_e32 v17, v22, v22
	v_lshlrev_b32_e32 v34, 16, v75
	v_and_b32_e32 v35, 0xffff0000, v75
	v_add_f32_e32 v16, v16, v17
	v_mul_f32_e32 v17, v31, v31
	v_pk_add_f32 v[28:29], v[18:19], v[34:35]
	v_fmac_f32_e32 v17, v30, v30
	v_add_f32_e32 v16, v17, v16
	v_mul_f32_e32 v17, v29, v29
	v_fmac_f32_e32 v17, v28, v28
	v_add_f32_e32 v16, v17, v16
	v_add_f32_e32 v19, v36, v16
	ds_bpermute_b32 v34, v186, v19
	v_lshl_add_u64 v[16:17], s[12:13], 0, v[94:95]
	v_lshl_add_u64 v[32:33], v[168:169], 1, v[16:17]
	ds_bpermute_b32 v240, v253, v24
	ds_bpermute_b32 v241, v253, v25
	ds_bpermute_b32 v242, v253, v26
	ds_bpermute_b32 v243, v253, v27
	v_lshl_add_u64 v[236:237], v[32:33], 0, v[250:251]
	s_waitcnt lgkmcnt(4)
	global_store_dwordx4 v[238:239], v[244:247], off offset:256
	v_cvt_pk_bf16_f32 v18, v20, v21
	s_waitcnt lgkmcnt(0)
	v_add_f32_e32 v16, v19, v34
	ds_bpermute_b32 v17, v187, v16
	v_cvt_pk_bf16_f32 v19, v22, v23
	v_cvt_pk_bf16_f32 v20, v30, v31
	v_cvt_pk_bf16_f32 v21, v28, v29
	ds_bpermute_b32 v244, v253, v18
	ds_bpermute_b32 v245, v253, v19
	ds_bpermute_b32 v246, v253, v20
	ds_bpermute_b32 v247, v253, v21
	v_lshl_add_u64 v[238:239], v[32:33], 0, v[250:251]
	s_waitcnt lgkmcnt(4)
	global_store_dwordx4 v[236:237], v[240:243], off
	s_and_saveexec_b64 s[34:35], s[4:5]
	s_cbranch_execz .LBB0_933
	v_lshlrev_b64 v[18:19], 6, v[92:93]
	v_lshl_add_u64 v[18:19], s[14:15], 0, v[18:19]
	v_lshl_add_u64 v[18:19], s[30:31], 2, v[18:19]
	s_lshl_b32 s8, s46, 2
	v_lshl_add_u64 v[18:19], v[18:19], 0, s[8:9]
	s_waitcnt lgkmcnt(0)
	v_add_f32_e32 v16, v16, v17
	global_store_dword v[18:19], v16, off
.LBB0_933:
	s_or_b64 exec, exec, s[34:35]
	s_waitcnt vmcnt(7)
	v_lshlrev_b32_e32 v16, 16, v68
	s_waitcnt lgkmcnt(0)
	v_and_b32_e32 v17, 0xffff0000, v68
	v_lshlrev_b32_e32 v18, 16, v69
	v_and_b32_e32 v19, 0xffff0000, v69
	v_lshlrev_b32_e32 v20, 16, v70
	v_and_b32_e32 v21, 0xffff0000, v70
	v_lshlrev_b32_e32 v22, 16, v71
	v_and_b32_e32 v23, 0xffff0000, v71
	v_pk_add_f32 v[14:15], v[14:15], v[18:19]
	v_pk_add_f32 v[12:13], v[12:13], v[16:17]
	v_pk_add_f32 v[16:17], v[10:11], v[22:23]
	v_pk_add_f32 v[10:11], v[8:9], v[20:21]
	v_mul_f32_e32 v8, v13, v13
	v_mul_f32_e32 v9, v15, v15
	v_fmac_f32_e32 v8, v12, v12
	v_fmac_f32_e32 v9, v14, v14
	v_add_f32_e32 v8, v8, v9
	v_mul_f32_e32 v9, v11, v11
	v_fmac_f32_e32 v9, v10, v10
	v_add_f32_e32 v8, v9, v8
	v_mul_f32_e32 v9, v17, v17
	v_fmac_f32_e32 v9, v16, v16
	v_add_f32_e32 v20, v9, v8
	v_cvt_pk_bf16_f32 v8, v12, v13
	v_cvt_pk_bf16_f32 v9, v14, v15
	s_waitcnt vmcnt(6)
	v_lshlrev_b32_e32 v12, 16, v64
	v_and_b32_e32 v13, 0xffff0000, v64
	v_lshlrev_b32_e32 v14, 16, v65
	v_and_b32_e32 v15, 0xffff0000, v65
	v_cvt_pk_bf16_f32 v10, v10, v11
	v_cvt_pk_bf16_f32 v11, v16, v17
	v_lshlrev_b32_e32 v16, 16, v66
	v_and_b32_e32 v17, 0xffff0000, v66
	v_pk_add_f32 v[6:7], v[6:7], v[14:15]
	v_pk_add_f32 v[4:5], v[4:5], v[12:13]
	v_pk_add_f32 v[14:15], v[0:1], v[16:17]
	v_mul_f32_e32 v0, v5, v5
	v_mul_f32_e32 v1, v7, v7
	v_fmac_f32_e32 v0, v4, v4
	v_fmac_f32_e32 v1, v6, v6
	v_lshlrev_b32_e32 v18, 16, v67
	v_and_b32_e32 v19, 0xffff0000, v67
	v_add_f32_e32 v0, v0, v1
	v_mul_f32_e32 v1, v15, v15
	v_pk_add_f32 v[12:13], v[2:3], v[18:19]
	v_fmac_f32_e32 v1, v14, v14
	v_add_f32_e32 v0, v1, v0
	v_mul_f32_e32 v1, v13, v13
	v_fmac_f32_e32 v1, v12, v12
	v_add_f32_e32 v0, v1, v0
	v_add_f32_e32 v3, v20, v0
	ds_bpermute_b32 v18, v186, v3
	v_lshl_add_u64 v[0:1], s[12:13], 0, v[90:91]
	v_lshl_add_u64 v[16:17], v[168:169], 1, v[0:1]
	ds_bpermute_b32 v240, v253, v8
	ds_bpermute_b32 v241, v253, v9
	ds_bpermute_b32 v242, v253, v10
	ds_bpermute_b32 v243, v253, v11
	v_lshl_add_u64 v[236:237], v[16:17], 0, v[250:251]
	s_waitcnt lgkmcnt(4)
	global_store_dwordx4 v[238:239], v[244:247], off offset:256
	v_cvt_pk_bf16_f32 v2, v4, v5
	s_waitcnt lgkmcnt(0)
	v_add_f32_e32 v0, v3, v18
	ds_bpermute_b32 v1, v187, v0
	v_cvt_pk_bf16_f32 v3, v6, v7
	v_cvt_pk_bf16_f32 v4, v14, v15
	v_cvt_pk_bf16_f32 v5, v12, v13
	ds_bpermute_b32 v244, v253, v2
	ds_bpermute_b32 v245, v253, v3
	ds_bpermute_b32 v246, v253, v4
	ds_bpermute_b32 v247, v253, v5
	v_lshl_add_u64 v[238:239], v[16:17], 0, v[250:251]
	s_waitcnt lgkmcnt(4)
	global_store_dwordx4 v[236:237], v[240:243], off
	s_waitcnt lgkmcnt(0)
	global_store_dwordx4 v[238:239], v[244:247], off offset:256
	s_and_saveexec_b64 s[34:35], s[4:5]
	s_cbranch_execz .LBB0_935
	v_lshlrev_b64 v[2:3], 6, v[88:89]
	v_lshl_add_u64 v[2:3], s[14:15], 0, v[2:3]
	v_lshl_add_u64 v[2:3], s[30:31], 2, v[2:3]
	s_lshl_b32 s8, s46, 2
	v_lshl_add_u64 v[2:3], v[2:3], 0, s[8:9]
	s_waitcnt lgkmcnt(0)
	v_add_f32_e32 v0, v0, v1
	global_store_dword v[2:3], v0, off

; __device__ __forceinline__ int mk_lane() { int l = (int)__builtin_amdgcn_mbcnt_hi(~0u, __builtin_amdgcn_mbcnt_lo(~0u, 0u)); asm volatile("" : "+v"(l)); return l; }
; #define LAS __attribute__((address_space(3)))
; #define PH(k) (IN(k) && ((MK_MASK >> (k)) & 1))
; #define REPS(k) for (int rep_ = 0; rep_ < (((MK_REP_MASK) >> (k)) & 1) + 1; ++rep_)
; template <class Sched> __device__ __forceinline__ void build_rstd_tables(LAS unsigned char* lds, const Sched& S, const float* sspart, float eps, int wave) {
;     const int lane = mk_lane(), tid = wave * 64 + lane;
;     LAS int* pml = (LAS int*)(lds + RING_BYTES + 1536); LAS float* tab = (LAS float*)(lds + RING_BYTES + 2048);
;     if (tid == 0) { int n = 0; pg8::Unit u; for (int i = 0; S.next(i, u); ++i) { bool f = false; for (int j = 0; j < n; ++j) f |= (pml[j] == u.pm); if (!f && n < 8) pml[n++] = u.pm; } pml[8] = n; }
; __global__ void __launch_bounds__(NWAVES * 64, 2) mk_fwd(Params P) {
;     ...
;     if (PH(5)) REPS(5) { pg8::Gemm g{H1B, Wcq_t, M, D, D}; pg8::StaticOrder S; S.init(M, D, G, bx);
;         build_rstd_tables(lds, S, SS1, EPS, wave);
.LBB0_991:
	s_cmp_lt_i32 s74, 6
	s_cselect_b64 s[0:1], -1, 0
	s_and_b64 s[36:37], s[0:1], s[4:5]
	s_andn2_b64 vcc, exec, s[36:37]
	s_cbranch_vccnz .LBB0_1089
	v_and_b32_e32 v248, 15, v212
	v_lshrrev_b32_e32 v249, 2, v212
	v_sub_u32_e32 v249, v249, v248
	v_lshrrev_b32_e32 v248, 4, v212
	v_and_b32_e32 v253, 3, v212
	v_sub_u32_e32 v248, v253, v248
	v_lshlrev_b32_e32 v248, 4, v248
	v_mul_i32_i24_e32 v250, 0x800, v249
	v_add_u32_e32 v250, v250, v248
	v_ashrrev_i32_e32 v251, 31, v250
	v_lshlrev_b32_e32 v253, 4, v253
	v_lshrrev_b32_e32 v248, 2, v212
	v_add_u32_e32 v253, v253, v248
	v_lshlrev_b32_e32 v253, 2, v253
	s_and_b32 s20, s93, 0xffffffc0
	v_mov_b32_e32 v3, v212
	s_ashr_i32 s2, s82, 31
	v_add_u32_e32 v2, s20, v3
	s_ashr_i32 s3, s88, 31
	s_mov_b32 s21, 0
	v_cmp_eq_u32_e32 vcc, 0, v2
	s_and_saveexec_b64 s[38:39], vcc
	s_cbranch_execz .LBB0_1018
	s_waitcnt lgkmcnt(0)
	v_mov_b64_e32 v[0:1], 0x1ff
	s_add_i32 s33, 0, 0x20600
	s_mov_b32 s1, 0
	s_branch .LBB0_996

; __device__ __forceinline__ unsigned cvt_pk_bf16(float lo, float hi) { unsigned r; asm volatile("v_cvt_pk_bf16_f32 %0, %1, %2" : "=v"(r) : "v"(lo), "v"(hi)); return r; }
; __device__ __forceinline__ float row_rstd(const float* part, int row, float eps) {
;     const f32x4* p = (const f32x4*)(part + (size_t)row * 16);
;     const f32x4 a = p[0], b = p[1], c = p[2], d = p[3];
;     const float s = ((a[0] + a[1]) + (a[2] + a[3])) + ((b[0] + b[1]) + (b[2] + b[3])) + ((c[0] + c[1]) + (c[2] + c[3])) + ((d[0] + d[1]) + (d[2] + d[3]));
;     return 1.0f / sqrtf(s * (1.0f / 1024.0f) + eps);
; }
;     __device__ __forceinline__ void operator()(const f32x4 (&acc)[2][2][4][2], const Unit& u, int wr, int wc, int fr, int fq) const {
;     ...
;                 const int row = row0 + ai * HALF + m * 16; bf16_t* rowp = O + (size_t)row * ldc + col0;
;                 const float r = (slot >= 0 ? tab[slot * 256 + (row - u.pm * BM)] : row_rstd(sspart, row, eps)) * sc;
; #pragma unroll
;                 for (int bj = 0; bj < 2; ++bj) {
;                     f32x4 v0 = acc[ai][bj][m][0] * r, v1 = acc[ai][bj][m][1] * r;
;                     if (ACT == 1) {
; #pragma unroll
;                         for (int e = 0; e < 4; ++e) { const float a = fmaxf(v0[e], 0.f), b = fmaxf(v1[e], 0.f); v0[e] = a * a; v1[e] = b * b; }
;                     }
;                     u32x4 w; w.x = cvt_pk_bf16(v0[0], v0[1]); w.y = cvt_pk_bf16(v0[2], v0[3]); w.z = cvt_pk_bf16(v1[0], v1[1]); w.w = cvt_pk_bf16(v1[2], v1[3]);
;                     *(u32x4*)(rowp + bj * HALF) = w;
.LBB0_1057:
	v_lshl_or_b32 v146, s6, 8, v151
	v_lshlrev_b64 v[160:161], 11, v[144:145]
	v_ashrrev_i32_e32 v147, 31, v146
	v_lshl_add_u64 v[160:161], s[14:15], 0, v[160:161]
	s_waitcnt lgkmcnt(0)
	v_mul_f32_e32 v158, 0x3db8aa3b, v158
	v_lshl_add_u64 v[160:161], v[146:147], 1, v[160:161]
	v_pk_mul_f32 v[126:127], v[126:127], v[158:159] op_sel_hi:[1,0]
	v_pk_mul_f32 v[124:125], v[124:125], v[158:159] op_sel_hi:[1,0]
	v_pk_mul_f32 v[162:163], v[122:123], v[158:159] op_sel_hi:[1,0]
	v_pk_mul_f32 v[122:123], v[120:121], v[158:159] op_sel_hi:[1,0]
	v_cvt_pk_bf16_f32 v120, v124, v125
	v_cvt_pk_bf16_f32 v121, v126, v127
	v_pk_mul_f32 v[118:119], v[118:119], v[158:159] op_sel_hi:[1,0]
	v_cvt_pk_bf16_f32 v122, v122, v123
	v_cvt_pk_bf16_f32 v123, v162, v163
	ds_bpermute_b32 v240, v253, v120
	ds_bpermute_b32 v241, v253, v121
	ds_bpermute_b32 v242, v253, v122
	ds_bpermute_b32 v243, v253, v123
	v_lshl_add_u64 v[236:237], v[160:161], 0, v[250:251]
	v_pk_mul_f32 v[116:117], v[116:117], v[158:159] op_sel_hi:[1,0]
	s_andn2_b64 vcc, exec, s[8:9]
	v_pk_mul_f32 v[120:121], v[114:115], v[158:159] op_sel_hi:[1,0]
	v_pk_mul_f32 v[114:115], v[112:113], v[158:159] op_sel_hi:[1,0]
	v_cvt_pk_bf16_f32 v112, v116, v117
	v_cvt_pk_bf16_f32 v113, v118, v119
	s_mov_b64 s[0:1], -1
	v_cvt_pk_bf16_f32 v114, v114, v115
	v_cvt_pk_bf16_f32 v115, v120, v121
	ds_bpermute_b32 v244, v253, v112
	ds_bpermute_b32 v245, v253, v113
	ds_bpermute_b32 v246, v253, v114
	ds_bpermute_b32 v247, v253, v115
	v_lshl_add_u64 v[238:239], v[160:161], 0, v[250:251]
	s_waitcnt lgkmcnt(4)
	global_store_dwordx4 v[236:237], v[240:243], off
	s_nop 1
	v_or_b32_e32 v112, 16, v144
	v_cndmask_b32_e64 v114, 0, 1, s[8:9]
	v_ashrrev_i32_e32 v113, 31, v112
	v_cmp_ne_u32_e64 s[6:7], 1, v114
	s_cbranch_vccnz .LBB0_1059
	v_lshlrev_b64 v[114:115], 6, v[112:113]
	v_lshl_add_u64 v[126:127], s[10:11], 0, v[114:115]
	global_load_dwordx4 v[114:117], v[126:127], off
	global_load_dwordx4 v[118:121], v[126:127], off offset:16
	global_load_dwordx4 v[122:125], v[126:127], off offset:32
	global_load_dwordx4 v[158:161], v[126:127], off offset:48
	s_waitcnt vmcnt(0)
	v_mov_b32_e32 v126, v115
	v_mov_b32_e32 v127, v116
	v_mov_b32_e32 v115, v117
	v_mov_b32_e32 v116, v119
	v_mov_b32_e32 v117, v120
	v_mov_b32_e32 v119, v121
	v_pk_add_f32 v[114:115], v[126:127], v[114:115]
	v_pk_add_f32 v[116:117], v[116:117], v[118:119]
	v_pk_add_f32 v[114:115], v[114:115], v[114:115] op_sel:[0,1] op_sel_hi:[1,0]
	v_pk_add_f32 v[116:117], v[116:117], v[116:117] op_sel:[0,1] op_sel_hi:[1,0]
	v_add_f32_e32 v120, v122, v123
	v_add_f32_e32 v122, v124, v125
	v_mov_b32_e32 v121, v160
	v_mov_b32_e32 v123, v161
	v_mov_b32_e32 v115, v158
	v_mov_b32_e32 v117, v159
	v_pk_add_f32 v[118:119], v[120:121], v[122:123]
	v_pk_add_f32 v[114:115], v[114:115], v[116:117]
	s_nop 0
	v_pk_add_f32 v[114:115], v[114:115], v[118:119]
	s_nop 0
	v_add_f32_e32 v114, v114, v115
	v_fmamk_f32 v114, v114, 0x3a800000, v155
	v_mul_f32_e32 v115, 0x4f800000, v114
	v_cmp_gt_f32_e32 vcc, s55, v114
	s_nop 1
	v_cndmask_b32_e32 v114, v114, v115, vcc
	v_sqrt_f32_e32 v115, v114
	s_nop 0
	v_add_u32_e32 v116, -1, v115
	v_add_u32_e32 v117, 1, v115
	v_fma_f32 v118, -v116, v115, v114
	v_fma_f32 v119, -v117, v115, v114
	v_cmp_ge_f32_e64 s[0:1], 0, v118
	s_nop 1
	v_cndmask_b32_e64 v115, v115, v116, s[0:1]
	v_cmp_lt_f32_e64 s[0:1], 0, v119
	s_nop 1
	v_cndmask_b32_e64 v115, v115, v117, s[0:1]
	v_mul_f32_e32 v116, 0x37800000, v115
	v_cndmask_b32_e32 v115, v115, v116, vcc
	v_cmp_class_f32_e32 vcc, v114, v156
	s_nop 1
	v_cndmask_b32_e32 v114, v115, v114, vcc
	v_div_scale_f32 v115, s[0:1], v114, v114, 1.0
	v_rcp_f32_e32 v116, v115
	v_div_scale_f32 v117, vcc, 1.0, v114, 1.0
	s_mov_b64 s[0:1], 0
	v_fma_f32 v118, -v115, v116, 1.0
	v_fmac_f32_e32 v116, v118, v116
	v_mul_f32_e32 v118, v117, v116
	v_fma_f32 v119, -v115, v118, v117
	v_fmac_f32_e32 v118, v119, v116
	v_fma_f32 v115, -v115, v118, v117
	v_div_fmas_f32 v115, v115, v116, v118
	v_div_fixup_f32 v114, v115, v114, 1.0

; __device__ __forceinline__ unsigned cvt_pk_bf16(float lo, float hi) { unsigned r; asm volatile("v_cvt_pk_bf16_f32 %0, %1, %2" : "=v"(r) : "v"(lo), "v"(hi)); return r; }
; __device__ __forceinline__ float row_rstd(const float* part, int row, float eps) {
;     const f32x4* p = (const f32x4*)(part + (size_t)row * 16);
;     const f32x4 a = p[0], b = p[1], c = p[2], d = p[3];
;     const float s = ((a[0] + a[1]) + (a[2] + a[3])) + ((b[0] + b[1]) + (b[2] + b[3])) + ((c[0] + c[1]) + (c[2] + c[3])) + ((d[0] + d[1]) + (d[2] + d[3]));
;     return 1.0f / sqrtf(s * (1.0f / 1024.0f) + eps);
; }
;     __device__ __forceinline__ void operator()(const f32x4 (&acc)[2][2][4][2], const Unit& u, int wr, int wc, int fr, int fq) const {
;     ...
;                 const int row = row0 + ai * HALF + m * 16; bf16_t* rowp = O + (size_t)row * ldc + col0;
;                 const float r = (slot >= 0 ? tab[slot * 256 + (row - u.pm * BM)] : row_rstd(sspart, row, eps)) * sc;
; #pragma unroll
;                 for (int bj = 0; bj < 2; ++bj) {
;                     f32x4 v0 = acc[ai][bj][m][0] * r, v1 = acc[ai][bj][m][1] * r;
;                     if (ACT == 1) {
; #pragma unroll
;                         for (int e = 0; e < 4; ++e) { const float a = fmaxf(v0[e], 0.f), b = fmaxf(v1[e], 0.f); v0[e] = a * a; v1[e] = b * b; }
;                     }
;                     u32x4 w; w.x = cvt_pk_bf16(v0[0], v0[1]); w.y = cvt_pk_bf16(v0[2], v0[3]); w.z = cvt_pk_bf16(v1[0], v1[1]); w.w = cvt_pk_bf16(v1[2], v1[3]);
;                     *(u32x4*)(rowp + bj * HALF) = w;
.LBB0_1061:
	v_lshlrev_b64 v[112:113], 11, v[112:113]
	v_lshl_add_u64 v[112:113], s[14:15], 0, v[112:113]
	s_waitcnt lgkmcnt(0)
	v_mul_f32_e32 v114, 0x3db8aa3b, v114
	v_lshl_add_u64 v[112:113], v[146:147], 1, v[112:113]
	v_pk_mul_f32 v[110:111], v[110:111], v[114:115] op_sel_hi:[1,0]
	v_pk_mul_f32 v[108:109], v[108:109], v[114:115] op_sel_hi:[1,0]
	v_pk_mul_f32 v[116:117], v[106:107], v[114:115] op_sel_hi:[1,0]
	v_pk_mul_f32 v[106:107], v[104:105], v[114:115] op_sel_hi:[1,0]
	v_cvt_pk_bf16_f32 v104, v108, v109
	v_cvt_pk_bf16_f32 v105, v110, v111
	v_pk_mul_f32 v[100:101], v[100:101], v[114:115] op_sel_hi:[1,0]
	v_cvt_pk_bf16_f32 v106, v106, v107
	v_cvt_pk_bf16_f32 v107, v116, v117
	ds_bpermute_b32 v240, v253, v104
	ds_bpermute_b32 v241, v253, v105
	ds_bpermute_b32 v242, v253, v106
	ds_bpermute_b32 v243, v253, v107
	v_lshl_add_u64 v[236:237], v[112:113], 0, v[250:251]
	s_waitcnt lgkmcnt(4)
	global_store_dwordx4 v[238:239], v[244:247], off offset:256
	v_pk_mul_f32 v[102:103], v[102:103], v[114:115] op_sel_hi:[1,0]
	s_and_b64 vcc, exec, s[6:7]
	v_pk_mul_f32 v[104:105], v[98:99], v[114:115] op_sel_hi:[1,0]
	v_pk_mul_f32 v[98:99], v[96:97], v[114:115] op_sel_hi:[1,0]
	v_cvt_pk_bf16_f32 v96, v100, v101
	v_cvt_pk_bf16_f32 v97, v102, v103
	s_mov_b64 s[0:1], -1
	v_cvt_pk_bf16_f32 v98, v98, v99
	v_cvt_pk_bf16_f32 v99, v104, v105
	ds_bpermute_b32 v244, v253, v96
	ds_bpermute_b32 v245, v253, v97
	ds_bpermute_b32 v246, v253, v98
	ds_bpermute_b32 v247, v253, v99
	v_lshl_add_u64 v[238:239], v[112:113], 0, v[250:251]
	s_waitcnt lgkmcnt(4)
	global_store_dwordx4 v[236:237], v[240:243], off
	s_nop 1
	v_or_b32_e32 v96, 32, v144
	v_ashrrev_i32_e32 v97, 31, v96
	s_cbranch_vccnz .LBB0_1063
	v_lshlrev_b64 v[98:99], 6, v[96:97]
	v_lshl_add_u64 v[110:111], s[10:11], 0, v[98:99]
	global_load_dwordx4 v[98:101], v[110:111], off
	global_load_dwordx4 v[102:105], v[110:111], off offset:16
	global_load_dwordx4 v[106:109], v[110:111], off offset:32
	s_nop 0
	global_load_dwordx4 v[110:113], v[110:111], off offset:48
	s_waitcnt vmcnt(0)
	v_mov_b32_e32 v114, v99
	v_mov_b32_e32 v115, v100
	v_mov_b32_e32 v99, v101
	v_mov_b32_e32 v100, v103
	v_mov_b32_e32 v101, v104
	v_mov_b32_e32 v103, v105
	v_pk_add_f32 v[98:99], v[114:115], v[98:99]
	v_pk_add_f32 v[100:101], v[100:101], v[102:103]
	v_pk_add_f32 v[98:99], v[98:99], v[98:99] op_sel:[0,1] op_sel_hi:[1,0]
	v_pk_add_f32 v[100:101], v[100:101], v[100:101] op_sel:[0,1] op_sel_hi:[1,0]
	v_add_f32_e32 v104, v106, v107
	v_add_f32_e32 v106, v108, v109
	v_mov_b32_e32 v105, v112
	v_mov_b32_e32 v107, v113
	v_mov_b32_e32 v99, v110
	v_mov_b32_e32 v101, v111
	v_pk_add_f32 v[102:103], v[104:105], v[106:107]
	v_pk_add_f32 v[98:99], v[98:99], v[100:101]
	s_nop 0
	v_pk_add_f32 v[98:99], v[98:99], v[102:103]
	s_nop 0
	v_add_f32_e32 v98, v98, v99
	v_fmamk_f32 v98, v98, 0x3a800000, v155
	v_mul_f32_e32 v99, 0x4f800000, v98
	v_cmp_gt_f32_e32 vcc, s55, v98
	s_nop 1
	v_cndmask_b32_e32 v98, v98, v99, vcc
	v_sqrt_f32_e32 v99, v98
	s_nop 0
	v_add_u32_e32 v100, -1, v99
	v_add_u32_e32 v101, 1, v99
	v_fma_f32 v102, -v100, v99, v98
	v_fma_f32 v103, -v101, v99, v98
	v_cmp_ge_f32_e64 s[0:1], 0, v102
	s_nop 1
	v_cndmask_b32_e64 v99, v99, v100, s[0:1]
	v_cmp_lt_f32_e64 s[0:1], 0, v103
	s_nop 1
	v_cndmask_b32_e64 v99, v99, v101, s[0:1]
	v_mul_f32_e32 v100, 0x37800000, v99
	v_cndmask_b32_e32 v99, v99, v100, vcc
	v_cmp_class_f32_e32 vcc, v98, v156
	s_nop 1
	v_cndmask_b32_e32 v98, v99, v98, vcc
	v_div_scale_f32 v99, s[0:1], v98, v98, 1.0
	v_rcp_f32_e32 v100, v99
	v_div_scale_f32 v101, vcc, 1.0, v98, 1.0
	s_mov_b64 s[0:1], 0
	v_fma_f32 v102, -v99, v100, 1.0
	v_fmac_f32_e32 v100, v102, v100
	v_mul_f32_e32 v102, v101, v100
	v_fma_f32 v103, -v99, v102, v101
	v_fmac_f32_e32 v102, v103, v100
	v_fma_f32 v99, -v99, v102, v101
	v_div_fmas_f32 v99, v99, v100, v102
	v_div_fixup_f32 v98, v99, v98, 1.0

; __device__ __forceinline__ unsigned cvt_pk_bf16(float lo, float hi) { unsigned r; asm volatile("v_cvt_pk_bf16_f32 %0, %1, %2" : "=v"(r) : "v"(lo), "v"(hi)); return r; }
; __device__ __forceinline__ float row_rstd(const float* part, int row, float eps) {
;     const f32x4* p = (const f32x4*)(part + (size_t)row * 16);
;     const f32x4 a = p[0], b = p[1], c = p[2], d = p[3];
;     const float s = ((a[0] + a[1]) + (a[2] + a[3])) + ((b[0] + b[1]) + (b[2] + b[3])) + ((c[0] + c[1]) + (c[2] + c[3])) + ((d[0] + d[1]) + (d[2] + d[3]));
;     return 1.0f / sqrtf(s * (1.0f / 1024.0f) + eps);
; }
;     __device__ __forceinline__ void operator()(const f32x4 (&acc)[2][2][4][2], const Unit& u, int wr, int wc, int fr, int fq) const {
;     ...
;                 const int row = row0 + ai * HALF + m * 16; bf16_t* rowp = O + (size_t)row * ldc + col0;
;                 const float r = (slot >= 0 ? tab[slot * 256 + (row - u.pm * BM)] : row_rstd(sspart, row, eps)) * sc;
; #pragma unroll
;                 for (int bj = 0; bj < 2; ++bj) {
;                     f32x4 v0 = acc[ai][bj][m][0] * r, v1 = acc[ai][bj][m][1] * r;
;                     if (ACT == 1) {
; #pragma unroll
;                         for (int e = 0; e < 4; ++e) { const float a = fmaxf(v0[e], 0.f), b = fmaxf(v1[e], 0.f); v0[e] = a * a; v1[e] = b * b; }
;                     }
;                     u32x4 w; w.x = cvt_pk_bf16(v0[0], v0[1]); w.y = cvt_pk_bf16(v0[2], v0[3]); w.z = cvt_pk_bf16(v1[0], v1[1]); w.w = cvt_pk_bf16(v1[2], v1[3]);
;                     *(u32x4*)(rowp + bj * HALF) = w;
.LBB0_1065:
	v_lshlrev_b64 v[96:97], 11, v[96:97]
	v_lshl_add_u64 v[96:97], s[14:15], 0, v[96:97]
	s_waitcnt lgkmcnt(0)
	v_mul_f32_e32 v98, 0x3db8aa3b, v98
	v_lshl_add_u64 v[96:97], v[146:147], 1, v[96:97]
	v_pk_mul_f32 v[94:95], v[94:95], v[98:99] op_sel_hi:[1,0]
	v_pk_mul_f32 v[92:93], v[92:93], v[98:99] op_sel_hi:[1,0]
	v_pk_mul_f32 v[100:101], v[90:91], v[98:99] op_sel_hi:[1,0]
	v_pk_mul_f32 v[90:91], v[88:89], v[98:99] op_sel_hi:[1,0]
	v_cvt_pk_bf16_f32 v88, v92, v93
	v_cvt_pk_bf16_f32 v89, v94, v95
	v_pk_mul_f32 v[84:85], v[84:85], v[98:99] op_sel_hi:[1,0]
	v_cvt_pk_bf16_f32 v90, v90, v91
	v_cvt_pk_bf16_f32 v91, v100, v101
	ds_bpermute_b32 v240, v253, v88
	ds_bpermute_b32 v241, v253, v89
	ds_bpermute_b32 v242, v253, v90
	ds_bpermute_b32 v243, v253, v91
	v_lshl_add_u64 v[236:237], v[96:97], 0, v[250:251]
	s_waitcnt lgkmcnt(4)
	global_store_dwordx4 v[238:239], v[244:247], off offset:256
	v_pk_mul_f32 v[86:87], v[86:87], v[98:99] op_sel_hi:[1,0]
	s_and_b64 vcc, exec, s[6:7]
	v_pk_mul_f32 v[88:89], v[82:83], v[98:99] op_sel_hi:[1,0]
	v_pk_mul_f32 v[82:83], v[80:81], v[98:99] op_sel_hi:[1,0]
	v_cvt_pk_bf16_f32 v80, v84, v85
	v_cvt_pk_bf16_f32 v81, v86, v87
	s_mov_b64 s[0:1], -1
	v_cvt_pk_bf16_f32 v82, v82, v83
	v_cvt_pk_bf16_f32 v83, v88, v89
	ds_bpermute_b32 v244, v253, v80
	ds_bpermute_b32 v245, v253, v81
	ds_bpermute_b32 v246, v253, v82
	ds_bpermute_b32 v247, v253, v83
	v_lshl_add_u64 v[238:239], v[96:97], 0, v[250:251]
	s_waitcnt lgkmcnt(4)
	global_store_dwordx4 v[236:237], v[240:243], off
	s_nop 1
	v_or_b32_e32 v80, 48, v144
	v_ashrrev_i32_e32 v81, 31, v80
	s_cbranch_vccnz .LBB0_1067
	v_lshlrev_b64 v[82:83], 6, v[80:81]
	v_lshl_add_u64 v[94:95], s[10:11], 0, v[82:83]
	global_load_dwordx4 v[82:85], v[94:95], off
	global_load_dwordx4 v[86:89], v[94:95], off offset:16
	global_load_dwordx4 v[90:93], v[94:95], off offset:32
	s_nop 0
	global_load_dwordx4 v[94:97], v[94:95], off offset:48
	s_waitcnt vmcnt(0)
	v_mov_b32_e32 v98, v83
	v_mov_b32_e32 v99, v84
	v_mov_b32_e32 v83, v85
	v_mov_b32_e32 v84, v87
	v_mov_b32_e32 v85, v88
	v_mov_b32_e32 v87, v89
	v_pk_add_f32 v[82:83], v[98:99], v[82:83]
	v_pk_add_f32 v[84:85], v[84:85], v[86:87]
	v_pk_add_f32 v[82:83], v[82:83], v[82:83] op_sel:[0,1] op_sel_hi:[1,0]
	v_pk_add_f32 v[84:85], v[84:85], v[84:85] op_sel:[0,1] op_sel_hi:[1,0]
	v_add_f32_e32 v88, v90, v91
	v_add_f32_e32 v90, v92, v93
	v_mov_b32_e32 v89, v96
	v_mov_b32_e32 v91, v97
	v_mov_b32_e32 v83, v94
	v_mov_b32_e32 v85, v95
	v_pk_add_f32 v[86:87], v[88:89], v[90:91]
	v_pk_add_f32 v[82:83], v[82:83], v[84:85]
	s_nop 0
	v_pk_add_f32 v[82:83], v[82:83], v[86:87]
	s_nop 0
	v_add_f32_e32 v82, v82, v83
	v_fmamk_f32 v82, v82, 0x3a800000, v155
	v_mul_f32_e32 v83, 0x4f800000, v82
	v_cmp_gt_f32_e32 vcc, s55, v82
	s_nop 1
	v_cndmask_b32_e32 v82, v82, v83, vcc
	v_sqrt_f32_e32 v83, v82
	s_nop 0
	v_add_u32_e32 v84, -1, v83
	v_add_u32_e32 v85, 1, v83
	v_fma_f32 v86, -v84, v83, v82
	v_fma_f32 v87, -v85, v83, v82
	v_cmp_ge_f32_e64 s[0:1], 0, v86
	s_nop 1
	v_cndmask_b32_e64 v83, v83, v84, s[0:1]
	v_cmp_lt_f32_e64 s[0:1], 0, v87
	s_nop 1
	v_cndmask_b32_e64 v83, v83, v85, s[0:1]
	v_mul_f32_e32 v84, 0x37800000, v83
	v_cndmask_b32_e32 v83, v83, v84, vcc
	v_cmp_class_f32_e32 vcc, v82, v156
	s_nop 1
	v_cndmask_b32_e32 v82, v83, v82, vcc
	v_div_scale_f32 v83, s[0:1], v82, v82, 1.0
	v_rcp_f32_e32 v84, v83
	v_div_scale_f32 v85, vcc, 1.0, v82, 1.0
	s_mov_b64 s[0:1], 0
	v_fma_f32 v86, -v83, v84, 1.0
	v_fmac_f32_e32 v84, v86, v84
	v_mul_f32_e32 v86, v85, v84
	v_fma_f32 v87, -v83, v86, v85
	v_fmac_f32_e32 v86, v87, v84
	v_fma_f32 v83, -v83, v86, v85
	v_div_fmas_f32 v83, v83, v84, v86
	v_div_fixup_f32 v82, v83, v82, 1.0

; __device__ __forceinline__ unsigned cvt_pk_bf16(float lo, float hi) { unsigned r; asm volatile("v_cvt_pk_bf16_f32 %0, %1, %2" : "=v"(r) : "v"(lo), "v"(hi)); return r; }
; __device__ __forceinline__ float row_rstd(const float* part, int row, float eps) {
;     const f32x4* p = (const f32x4*)(part + (size_t)row * 16);
;     const f32x4 a = p[0], b = p[1], c = p[2], d = p[3];
;     const float s = ((a[0] + a[1]) + (a[2] + a[3])) + ((b[0] + b[1]) + (b[2] + b[3])) + ((c[0] + c[1]) + (c[2] + c[3])) + ((d[0] + d[1]) + (d[2] + d[3]));
;     return 1.0f / sqrtf(s * (1.0f / 1024.0f) + eps);
; }
;     __device__ __forceinline__ void operator()(const f32x4 (&acc)[2][2][4][2], const Unit& u, int wr, int wc, int fr, int fq) const {
;     ...
;                 const int row = row0 + ai * HALF + m * 16; bf16_t* rowp = O + (size_t)row * ldc + col0;
;                 const float r = (slot >= 0 ? tab[slot * 256 + (row - u.pm * BM)] : row_rstd(sspart, row, eps)) * sc;
; #pragma unroll
;                 for (int bj = 0; bj < 2; ++bj) {
;                     f32x4 v0 = acc[ai][bj][m][0] * r, v1 = acc[ai][bj][m][1] * r;
;                     if (ACT == 1) {
; #pragma unroll
;                         for (int e = 0; e < 4; ++e) { const float a = fmaxf(v0[e], 0.f), b = fmaxf(v1[e], 0.f); v0[e] = a * a; v1[e] = b * b; }
;                     }
;                     u32x4 w; w.x = cvt_pk_bf16(v0[0], v0[1]); w.y = cvt_pk_bf16(v0[2], v0[3]); w.z = cvt_pk_bf16(v1[0], v1[1]); w.w = cvt_pk_bf16(v1[2], v1[3]);
;                     *(u32x4*)(rowp + bj * HALF) = w;
.LBB0_1069:
	v_lshlrev_b64 v[80:81], 11, v[80:81]
	v_lshl_add_u64 v[80:81], s[14:15], 0, v[80:81]
	s_waitcnt lgkmcnt(0)
	v_mul_f32_e32 v82, 0x3db8aa3b, v82
	v_lshl_add_u64 v[80:81], v[146:147], 1, v[80:81]
	v_pk_mul_f32 v[78:79], v[78:79], v[82:83] op_sel_hi:[1,0]
	v_pk_mul_f32 v[76:77], v[76:77], v[82:83] op_sel_hi:[1,0]
	v_pk_mul_f32 v[84:85], v[74:75], v[82:83] op_sel_hi:[1,0]
	v_pk_mul_f32 v[74:75], v[72:73], v[82:83] op_sel_hi:[1,0]
	v_cvt_pk_bf16_f32 v72, v76, v77
	v_cvt_pk_bf16_f32 v73, v78, v79
	v_pk_mul_f32 v[68:69], v[68:69], v[82:83] op_sel_hi:[1,0]
	v_cvt_pk_bf16_f32 v74, v74, v75
	v_cvt_pk_bf16_f32 v75, v84, v85
	ds_bpermute_b32 v240, v253, v72
	ds_bpermute_b32 v241, v253, v73
	ds_bpermute_b32 v242, v253, v74
	ds_bpermute_b32 v243, v253, v75
	v_lshl_add_u64 v[236:237], v[80:81], 0, v[250:251]
	s_waitcnt lgkmcnt(4)
	global_store_dwordx4 v[238:239], v[244:247], off offset:256
	v_pk_mul_f32 v[70:71], v[70:71], v[82:83] op_sel_hi:[1,0]
	s_and_b64 vcc, exec, s[6:7]
	v_pk_mul_f32 v[72:73], v[66:67], v[82:83] op_sel_hi:[1,0]
	v_pk_mul_f32 v[66:67], v[64:65], v[82:83] op_sel_hi:[1,0]
	v_cvt_pk_bf16_f32 v64, v68, v69
	v_cvt_pk_bf16_f32 v65, v70, v71
	s_mov_b64 s[0:1], -1
	v_cvt_pk_bf16_f32 v66, v66, v67
	v_cvt_pk_bf16_f32 v67, v72, v73
	ds_bpermute_b32 v244, v253, v64
	ds_bpermute_b32 v245, v253, v65
	ds_bpermute_b32 v246, v253, v66
	ds_bpermute_b32 v247, v253, v67
	v_lshl_add_u64 v[238:239], v[80:81], 0, v[250:251]
	s_waitcnt lgkmcnt(4)
	global_store_dwordx4 v[236:237], v[240:243], off
	s_nop 1
	v_add_u32_e32 v64, 0x80, v144
	v_ashrrev_i32_e32 v65, 31, v64
	s_cbranch_vccnz .LBB0_1071
	v_lshlrev_b64 v[66:67], 6, v[64:65]
	v_lshl_add_u64 v[78:79], s[10:11], 0, v[66:67]
	global_load_dwordx4 v[66:69], v[78:79], off
	global_load_dwordx4 v[70:73], v[78:79], off offset:16
	global_load_dwordx4 v[74:77], v[78:79], off offset:32
	s_nop 0
	global_load_dwordx4 v[78:81], v[78:79], off offset:48
	s_waitcnt vmcnt(0)
	v_mov_b32_e32 v82, v67
	v_mov_b32_e32 v83, v68
	v_mov_b32_e32 v67, v69
	v_mov_b32_e32 v68, v71
	v_mov_b32_e32 v69, v72
	v_mov_b32_e32 v71, v73
	v_pk_add_f32 v[66:67], v[82:83], v[66:67]
	v_pk_add_f32 v[68:69], v[68:69], v[70:71]
	v_pk_add_f32 v[66:67], v[66:67], v[66:67] op_sel:[0,1] op_sel_hi:[1,0]
	v_pk_add_f32 v[68:69], v[68:69], v[68:69] op_sel:[0,1] op_sel_hi:[1,0]
	v_add_f32_e32 v72, v74, v75
	v_add_f32_e32 v74, v76, v77
	v_mov_b32_e32 v73, v80
	v_mov_b32_e32 v75, v81
	v_mov_b32_e32 v67, v78
	v_mov_b32_e32 v69, v79
	v_pk_add_f32 v[70:71], v[72:73], v[74:75]
	v_pk_add_f32 v[66:67], v[66:67], v[68:69]
	s_nop 0
	v_pk_add_f32 v[66:67], v[66:67], v[70:71]
	s_nop 0
	v_add_f32_e32 v66, v66, v67
	v_fmamk_f32 v66, v66, 0x3a800000, v155
	v_mul_f32_e32 v67, 0x4f800000, v66
	v_cmp_gt_f32_e32 vcc, s55, v66
	s_nop 1
	v_cndmask_b32_e32 v66, v66, v67, vcc
	v_sqrt_f32_e32 v67, v66
	s_nop 0
	v_add_u32_e32 v68, -1, v67
	v_add_u32_e32 v69, 1, v67
	v_fma_f32 v70, -v68, v67, v66
	v_fma_f32 v71, -v69, v67, v66
	v_cmp_ge_f32_e64 s[0:1], 0, v70
	s_nop 1
	v_cndmask_b32_e64 v67, v67, v68, s[0:1]
	v_cmp_lt_f32_e64 s[0:1], 0, v71
	s_nop 1
	v_cndmask_b32_e64 v67, v67, v69, s[0:1]
	v_mul_f32_e32 v68, 0x37800000, v67
	v_cndmask_b32_e32 v67, v67, v68, vcc
	v_cmp_class_f32_e32 vcc, v66, v156
	s_nop 1
	v_cndmask_b32_e32 v66, v67, v66, vcc
	v_div_scale_f32 v67, s[0:1], v66, v66, 1.0
	v_rcp_f32_e32 v68, v67
	v_div_scale_f32 v69, vcc, 1.0, v66, 1.0
	s_mov_b64 s[0:1], 0
	v_fma_f32 v70, -v67, v68, 1.0
	v_fmac_f32_e32 v68, v70, v68
	v_mul_f32_e32 v70, v69, v68
	v_fma_f32 v71, -v67, v70, v69
	v_fmac_f32_e32 v70, v71, v68
	v_fma_f32 v67, -v67, v70, v69
	v_div_fmas_f32 v67, v67, v68, v70
	v_div_fixup_f32 v66, v67, v66, 1.0

; __device__ __forceinline__ unsigned cvt_pk_bf16(float lo, float hi) { unsigned r; asm volatile("v_cvt_pk_bf16_f32 %0, %1, %2" : "=v"(r) : "v"(lo), "v"(hi)); return r; }
; __device__ __forceinline__ float row_rstd(const float* part, int row, float eps) {
;     const f32x4* p = (const f32x4*)(part + (size_t)row * 16);
;     const f32x4 a = p[0], b = p[1], c = p[2], d = p[3];
;     const float s = ((a[0] + a[1]) + (a[2] + a[3])) + ((b[0] + b[1]) + (b[2] + b[3])) + ((c[0] + c[1]) + (c[2] + c[3])) + ((d[0] + d[1]) + (d[2] + d[3]));
;     return 1.0f / sqrtf(s * (1.0f / 1024.0f) + eps);
; }
;     __device__ __forceinline__ void operator()(const f32x4 (&acc)[2][2][4][2], const Unit& u, int wr, int wc, int fr, int fq) const {
;     ...
;                 const int row = row0 + ai * HALF + m * 16; bf16_t* rowp = O + (size_t)row * ldc + col0;
;                 const float r = (slot >= 0 ? tab[slot * 256 + (row - u.pm * BM)] : row_rstd(sspart, row, eps)) * sc;
; #pragma unroll
;                 for (int bj = 0; bj < 2; ++bj) {
;                     f32x4 v0 = acc[ai][bj][m][0] * r, v1 = acc[ai][bj][m][1] * r;
;                     if (ACT == 1) {
; #pragma unroll
;                         for (int e = 0; e < 4; ++e) { const float a = fmaxf(v0[e], 0.f), b = fmaxf(v1[e], 0.f); v0[e] = a * a; v1[e] = b * b; }
;                     }
;                     u32x4 w; w.x = cvt_pk_bf16(v0[0], v0[1]); w.y = cvt_pk_bf16(v0[2], v0[3]); w.z = cvt_pk_bf16(v1[0], v1[1]); w.w = cvt_pk_bf16(v1[2], v1[3]);
;                     *(u32x4*)(rowp + bj * HALF) = w;
.LBB0_1073:
	v_lshlrev_b64 v[64:65], 11, v[64:65]
	v_lshl_add_u64 v[64:65], s[14:15], 0, v[64:65]
	s_waitcnt lgkmcnt(0)
	v_mul_f32_e32 v66, 0x3db8aa3b, v66
	v_lshl_add_u64 v[64:65], v[146:147], 1, v[64:65]
	v_pk_mul_f32 v[62:63], v[62:63], v[66:67] op_sel_hi:[1,0]
	v_pk_mul_f32 v[60:61], v[60:61], v[66:67] op_sel_hi:[1,0]
	v_pk_mul_f32 v[68:69], v[58:59], v[66:67] op_sel_hi:[1,0]
	v_pk_mul_f32 v[58:59], v[56:57], v[66:67] op_sel_hi:[1,0]
	v_cvt_pk_bf16_f32 v56, v60, v61
	v_cvt_pk_bf16_f32 v57, v62, v63
	v_pk_mul_f32 v[52:53], v[52:53], v[66:67] op_sel_hi:[1,0]
	v_cvt_pk_bf16_f32 v58, v58, v59
	v_cvt_pk_bf16_f32 v59, v68, v69
	ds_bpermute_b32 v240, v253, v56
	ds_bpermute_b32 v241, v253, v57
	ds_bpermute_b32 v242, v253, v58
	ds_bpermute_b32 v243, v253, v59
	v_lshl_add_u64 v[236:237], v[64:65], 0, v[250:251]
	s_waitcnt lgkmcnt(4)
	global_store_dwordx4 v[238:239], v[244:247], off offset:256
	v_pk_mul_f32 v[54:55], v[54:55], v[66:67] op_sel_hi:[1,0]
	s_and_b64 vcc, exec, s[6:7]
	v_pk_mul_f32 v[56:57], v[50:51], v[66:67] op_sel_hi:[1,0]
	v_pk_mul_f32 v[50:51], v[48:49], v[66:67] op_sel_hi:[1,0]
	v_cvt_pk_bf16_f32 v48, v52, v53
	v_cvt_pk_bf16_f32 v49, v54, v55
	s_mov_b64 s[0:1], -1
	v_cvt_pk_bf16_f32 v50, v50, v51
	v_cvt_pk_bf16_f32 v51, v56, v57
	ds_bpermute_b32 v244, v253, v48
	ds_bpermute_b32 v245, v253, v49
	ds_bpermute_b32 v246, v253, v50
	ds_bpermute_b32 v247, v253, v51
	v_lshl_add_u64 v[238:239], v[64:65], 0, v[250:251]
	s_waitcnt lgkmcnt(4)
	global_store_dwordx4 v[236:237], v[240:243], off
	s_nop 1
	v_add_u32_e32 v48, 0x90, v144
	v_ashrrev_i32_e32 v49, 31, v48
	s_cbranch_vccnz .LBB0_1075
	v_lshlrev_b64 v[50:51], 6, v[48:49]
	v_lshl_add_u64 v[62:63], s[10:11], 0, v[50:51]
	global_load_dwordx4 v[50:53], v[62:63], off
	global_load_dwordx4 v[54:57], v[62:63], off offset:16
	global_load_dwordx4 v[58:61], v[62:63], off offset:32
	s_nop 0
	global_load_dwordx4 v[62:65], v[62:63], off offset:48
	s_waitcnt vmcnt(0)
	v_mov_b32_e32 v66, v51
	v_mov_b32_e32 v67, v52
	v_mov_b32_e32 v51, v53
	v_mov_b32_e32 v52, v55
	v_mov_b32_e32 v53, v56
	v_mov_b32_e32 v55, v57
	v_pk_add_f32 v[50:51], v[66:67], v[50:51]
	v_pk_add_f32 v[52:53], v[52:53], v[54:55]
	v_pk_add_f32 v[50:51], v[50:51], v[50:51] op_sel:[0,1] op_sel_hi:[1,0]
	v_pk_add_f32 v[52:53], v[52:53], v[52:53] op_sel:[0,1] op_sel_hi:[1,0]
	v_add_f32_e32 v56, v58, v59
	v_add_f32_e32 v58, v60, v61
	v_mov_b32_e32 v57, v64
	v_mov_b32_e32 v59, v65
	v_mov_b32_e32 v51, v62
	v_mov_b32_e32 v53, v63
	v_pk_add_f32 v[54:55], v[56:57], v[58:59]
	v_pk_add_f32 v[50:51], v[50:51], v[52:53]
	s_nop 0
	v_pk_add_f32 v[50:51], v[50:51], v[54:55]
	s_nop 0
	v_add_f32_e32 v50, v50, v51
	v_fmamk_f32 v50, v50, 0x3a800000, v155
	v_mul_f32_e32 v51, 0x4f800000, v50
	v_cmp_gt_f32_e32 vcc, s55, v50
	s_nop 1
	v_cndmask_b32_e32 v50, v50, v51, vcc
	v_sqrt_f32_e32 v51, v50
	s_nop 0
	v_add_u32_e32 v52, -1, v51
	v_add_u32_e32 v53, 1, v51
	v_fma_f32 v54, -v52, v51, v50
	v_fma_f32 v55, -v53, v51, v50
	v_cmp_ge_f32_e64 s[0:1], 0, v54
	s_nop 1
	v_cndmask_b32_e64 v51, v51, v52, s[0:1]
	v_cmp_lt_f32_e64 s[0:1], 0, v55
	s_nop 1
	v_cndmask_b32_e64 v51, v51, v53, s[0:1]
	v_mul_f32_e32 v52, 0x37800000, v51
	v_cndmask_b32_e32 v51, v51, v52, vcc
	v_cmp_class_f32_e32 vcc, v50, v156
	s_nop 1
	v_cndmask_b32_e32 v50, v51, v50, vcc
	v_div_scale_f32 v51, s[0:1], v50, v50, 1.0
	v_rcp_f32_e32 v52, v51
	v_div_scale_f32 v53, vcc, 1.0, v50, 1.0
	s_mov_b64 s[0:1], 0
	v_fma_f32 v54, -v51, v52, 1.0
	v_fmac_f32_e32 v52, v54, v52
	v_mul_f32_e32 v54, v53, v52
	v_fma_f32 v55, -v51, v54, v53
	v_fmac_f32_e32 v54, v55, v52
	v_fma_f32 v51, -v51, v54, v53
	v_div_fmas_f32 v51, v51, v52, v54
	v_div_fixup_f32 v50, v51, v50, 1.0

; __device__ __forceinline__ unsigned cvt_pk_bf16(float lo, float hi) { unsigned r; asm volatile("v_cvt_pk_bf16_f32 %0, %1, %2" : "=v"(r) : "v"(lo), "v"(hi)); return r; }
; __device__ __forceinline__ float row_rstd(const float* part, int row, float eps) {
;     const f32x4* p = (const f32x4*)(part + (size_t)row * 16);
;     const f32x4 a = p[0], b = p[1], c = p[2], d = p[3];
;     const float s = ((a[0] + a[1]) + (a[2] + a[3])) + ((b[0] + b[1]) + (b[2] + b[3])) + ((c[0] + c[1]) + (c[2] + c[3])) + ((d[0] + d[1]) + (d[2] + d[3]));
;     return 1.0f / sqrtf(s * (1.0f / 1024.0f) + eps);
; }
;     __device__ __forceinline__ void operator()(const f32x4 (&acc)[2][2][4][2], const Unit& u, int wr, int wc, int fr, int fq) const {
;     ...
;                 const int row = row0 + ai * HALF + m * 16; bf16_t* rowp = O + (size_t)row * ldc + col0;
;                 const float r = (slot >= 0 ? tab[slot * 256 + (row - u.pm * BM)] : row_rstd(sspart, row, eps)) * sc;
; #pragma unroll
;                 for (int bj = 0; bj < 2; ++bj) {
;                     f32x4 v0 = acc[ai][bj][m][0] * r, v1 = acc[ai][bj][m][1] * r;
;                     if (ACT == 1) {
; #pragma unroll
;                         for (int e = 0; e < 4; ++e) { const float a = fmaxf(v0[e], 0.f), b = fmaxf(v1[e], 0.f); v0[e] = a * a; v1[e] = b * b; }
;                     }
;                     u32x4 w; w.x = cvt_pk_bf16(v0[0], v0[1]); w.y = cvt_pk_bf16(v0[2], v0[3]); w.z = cvt_pk_bf16(v1[0], v1[1]); w.w = cvt_pk_bf16(v1[2], v1[3]);
;                     *(u32x4*)(rowp + bj * HALF) = w;
.LBB0_1077:
	v_lshlrev_b64 v[48:49], 11, v[48:49]
	v_lshl_add_u64 v[48:49], s[14:15], 0, v[48:49]
	s_waitcnt lgkmcnt(0)
	v_mul_f32_e32 v50, 0x3db8aa3b, v50
	v_lshl_add_u64 v[48:49], v[146:147], 1, v[48:49]
	v_pk_mul_f32 v[46:47], v[46:47], v[50:51] op_sel_hi:[1,0]
	v_pk_mul_f32 v[44:45], v[44:45], v[50:51] op_sel_hi:[1,0]
	v_pk_mul_f32 v[52:53], v[42:43], v[50:51] op_sel_hi:[1,0]
	v_pk_mul_f32 v[42:43], v[40:41], v[50:51] op_sel_hi:[1,0]
	v_cvt_pk_bf16_f32 v40, v44, v45
	v_cvt_pk_bf16_f32 v41, v46, v47
	v_pk_mul_f32 v[36:37], v[36:37], v[50:51] op_sel_hi:[1,0]
	v_cvt_pk_bf16_f32 v42, v42, v43
	v_cvt_pk_bf16_f32 v43, v52, v53
	ds_bpermute_b32 v240, v253, v40
	ds_bpermute_b32 v241, v253, v41
	ds_bpermute_b32 v242, v253, v42
	ds_bpermute_b32 v243, v253, v43
	v_lshl_add_u64 v[236:237], v[48:49], 0, v[250:251]
	s_waitcnt lgkmcnt(4)
	global_store_dwordx4 v[238:239], v[244:247], off offset:256
	v_pk_mul_f32 v[38:39], v[38:39], v[50:51] op_sel_hi:[1,0]
	s_and_b64 vcc, exec, s[6:7]
	v_pk_mul_f32 v[40:41], v[34:35], v[50:51] op_sel_hi:[1,0]
	v_pk_mul_f32 v[34:35], v[32:33], v[50:51] op_sel_hi:[1,0]
	v_cvt_pk_bf16_f32 v32, v36, v37
	v_cvt_pk_bf16_f32 v33, v38, v39
	s_mov_b64 s[0:1], -1
	v_cvt_pk_bf16_f32 v34, v34, v35
	v_cvt_pk_bf16_f32 v35, v40, v41
	ds_bpermute_b32 v244, v253, v32
	ds_bpermute_b32 v245, v253, v33
	ds_bpermute_b32 v246, v253, v34
	ds_bpermute_b32 v247, v253, v35
	v_lshl_add_u64 v[238:239], v[48:49], 0, v[250:251]
	s_waitcnt lgkmcnt(4)
	global_store_dwordx4 v[236:237], v[240:243], off
	s_nop 1
	v_add_u32_e32 v32, 0xa0, v144
	v_ashrrev_i32_e32 v33, 31, v32
	s_cbranch_vccnz .LBB0_1079
	v_lshlrev_b64 v[34:35], 6, v[32:33]
	v_lshl_add_u64 v[46:47], s[10:11], 0, v[34:35]
	global_load_dwordx4 v[34:37], v[46:47], off
	global_load_dwordx4 v[38:41], v[46:47], off offset:16
	global_load_dwordx4 v[42:45], v[46:47], off offset:32
	s_nop 0
	global_load_dwordx4 v[46:49], v[46:47], off offset:48
	s_waitcnt vmcnt(0)
	v_mov_b32_e32 v50, v35
	v_mov_b32_e32 v51, v36
	v_mov_b32_e32 v35, v37
	v_mov_b32_e32 v36, v39
	v_mov_b32_e32 v37, v40
	v_mov_b32_e32 v39, v41
	v_pk_add_f32 v[34:35], v[50:51], v[34:35]
	v_pk_add_f32 v[36:37], v[36:37], v[38:39]
	v_pk_add_f32 v[34:35], v[34:35], v[34:35] op_sel:[0,1] op_sel_hi:[1,0]
	v_pk_add_f32 v[36:37], v[36:37], v[36:37] op_sel:[0,1] op_sel_hi:[1,0]
	v_add_f32_e32 v40, v42, v43
	v_add_f32_e32 v42, v44, v45
	v_mov_b32_e32 v41, v48
	v_mov_b32_e32 v43, v49
	v_mov_b32_e32 v35, v46
	v_mov_b32_e32 v37, v47
	v_pk_add_f32 v[38:39], v[40:41], v[42:43]
	v_pk_add_f32 v[34:35], v[34:35], v[36:37]
	s_nop 0
	v_pk_add_f32 v[34:35], v[34:35], v[38:39]
	s_nop 0
	v_add_f32_e32 v34, v34, v35
	v_fmamk_f32 v34, v34, 0x3a800000, v155
	v_mul_f32_e32 v35, 0x4f800000, v34
	v_cmp_gt_f32_e32 vcc, s55, v34
	s_nop 1
	v_cndmask_b32_e32 v34, v34, v35, vcc
	v_sqrt_f32_e32 v35, v34
	s_nop 0
	v_add_u32_e32 v36, -1, v35
	v_add_u32_e32 v37, 1, v35
	v_fma_f32 v38, -v36, v35, v34
	v_fma_f32 v39, -v37, v35, v34
	v_cmp_ge_f32_e64 s[0:1], 0, v38
	s_nop 1
	v_cndmask_b32_e64 v35, v35, v36, s[0:1]
	v_cmp_lt_f32_e64 s[0:1], 0, v39
	s_nop 1
	v_cndmask_b32_e64 v35, v35, v37, s[0:1]
	v_mul_f32_e32 v36, 0x37800000, v35
	v_cndmask_b32_e32 v35, v35, v36, vcc
	v_cmp_class_f32_e32 vcc, v34, v156
	s_nop 1
	v_cndmask_b32_e32 v34, v35, v34, vcc
	v_div_scale_f32 v35, s[0:1], v34, v34, 1.0
	v_rcp_f32_e32 v36, v35
	v_div_scale_f32 v37, vcc, 1.0, v34, 1.0
	s_mov_b64 s[0:1], 0
	v_fma_f32 v38, -v35, v36, 1.0
	v_fmac_f32_e32 v36, v38, v36
	v_mul_f32_e32 v38, v37, v36
	v_fma_f32 v39, -v35, v38, v37
	v_fmac_f32_e32 v38, v39, v36
	v_fma_f32 v35, -v35, v38, v37
	v_div_fmas_f32 v35, v35, v36, v38
	v_div_fixup_f32 v34, v35, v34, 1.0

; __device__ __forceinline__ unsigned cvt_pk_bf16(float lo, float hi) { unsigned r; asm volatile("v_cvt_pk_bf16_f32 %0, %1, %2" : "=v"(r) : "v"(lo), "v"(hi)); return r; }
; __device__ __forceinline__ float row_rstd(const float* part, int row, float eps) {
;     const f32x4* p = (const f32x4*)(part + (size_t)row * 16);
;     const f32x4 a = p[0], b = p[1], c = p[2], d = p[3];
;     const float s = ((a[0] + a[1]) + (a[2] + a[3])) + ((b[0] + b[1]) + (b[2] + b[3])) + ((c[0] + c[1]) + (c[2] + c[3])) + ((d[0] + d[1]) + (d[2] + d[3]));
;     return 1.0f / sqrtf(s * (1.0f / 1024.0f) + eps);
; }
;     __device__ __forceinline__ void operator()(const f32x4 (&acc)[2][2][4][2], const Unit& u, int wr, int wc, int fr, int fq) const {
;     ...
;                 const int row = row0 + ai * HALF + m * 16; bf16_t* rowp = O + (size_t)row * ldc + col0;
;                 const float r = (slot >= 0 ? tab[slot * 256 + (row - u.pm * BM)] : row_rstd(sspart, row, eps)) * sc;
; #pragma unroll
;                 for (int bj = 0; bj < 2; ++bj) {
;                     f32x4 v0 = acc[ai][bj][m][0] * r, v1 = acc[ai][bj][m][1] * r;
;                     if (ACT == 1) {
; #pragma unroll
;                         for (int e = 0; e < 4; ++e) { const float a = fmaxf(v0[e], 0.f), b = fmaxf(v1[e], 0.f); v0[e] = a * a; v1[e] = b * b; }
;                     }
;                     u32x4 w; w.x = cvt_pk_bf16(v0[0], v0[1]); w.y = cvt_pk_bf16(v0[2], v0[3]); w.z = cvt_pk_bf16(v1[0], v1[1]); w.w = cvt_pk_bf16(v1[2], v1[3]);
;                     *(u32x4*)(rowp + bj * HALF) = w;
.LBB0_1081:
	v_lshlrev_b64 v[32:33], 11, v[32:33]
	v_lshl_add_u64 v[32:33], s[14:15], 0, v[32:33]
	s_waitcnt lgkmcnt(0)
	v_mul_f32_e32 v34, 0x3db8aa3b, v34
	v_lshl_add_u64 v[32:33], v[146:147], 1, v[32:33]
	v_pk_mul_f32 v[30:31], v[30:31], v[34:35] op_sel_hi:[1,0]
	v_pk_mul_f32 v[28:29], v[28:29], v[34:35] op_sel_hi:[1,0]
	v_pk_mul_f32 v[36:37], v[26:27], v[34:35] op_sel_hi:[1,0]
	v_pk_mul_f32 v[26:27], v[24:25], v[34:35] op_sel_hi:[1,0]
	v_cvt_pk_bf16_f32 v24, v28, v29
	v_cvt_pk_bf16_f32 v25, v30, v31
	v_pk_mul_f32 v[20:21], v[20:21], v[34:35] op_sel_hi:[1,0]
	v_cvt_pk_bf16_f32 v26, v26, v27
	v_cvt_pk_bf16_f32 v27, v36, v37
	ds_bpermute_b32 v240, v253, v24
	ds_bpermute_b32 v241, v253, v25
	ds_bpermute_b32 v242, v253, v26
	ds_bpermute_b32 v243, v253, v27
	v_lshl_add_u64 v[236:237], v[32:33], 0, v[250:251]
	s_waitcnt lgkmcnt(4)
	global_store_dwordx4 v[238:239], v[244:247], off offset:256
	v_pk_mul_f32 v[22:23], v[22:23], v[34:35] op_sel_hi:[1,0]
	s_and_b64 vcc, exec, s[6:7]
	v_pk_mul_f32 v[24:25], v[18:19], v[34:35] op_sel_hi:[1,0]
	v_pk_mul_f32 v[18:19], v[16:17], v[34:35] op_sel_hi:[1,0]
	v_cvt_pk_bf16_f32 v16, v20, v21
	v_cvt_pk_bf16_f32 v17, v22, v23
	s_mov_b64 s[0:1], -1
	v_cvt_pk_bf16_f32 v18, v18, v19
	v_cvt_pk_bf16_f32 v19, v24, v25
	ds_bpermute_b32 v244, v253, v16
	ds_bpermute_b32 v245, v253, v17
	ds_bpermute_b32 v246, v253, v18
	ds_bpermute_b32 v247, v253, v19
	v_lshl_add_u64 v[238:239], v[32:33], 0, v[250:251]
	s_waitcnt lgkmcnt(4)
	global_store_dwordx4 v[236:237], v[240:243], off
	s_nop 1
	v_add_u32_e32 v16, 0xb0, v144
	v_ashrrev_i32_e32 v17, 31, v16
	s_cbranch_vccnz .LBB0_1083
	v_lshlrev_b64 v[18:19], 6, v[16:17]
	v_lshl_add_u64 v[30:31], s[10:11], 0, v[18:19]
	global_load_dwordx4 v[18:21], v[30:31], off
	global_load_dwordx4 v[22:25], v[30:31], off offset:16
	global_load_dwordx4 v[26:29], v[30:31], off offset:32
	s_nop 0
	global_load_dwordx4 v[30:33], v[30:31], off offset:48
	s_waitcnt vmcnt(0)
	v_mov_b32_e32 v34, v19
	v_mov_b32_e32 v35, v20
	v_mov_b32_e32 v19, v21
	v_mov_b32_e32 v20, v23
	v_mov_b32_e32 v21, v24
	v_mov_b32_e32 v23, v25
	v_pk_add_f32 v[18:19], v[34:35], v[18:19]
	v_pk_add_f32 v[20:21], v[20:21], v[22:23]
	v_pk_add_f32 v[18:19], v[18:19], v[18:19] op_sel:[0,1] op_sel_hi:[1,0]
	v_pk_add_f32 v[20:21], v[20:21], v[20:21] op_sel:[0,1] op_sel_hi:[1,0]
	v_add_f32_e32 v24, v26, v27
	v_add_f32_e32 v26, v28, v29
	v_mov_b32_e32 v25, v32
	v_mov_b32_e32 v27, v33
	v_mov_b32_e32 v19, v30
	v_mov_b32_e32 v21, v31
	v_pk_add_f32 v[22:23], v[24:25], v[26:27]
	v_pk_add_f32 v[18:19], v[18:19], v[20:21]
	s_nop 0
	v_pk_add_f32 v[18:19], v[18:19], v[22:23]
	s_nop 0
	v_add_f32_e32 v18, v18, v19
	v_fmamk_f32 v18, v18, 0x3a800000, v155
	v_mul_f32_e32 v19, 0x4f800000, v18
	v_cmp_gt_f32_e32 vcc, s55, v18
	s_nop 1
	v_cndmask_b32_e32 v18, v18, v19, vcc
	v_sqrt_f32_e32 v19, v18
	s_nop 0
	v_add_u32_e32 v20, -1, v19
	v_add_u32_e32 v21, 1, v19
	v_fma_f32 v22, -v20, v19, v18
	v_fma_f32 v23, -v21, v19, v18
	v_cmp_ge_f32_e64 s[0:1], 0, v22
	s_nop 1
	v_cndmask_b32_e64 v19, v19, v20, s[0:1]
	v_cmp_lt_f32_e64 s[0:1], 0, v23
	s_nop 1
	v_cndmask_b32_e64 v19, v19, v21, s[0:1]
	v_mul_f32_e32 v20, 0x37800000, v19
	v_cndmask_b32_e32 v19, v19, v20, vcc
	v_cmp_class_f32_e32 vcc, v18, v156
	s_nop 1
	v_cndmask_b32_e32 v18, v19, v18, vcc
	v_div_scale_f32 v19, s[0:1], v18, v18, 1.0
	v_rcp_f32_e32 v20, v19
	v_div_scale_f32 v21, vcc, 1.0, v18, 1.0
	s_mov_b64 s[0:1], 0
	v_fma_f32 v22, -v19, v20, 1.0
	v_fmac_f32_e32 v20, v22, v20
	v_mul_f32_e32 v22, v21, v20
	v_fma_f32 v23, -v19, v22, v21
	v_fmac_f32_e32 v22, v23, v20
	v_fma_f32 v19, -v19, v22, v21
	v_div_fmas_f32 v19, v19, v20, v22
	v_div_fixup_f32 v18, v19, v18, 1.0

; __device__ __forceinline__ unsigned cvt_pk_bf16(float lo, float hi) { unsigned r; asm volatile("v_cvt_pk_bf16_f32 %0, %1, %2" : "=v"(r) : "v"(lo), "v"(hi)); return r; }
; #define PG8_BAR __builtin_amdgcn_s_barrier()
;     __device__ __forceinline__ void operator()(const f32x4 (&acc)[2][2][4][2], const Unit& u, int wr, int wc, int fr, int fq) const {
;     ...
;                 const int row = row0 + ai * HALF + m * 16; bf16_t* rowp = O + (size_t)row * ldc + col0;
;                 const float r = (slot >= 0 ? tab[slot * 256 + (row - u.pm * BM)] : row_rstd(sspart, row, eps)) * sc;
; #pragma unroll
;                 for (int bj = 0; bj < 2; ++bj) {
;                     f32x4 v0 = acc[ai][bj][m][0] * r, v1 = acc[ai][bj][m][1] * r;
;                     if (ACT == 1) {
; #pragma unroll
;                         for (int e = 0; e < 4; ++e) { const float a = fmaxf(v0[e], 0.f), b = fmaxf(v1[e], 0.f); v0[e] = a * a; v1[e] = b * b; }
;                     }
;                     u32x4 w; w.x = cvt_pk_bf16(v0[0], v0[1]); w.y = cvt_pk_bf16(v0[2], v0[3]); w.z = cvt_pk_bf16(v1[0], v1[1]); w.w = cvt_pk_bf16(v1[2], v1[3]);
;                     *(u32x4*)(rowp + bj * HALF) = w;
; template <class Epi, class Sched, bool ALIGN_EPI = false, bool SP2 = false>
; __device__ __forceinline__ void gemm_phase(PG8_LAS unsigned char* lds, const Gemm g, const Sched& S, const Epi& E, const int wv  ) {
;     ...
;         if (!has_next) break;
; #pragma unroll
;         for (int a = 0; a < 2; ++a)
; #pragma unroll
;             for (int b = 0; b < 2; ++b)
; #pragma unroll
;                 for (int m = 0; m < 4; ++m)
; #pragma unroll
;                     for (int n = 0; n < 2; ++n) acc[a][b][m][n] = (f32x4){0.f, 0.f, 0.f, 0.f};
;         cur = nxt; cA = nA; cB = nB; ++ui;
;         if constexpr (ALIGN_EPI) { if (wr == 1) PG8_BAR; }
.LBB0_1085:
	v_lshlrev_b64 v[16:17], 11, v[16:17]
	v_lshl_add_u64 v[16:17], s[14:15], 0, v[16:17]
	s_waitcnt lgkmcnt(0)
	v_mul_f32_e32 v18, 0x3db8aa3b, v18
	v_lshl_add_u64 v[16:17], v[146:147], 1, v[16:17]
	v_pk_mul_f32 v[14:15], v[14:15], v[18:19] op_sel_hi:[1,0]
	v_pk_mul_f32 v[12:13], v[12:13], v[18:19] op_sel_hi:[1,0]
	v_pk_mul_f32 v[20:21], v[10:11], v[18:19] op_sel_hi:[1,0]
	v_pk_mul_f32 v[10:11], v[8:9], v[18:19] op_sel_hi:[1,0]
	v_cvt_pk_bf16_f32 v8, v12, v13
	v_cvt_pk_bf16_f32 v9, v14, v15
	s_andn2_b64 vcc, exec, s[4:5]
	v_cvt_pk_bf16_f32 v10, v10, v11
	v_cvt_pk_bf16_f32 v11, v20, v21
	ds_bpermute_b32 v240, v253, v8
	ds_bpermute_b32 v241, v253, v9
	ds_bpermute_b32 v242, v253, v10
	ds_bpermute_b32 v243, v253, v11
	v_lshl_add_u64 v[236:237], v[16:17], 0, v[250:251]
	s_waitcnt lgkmcnt(4)
	global_store_dwordx4 v[238:239], v[244:247], off offset:256
	s_mov_b64 s[0:1], -1
	v_pk_mul_f32 v[6:7], v[6:7], v[18:19] op_sel_hi:[1,0]
	v_pk_mul_f32 v[8:9], v[2:3], v[18:19] op_sel_hi:[1,0]
	v_pk_mul_f32 v[2:3], v[0:1], v[18:19] op_sel_hi:[1,0]
	v_pk_mul_f32 v[4:5], v[4:5], v[18:19] op_sel_hi:[1,0]
	s_nop 0
	v_cvt_pk_bf16_f32 v0, v4, v5
	v_cvt_pk_bf16_f32 v1, v6, v7
	v_cvt_pk_bf16_f32 v2, v2, v3
	v_cvt_pk_bf16_f32 v3, v8, v9
	ds_bpermute_b32 v244, v253, v0
	ds_bpermute_b32 v245, v253, v1
	ds_bpermute_b32 v246, v253, v2
	ds_bpermute_b32 v247, v253, v3
	v_lshl_add_u64 v[238:239], v[16:17], 0, v[250:251]
	s_waitcnt lgkmcnt(4)
	global_store_dwordx4 v[236:237], v[240:243], off
	s_waitcnt lgkmcnt(0)
	global_store_dwordx4 v[238:239], v[244:247], off offset:256
	s_cbranch_vccnz .LBB0_1028
	s_andn2_b64 vcc, exec, s[12:13]
	s_cbranch_vccnz .LBB0_1027
	s_barrier
	s_branch .LBB0_1027

; #define PH(k) (IN(k) && ((MK_MASK >> (k)) & 1))
; #define REPS(k) for (int rep_ = 0; rep_ < (((MK_REP_MASK) >> (k)) & 1) + 1; ++rep_)
;     __host__ __device__ __forceinline__ bool next(int i, Unit& u) const {
;         const long L = (long)i * G + c; if (L >= nwg) return false;
;         int wgid = (int)L; { const int q = nwg / NXCD, r = nwg % NXCD, xcd = wgid % NXCD, off = wgid / NXCD; wgid = (xcd < r ? xcd * (q + 1) : r * (q + 1) + (xcd - r) * q) + off; }
;         const int nig = WGM * nN, gid = wgid / nig, fm = gid * WGM, gsz = (nM - fm) < WGM ? (nM - fm) : WGM;
;         u.pm = fm + ((wgid % nig) % gsz); u.pn = (wgid % nig) / gsz; if (rev) u.pm = nM - 1 - u.pm; return true;
; __global__ void __launch_bounds__(NWAVES * 64, 2) mk_fwd(Params P) {
;     ...
;     if (PH(7)) REPS(7) { pg8::Gemm g{CO, Wco_t, M, D, D}; pg8::StaticOrder S; S.init(M, D, G, bx);
;         pg8::EpiRes2<true, true> E{H1B, H2B, SS2};
;         pg8::gemm_phase<pg8::EpiRes2<true, true>, pg8::StaticOrder, true, true>(lds, g, S, E, wave); }
.LBB0_1199:
	s_cmp_lt_i32 s74, 8
	s_cselect_b64 s[0:1], -1, 0
	s_and_b64 s[0:1], s[0:1], s[4:5]
	s_andn2_b64 vcc, exec, s[0:1]
	s_cbranch_vccnz .LBB0_1238
	v_and_b32_e32 v248, 15, v212
	v_lshrrev_b32_e32 v249, 2, v212
	v_sub_u32_e32 v249, v249, v248
	v_lshrrev_b32_e32 v248, 4, v212
	v_and_b32_e32 v253, 3, v212
	v_sub_u32_e32 v248, v253, v248
	v_lshlrev_b32_e32 v248, 4, v248
	v_mul_i32_i24_e32 v250, 0x800, v249
	v_add_u32_e32 v250, v250, v248
	v_ashrrev_i32_e32 v251, 31, v250
	v_lshlrev_b32_e32 v253, 4, v253
	v_lshrrev_b32_e32 v248, 2, v212
	v_add_u32_e32 v253, v253, v248
	v_lshlrev_b32_e32 v253, 2, v253
	s_and_b32 s2, s93, 0xffffffc0
	v_mov_b32_e32 v8, v212
	s_cmpk_lt_i32 s88, 0x200
	s_cselect_b64 s[4:5], -1, 0
	v_add_u32_e32 v0, s2, v8
	s_cmpk_gt_i32 s88, 0x1ff
	v_readfirstlane_b32 s6, v0
	s_cbranch_scc1 .LBB0_1202
	s_ashr_i32 s2, s88, 31
	s_lshr_b32 s2, s2, 29
	s_add_i32 s2, s88, s2
	s_and_b32 s3, s2, -8
	s_sub_i32 s3, s88, s3
	s_lshl_b32 s8, s3, 6
	s_ashr_i32 s2, s2, 3
	s_mul_i32 s7, s3, 0x41
	s_cmp_lt_i32 s3, 0
	s_cselect_b32 s3, s7, s8
	s_add_i32 s2, s3, s2
	s_ashr_i32 s3, s2, 31
	s_lshr_b32 s3, s3, 27
	s_add_i32 s3, s2, s3
	s_ashr_i32 s7, s3, 5
	s_andn2_b32 s3, s3, 31
	s_sub_i32 s2, s2, s3
	s_bfe_i32 s3, s2, 0x80000
	s_bfe_u32 s3, s3, 0x3000c
	s_add_i32 s3, s2, s3
	s_bfe_i32 s8, s3, 0x80000
	s_and_b32 s3, s3, 0xf8
	s_sub_i32 s2, s2, s3
	s_lshl_b32 s7, s7, 3
	s_sext_i32_i16 s8, s8
	s_sext_i32_i8 s2, s2
	s_add_i32 s34, s7, s2
	s_ashr_i32 s8, s8, 3

;     __device__ __forceinline__ void operator()(const f32x4 (&acc)[2][2][4][2], const Unit& u, int wr, int wc, int fr, int fq) const {
;         const int row0 = u.pm * BM + wr * 64 + fr, col0 = u.pn * BM + wc * 32 + 8 * fq;
; #pragma unroll
;         for (int ai = 0; ai < 2; ++ai) {
;             u32x4 bw[4][2]; f32x4 bf[4][2][2];
; #pragma unroll
;             for (int m = 0; m < 4; ++m)
; #pragma unroll
;                 for (int bj = 0; bj < 2; ++bj) { const size_t off = (size_t)(row0 + ai * HALF + m * 16) * 1024 + col0 + bj * HALF;
;                     if (BASE_BF16) bw[m][bj] = *(const u32x4*)((const bf16_t*)base + off);
;                     else { bf[m][bj][0] = *(const f32x4*)((const float*)base + off); bf[m][bj][1] = *(const f32x4*)((const float*)base + off + 4); } }
; #pragma unroll
;             for (int m = 0; m < 4; ++m) {
;                 const int row = row0 + ai * HALF + m * 16; const size_t off = (size_t)row * 1024 + col0;
;                 float ss = 0.f;
; #pragma unroll
;                 for (int bj = 0; bj < 2; ++bj) {
;                     f32x4 b0, b1;
;                     if (BASE_BF16) { const u32x4 w = bw[m][bj];
;                         b0 = (f32x4){__builtin_bit_cast(float, w.x << 16), __builtin_bit_cast(float, w.x & 0xffff0000u), __builtin_bit_cast(float, w.y << 16), __builtin_bit_cast(float, w.y & 0xffff0000u)};
;                         b1 = (f32x4){__builtin_bit_cast(float, w.z << 16), __builtin_bit_cast(float, w.z & 0xffff0000u), __builtin_bit_cast(float, w.w << 16), __builtin_bit_cast(float, w.w & 0xffff0000u)}; }
;                     else { b0 = bf[m][bj][0]; b1 = bf[m][bj][1]; }
;                     const f32x4 v0 = acc[ai][bj][m][0] + b0, v1 = acc[ai][bj][m][1] + b1;
;                     ss += (v0[0] * v0[0] + v0[1] * v0[1]) + (v0[2] * v0[2] + v0[3] * v0[3]) + (v1[0] * v1[0] + v1[1] * v1[1]) + (v1[2] * v1[2] + v1[3] * v1[3]);
;                     if (OUT_BF16) { u32x4 w; w.x = cvt_pk_bf16(v0[0], v0[1]); w.y = cvt_pk_bf16(v0[2], v0[3]); w.z = cvt_pk_bf16(v1[0], v1[1]); w.w = cvt_pk_bf16(v1[2], v1[3]);
;                         *(u32x4*)((bf16_t*)out + off + bj * HALF) = w; }
;                     else { *(f32x4*)((float*)out + off + bj * HALF) = v0; *(f32x4*)((float*)out + off + bj * HALF + 4) = v1; }
;                 }
;                 ss += __shfl_xor(ss, 16); ss += __shfl_xor(ss, 32);
.LBB0_1218:
	v_lshl_or_b32 v168, s8, 8, v190
	v_lshl_add_u32 v172, s34, 8, v188
	v_ashrrev_i32_e32 v169, 31, v168
	v_lshlrev_b64 v[202:203], 1, v[168:169]
	v_ashrrev_i32_e32 v173, 31, v172
	v_lshl_add_u64 v[170:171], s[12:13], 0, v[202:203]
	v_lshlrev_b64 v[204:205], 11, v[172:173]
	v_lshl_add_u64 v[128:129], v[170:171], 0, v[204:205]
	global_load_dwordx4 v[194:197], v[128:129], off
	global_load_dwordx4 v[198:201], v[128:129], off offset:256
	v_or_b32_e32 v182, 16, v172
	v_or_b32_e32 v178, 32, v172
	v_or_b32_e32 v174, 48, v172
	v_ashrrev_i32_e32 v183, 31, v182
	v_ashrrev_i32_e32 v179, 31, v178
	v_ashrrev_i32_e32 v175, 31, v174
	v_lshlrev_b64 v[184:185], 11, v[182:183]
	v_lshlrev_b64 v[180:181], 11, v[178:179]
	v_lshlrev_b64 v[176:177], 11, v[174:175]
	v_lshl_add_u64 v[128:129], v[170:171], 0, v[184:185]
	v_lshl_add_u64 v[130:131], v[170:171], 0, v[180:181]
	v_lshl_add_u64 v[206:207], v[170:171], 0, v[176:177]
	global_load_dwordx4 v[148:151], v[128:129], off
	global_load_dwordx4 v[144:147], v[128:129], off offset:256
	global_load_dwordx4 v[140:143], v[130:131], off
	global_load_dwordx4 v[136:139], v[130:131], off offset:256
	global_load_dwordx4 v[132:135], v[206:207], off
	s_nop 0
	global_load_dwordx4 v[128:131], v[206:207], off offset:256
	s_lshl_b32 s34, s8, 2
	s_ashr_i32 s35, s34, 31
	s_waitcnt vmcnt(0)
	v_lshlrev_b32_e32 v206, 16, v194
	v_and_b32_e32 v207, 0xffff0000, v194
	v_lshlrev_b32_e32 v194, 16, v195
	v_and_b32_e32 v195, 0xffff0000, v195
	v_lshlrev_b32_e32 v208, 16, v196
	v_and_b32_e32 v209, 0xffff0000, v196
	v_lshlrev_b32_e32 v196, 16, v197
	v_and_b32_e32 v197, 0xffff0000, v197
	v_lshlrev_b32_e32 v210, 16, v198
	v_and_b32_e32 v211, 0xffff0000, v198
	v_lshlrev_b32_e32 v198, 16, v199
	v_and_b32_e32 v199, 0xffff0000, v199
	v_lshlrev_b32_e32 v214, 16, v200
	v_and_b32_e32 v215, 0xffff0000, v200
	v_lshlrev_b32_e32 v200, 16, v201
	v_and_b32_e32 v201, 0xffff0000, v201
	v_pk_add_f32 v[126:127], v[126:127], v[194:195]
	v_pk_add_f32 v[124:125], v[124:125], v[206:207]
	v_pk_add_f32 v[122:123], v[122:123], v[196:197]
	v_pk_add_f32 v[120:121], v[120:121], v[208:209]
	v_pk_add_f32 v[118:119], v[118:119], v[198:199]
	v_pk_add_f32 v[116:117], v[116:117], v[210:211]
	v_pk_add_f32 v[194:195], v[114:115], v[200:201]
	v_pk_add_f32 v[196:197], v[112:113], v[214:215]
	v_mul_f32_e32 v198, v125, v125
	v_mul_f32_e32 v199, v127, v127
	v_mul_f32_e32 v200, v121, v121
	v_mul_f32_e32 v201, v123, v123
	v_cvt_pk_bf16_f32 v112, v124, v125
	v_cvt_pk_bf16_f32 v113, v126, v127
	v_cvt_pk_bf16_f32 v114, v120, v121
	v_cvt_pk_bf16_f32 v115, v122, v123
	v_mul_f32_e32 v121, v117, v117
	v_mul_f32_e32 v123, v119, v119
	v_mul_f32_e32 v125, v197, v197
	v_fmac_f32_e32 v198, v124, v124
	v_fmac_f32_e32 v199, v126, v126
	v_fmac_f32_e32 v121, v116, v116
	v_fmac_f32_e32 v123, v118, v118
	v_mul_f32_e32 v127, v195, v195
	v_fmac_f32_e32 v200, v120, v120
	v_fmac_f32_e32 v125, v196, v196
	v_add_f32_e32 v120, v198, v199
	v_add_f32_e32 v121, v121, v123
	v_fmac_f32_e32 v201, v122, v122
	v_fmac_f32_e32 v127, v194, v194
	v_add_f32_e32 v120, v200, v120
	v_add_f32_e32 v121, v125, v121
	v_add_f32_e32 v120, v201, v120
	v_add_f32_e32 v121, v127, v121
	v_add_f32_e32 v122, v120, v121
	ds_bpermute_b32 v123, v186, v122
	v_lshl_add_u64 v[120:121], s[14:15], 0, v[204:205]
	v_lshl_add_u64 v[120:121], v[120:121], 0, v[202:203]
	ds_bpermute_b32 v240, v253, v112
	ds_bpermute_b32 v241, v253, v113
	ds_bpermute_b32 v242, v253, v114
	ds_bpermute_b32 v243, v253, v115
	v_lshl_add_u64 v[236:237], v[120:121], 0, v[250:251]
	s_waitcnt lgkmcnt(0)
	s_nop 0
	v_add_f32_e32 v112, v122, v123
	ds_bpermute_b32 v113, v187, v112
	v_cvt_pk_bf16_f32 v114, v116, v117
	v_cvt_pk_bf16_f32 v115, v118, v119
	v_cvt_pk_bf16_f32 v116, v196, v197
	v_cvt_pk_bf16_f32 v117, v194, v195
	ds_bpermute_b32 v244, v253, v114
	ds_bpermute_b32 v245, v253, v115
	ds_bpermute_b32 v246, v253, v116
	ds_bpermute_b32 v247, v253, v117
	v_lshl_add_u64 v[238:239], v[120:121], 0, v[250:251]
	s_waitcnt lgkmcnt(4)
	global_store_dwordx4 v[236:237], v[240:243], off
	s_and_saveexec_b64 s[36:37], s[4:5]
	s_cbranch_execz .LBB0_1220
	v_lshlrev_b64 v[114:115], 6, v[172:173]
	v_lshl_add_u64 v[114:115], s[16:17], 0, v[114:115]
	v_lshl_add_u64 v[114:115], s[34:35], 2, v[114:115]
	s_lshl_b32 s8, s48, 2
	v_lshl_add_u64 v[114:115], v[114:115], 0, s[8:9]
	s_waitcnt lgkmcnt(0)
	v_add_f32_e32 v112, v112, v113
	global_store_dword v[114:115], v112, off
; __device__ __forceinline__ unsigned cvt_pk_bf16(float lo, float hi) { unsigned r; asm volatile("v_cvt_pk_bf16_f32 %0, %1, %2" : "=v"(r) : "v"(lo), "v"(hi)); return r; }
;     __device__ __forceinline__ void operator()(const f32x4 (&acc)[2][2][4][2], const Unit& u, int wr, int wc, int fr, int fq) const {
;     ...
;             for (int m = 0; m < 4; ++m) {
;                 const int row = row0 + ai * HALF + m * 16; const size_t off = (size_t)row * 1024 + col0;
;                 float ss = 0.f;
; #pragma unroll
;                 for (int bj = 0; bj < 2; ++bj) {
;                     f32x4 b0, b1;
;                     if (BASE_BF16) { const u32x4 w = bw[m][bj];
;                         b0 = (f32x4){__builtin_bit_cast(float, w.x << 16), __builtin_bit_cast(float, w.x & 0xffff0000u), __builtin_bit_cast(float, w.y << 16), __builtin_bit_cast(float, w.y & 0xffff0000u)};
;                         b1 = (f32x4){__builtin_bit_cast(float, w.z << 16), __builtin_bit_cast(float, w.z & 0xffff0000u), __builtin_bit_cast(float, w.w << 16), __builtin_bit_cast(float, w.w & 0xffff0000u)}; }
;                     else { b0 = bf[m][bj][0]; b1 = bf[m][bj][1]; }
;                     const f32x4 v0 = acc[ai][bj][m][0] + b0, v1 = acc[ai][bj][m][1] + b1;
;                     ss += (v0[0] * v0[0] + v0[1] * v0[1]) + (v0[2] * v0[2] + v0[3] * v0[3]) + (v1[0] * v1[0] + v1[1] * v1[1]) + (v1[2] * v1[2] + v1[3] * v1[3]);
;                     if (OUT_BF16) { u32x4 w; w.x = cvt_pk_bf16(v0[0], v0[1]); w.y = cvt_pk_bf16(v0[2], v0[3]); w.z = cvt_pk_bf16(v1[0], v1[1]); w.w = cvt_pk_bf16(v1[2], v1[3]);
;                         *(u32x4*)((bf16_t*)out + off + bj * HALF) = w; }
;                     else { *(f32x4*)((float*)out + off + bj * HALF) = v0; *(f32x4*)((float*)out + off + bj * HALF + 4) = v1; }
;                 }
;                 ss += __shfl_xor(ss, 16); ss += __shfl_xor(ss, 32);
;                 if (fq == 0) sspart[(size_t)row * 16 + u.pn * 4 + wc] = ss;
.LBB0_1220:
	s_or_b64 exec, exec, s[36:37]
	v_lshlrev_b32_e32 v112, 16, v148
	s_waitcnt lgkmcnt(0)
	v_and_b32_e32 v113, 0xffff0000, v148
	v_lshlrev_b32_e32 v114, 16, v149
	v_and_b32_e32 v115, 0xffff0000, v149
	v_lshlrev_b32_e32 v116, 16, v150
	v_and_b32_e32 v117, 0xffff0000, v150
	v_lshlrev_b32_e32 v118, 16, v151
	v_and_b32_e32 v119, 0xffff0000, v151
	v_pk_add_f32 v[110:111], v[110:111], v[114:115]
	v_pk_add_f32 v[108:109], v[108:109], v[112:113]
	v_pk_add_f32 v[112:113], v[106:107], v[118:119]
	v_pk_add_f32 v[106:107], v[104:105], v[116:117]
	v_mul_f32_e32 v104, v109, v109
	v_mul_f32_e32 v105, v111, v111
	v_fmac_f32_e32 v104, v108, v108
	v_fmac_f32_e32 v105, v110, v110
	v_add_f32_e32 v104, v104, v105
	v_mul_f32_e32 v105, v107, v107
	v_fmac_f32_e32 v105, v106, v106
	v_add_f32_e32 v104, v105, v104
	v_mul_f32_e32 v105, v113, v113
	v_fmac_f32_e32 v105, v112, v112
	v_add_f32_e32 v116, v105, v104
	v_cvt_pk_bf16_f32 v104, v108, v109
	v_cvt_pk_bf16_f32 v105, v110, v111
	v_lshlrev_b32_e32 v108, 16, v144
	v_and_b32_e32 v109, 0xffff0000, v144
	v_lshlrev_b32_e32 v110, 16, v145
	v_and_b32_e32 v111, 0xffff0000, v145
	v_cvt_pk_bf16_f32 v106, v106, v107
	v_cvt_pk_bf16_f32 v107, v112, v113
	v_lshlrev_b32_e32 v112, 16, v146
	v_and_b32_e32 v113, 0xffff0000, v146
	v_pk_add_f32 v[102:103], v[102:103], v[110:111]
	v_pk_add_f32 v[100:101], v[100:101], v[108:109]
	v_pk_add_f32 v[110:111], v[96:97], v[112:113]
	v_mul_f32_e32 v96, v101, v101
	v_mul_f32_e32 v97, v103, v103
	v_fmac_f32_e32 v96, v100, v100
	v_fmac_f32_e32 v97, v102, v102
	v_lshlrev_b32_e32 v114, 16, v147
	v_and_b32_e32 v115, 0xffff0000, v147
	v_add_f32_e32 v96, v96, v97
	v_mul_f32_e32 v97, v111, v111
	v_pk_add_f32 v[108:109], v[98:99], v[114:115]
	v_fmac_f32_e32 v97, v110, v110
	v_add_f32_e32 v96, v97, v96
	v_mul_f32_e32 v97, v109, v109
	v_fmac_f32_e32 v97, v108, v108
	v_add_f32_e32 v96, v97, v96
	v_add_f32_e32 v99, v116, v96
	ds_bpermute_b32 v114, v186, v99
	v_lshl_add_u64 v[96:97], s[14:15], 0, v[184:185]
	v_lshl_add_u64 v[112:113], v[168:169], 1, v[96:97]
	ds_bpermute_b32 v240, v253, v104
	ds_bpermute_b32 v241, v253, v105
	ds_bpermute_b32 v242, v253, v106
	ds_bpermute_b32 v243, v253, v107
	v_lshl_add_u64 v[236:237], v[112:113], 0, v[250:251]
	s_waitcnt lgkmcnt(4)
	global_store_dwordx4 v[238:239], v[244:247], off offset:256
	v_cvt_pk_bf16_f32 v98, v100, v101
	s_waitcnt lgkmcnt(0)
	v_add_f32_e32 v96, v99, v114
	ds_bpermute_b32 v97, v187, v96
	v_cvt_pk_bf16_f32 v99, v102, v103
	v_cvt_pk_bf16_f32 v100, v110, v111
	v_cvt_pk_bf16_f32 v101, v108, v109
	ds_bpermute_b32 v244, v253, v98
	ds_bpermute_b32 v245, v253, v99
	ds_bpermute_b32 v246, v253, v100
	ds_bpermute_b32 v247, v253, v101
	v_lshl_add_u64 v[238:239], v[112:113], 0, v[250:251]
	s_waitcnt lgkmcnt(4)
	global_store_dwordx4 v[236:237], v[240:243], off
	s_and_saveexec_b64 s[36:37], s[4:5]
	s_cbranch_execz .LBB0_1222
	v_lshlrev_b64 v[98:99], 6, v[182:183]
	v_lshl_add_u64 v[98:99], s[16:17], 0, v[98:99]
	v_lshl_add_u64 v[98:99], s[34:35], 2, v[98:99]
	s_lshl_b32 s8, s48, 2
	v_lshl_add_u64 v[98:99], v[98:99], 0, s[8:9]
	s_waitcnt lgkmcnt(0)
	v_add_f32_e32 v96, v96, v97
	global_store_dword v[98:99], v96, off
.LBB0_1222:
	s_or_b64 exec, exec, s[36:37]
	v_lshlrev_b32_e32 v96, 16, v140
	s_waitcnt lgkmcnt(0)
	v_and_b32_e32 v97, 0xffff0000, v140
	v_lshlrev_b32_e32 v98, 16, v141
	v_and_b32_e32 v99, 0xffff0000, v141
	v_lshlrev_b32_e32 v100, 16, v142
	v_and_b32_e32 v101, 0xffff0000, v142
	v_lshlrev_b32_e32 v102, 16, v143
	v_and_b32_e32 v103, 0xffff0000, v143
	v_pk_add_f32 v[94:95], v[94:95], v[98:99]
	v_pk_add_f32 v[92:93], v[92:93], v[96:97]
	v_pk_add_f32 v[96:97], v[90:91], v[102:103]
	v_pk_add_f32 v[90:91], v[88:89], v[100:101]
	v_mul_f32_e32 v88, v93, v93
	v_mul_f32_e32 v89, v95, v95
	v_fmac_f32_e32 v88, v92, v92
	v_fmac_f32_e32 v89, v94, v94
	v_add_f32_e32 v88, v88, v89
	v_mul_f32_e32 v89, v91, v91
	v_fmac_f32_e32 v89, v90, v90
	v_add_f32_e32 v88, v89, v88
	v_mul_f32_e32 v89, v97, v97
	v_fmac_f32_e32 v89, v96, v96
	v_add_f32_e32 v100, v89, v88
	v_cvt_pk_bf16_f32 v88, v92, v93
	v_cvt_pk_bf16_f32 v89, v94, v95
	v_lshlrev_b32_e32 v92, 16, v136
	v_and_b32_e32 v93, 0xffff0000, v136
	v_lshlrev_b32_e32 v94, 16, v137
	v_and_b32_e32 v95, 0xffff0000, v137
	v_cvt_pk_bf16_f32 v90, v90, v91
	v_cvt_pk_bf16_f32 v91, v96, v97
	v_lshlrev_b32_e32 v96, 16, v138
	v_and_b32_e32 v97, 0xffff0000, v138
	v_pk_add_f32 v[86:87], v[86:87], v[94:95]
	v_pk_add_f32 v[84:85], v[84:85], v[92:93]
	v_pk_add_f32 v[94:95], v[80:81], v[96:97]
	v_mul_f32_e32 v80, v85, v85
	v_mul_f32_e32 v81, v87, v87
	v_fmac_f32_e32 v80, v84, v84
	v_fmac_f32_e32 v81, v86, v86
	v_lshlrev_b32_e32 v98, 16, v139
	v_and_b32_e32 v99, 0xffff0000, v139
	v_add_f32_e32 v80, v80, v81
	v_mul_f32_e32 v81, v95, v95
	v_pk_add_f32 v[92:93], v[82:83], v[98:99]
	v_fmac_f32_e32 v81, v94, v94
	v_add_f32_e32 v80, v81, v80
	v_mul_f32_e32 v81, v93, v93
	v_fmac_f32_e32 v81, v92, v92
	v_add_f32_e32 v80, v81, v80
	v_add_f32_e32 v83, v100, v80
	ds_bpermute_b32 v98, v186, v83
	v_lshl_add_u64 v[80:81], s[14:15], 0, v[180:181]
	v_lshl_add_u64 v[96:97], v[168:169], 1, v[80:81]
	ds_bpermute_b32 v240, v253, v88
	ds_bpermute_b32 v241, v253, v89
	ds_bpermute_b32 v242, v253, v90
	ds_bpermute_b32 v243, v253, v91
	v_lshl_add_u64 v[236:237], v[96:97], 0, v[250:251]
	s_waitcnt lgkmcnt(4)
	global_store_dwordx4 v[238:239], v[244:247], off offset:256
	v_cvt_pk_bf16_f32 v82, v84, v85
	s_waitcnt lgkmcnt(0)
	v_add_f32_e32 v80, v83, v98
	ds_bpermute_b32 v81, v187, v80
	v_cvt_pk_bf16_f32 v83, v86, v87
	v_cvt_pk_bf16_f32 v84, v94, v95
	v_cvt_pk_bf16_f32 v85, v92, v93
	ds_bpermute_b32 v244, v253, v82
	ds_bpermute_b32 v245, v253, v83
	ds_bpermute_b32 v246, v253, v84
	ds_bpermute_b32 v247, v253, v85
	v_lshl_add_u64 v[238:239], v[96:97], 0, v[250:251]
	s_waitcnt lgkmcnt(4)
	global_store_dwordx4 v[236:237], v[240:243], off
	s_and_saveexec_b64 s[36:37], s[4:5]
	s_cbranch_execz .LBB0_1224
	v_lshlrev_b64 v[82:83], 6, v[178:179]
	v_lshl_add_u64 v[82:83], s[16:17], 0, v[82:83]
	v_lshl_add_u64 v[82:83], s[34:35], 2, v[82:83]
	s_lshl_b32 s8, s48, 2
	v_lshl_add_u64 v[82:83], v[82:83], 0, s[8:9]
	s_waitcnt lgkmcnt(0)
	v_add_f32_e32 v80, v80, v81
	global_store_dword v[82:83], v80, off
; __device__ __forceinline__ unsigned cvt_pk_bf16(float lo, float hi) { unsigned r; asm volatile("v_cvt_pk_bf16_f32 %0, %1, %2" : "=v"(r) : "v"(lo), "v"(hi)); return r; }
;     __device__ __forceinline__ void operator()(const f32x4 (&acc)[2][2][4][2], const Unit& u, int wr, int wc, int fr, int fq) const {
;     ...
;                 for (int bj = 0; bj < 2; ++bj) { const size_t off = (size_t)(row0 + ai * HALF + m * 16) * 1024 + col0 + bj * HALF;
;                     if (BASE_BF16) bw[m][bj] = *(const u32x4*)((const bf16_t*)base + off);
;                     else { bf[m][bj][0] = *(const f32x4*)((const float*)base + off); bf[m][bj][1] = *(const f32x4*)((const float*)base + off + 4); } }
; #pragma unroll
;             for (int m = 0; m < 4; ++m) {
;                 const int row = row0 + ai * HALF + m * 16; const size_t off = (size_t)row * 1024 + col0;
;                 float ss = 0.f;
; #pragma unroll
;                 for (int bj = 0; bj < 2; ++bj) {
;                     f32x4 b0, b1;
;                     if (BASE_BF16) { const u32x4 w = bw[m][bj];
;                         b0 = (f32x4){__builtin_bit_cast(float, w.x << 16), __builtin_bit_cast(float, w.x & 0xffff0000u), __builtin_bit_cast(float, w.y << 16), __builtin_bit_cast(float, w.y & 0xffff0000u)};
;                         b1 = (f32x4){__builtin_bit_cast(float, w.z << 16), __builtin_bit_cast(float, w.z & 0xffff0000u), __builtin_bit_cast(float, w.w << 16), __builtin_bit_cast(float, w.w & 0xffff0000u)}; }
;                     else { b0 = bf[m][bj][0]; b1 = bf[m][bj][1]; }
;                     const f32x4 v0 = acc[ai][bj][m][0] + b0, v1 = acc[ai][bj][m][1] + b1;
;                     ss += (v0[0] * v0[0] + v0[1] * v0[1]) + (v0[2] * v0[2] + v0[3] * v0[3]) + (v1[0] * v1[0] + v1[1] * v1[1]) + (v1[2] * v1[2] + v1[3] * v1[3]);
;                     if (OUT_BF16) { u32x4 w; w.x = cvt_pk_bf16(v0[0], v0[1]); w.y = cvt_pk_bf16(v0[2], v0[3]); w.z = cvt_pk_bf16(v1[0], v1[1]); w.w = cvt_pk_bf16(v1[2], v1[3]);
;                         *(u32x4*)((bf16_t*)out + off + bj * HALF) = w; }
;                     else { *(f32x4*)((float*)out + off + bj * HALF) = v0; *(f32x4*)((float*)out + off + bj * HALF + 4) = v1; }
;                 }
;                 ss += __shfl_xor(ss, 16); ss += __shfl_xor(ss, 32);
;                 if (fq == 0) sspart[(size_t)row * 16 + u.pn * 4 + wc] = ss;
.LBB0_1224:
	s_or_b64 exec, exec, s[36:37]
	v_lshlrev_b32_e32 v80, 16, v132
	s_waitcnt lgkmcnt(0)
	v_and_b32_e32 v81, 0xffff0000, v132
	v_lshlrev_b32_e32 v82, 16, v133
	v_and_b32_e32 v83, 0xffff0000, v133
	v_lshlrev_b32_e32 v84, 16, v134
	v_and_b32_e32 v85, 0xffff0000, v134
	v_lshlrev_b32_e32 v86, 16, v135
	v_and_b32_e32 v87, 0xffff0000, v135
	v_pk_add_f32 v[78:79], v[78:79], v[82:83]
	v_pk_add_f32 v[76:77], v[76:77], v[80:81]
	v_pk_add_f32 v[80:81], v[74:75], v[86:87]
	v_pk_add_f32 v[74:75], v[72:73], v[84:85]
	v_mul_f32_e32 v72, v77, v77
	v_mul_f32_e32 v73, v79, v79
	v_fmac_f32_e32 v72, v76, v76
	v_fmac_f32_e32 v73, v78, v78
	v_add_f32_e32 v72, v72, v73
	v_mul_f32_e32 v73, v75, v75
	v_fmac_f32_e32 v73, v74, v74
	v_add_f32_e32 v72, v73, v72
	v_mul_f32_e32 v73, v81, v81
	v_fmac_f32_e32 v73, v80, v80
	v_add_f32_e32 v84, v73, v72
	v_cvt_pk_bf16_f32 v72, v76, v77
	v_cvt_pk_bf16_f32 v73, v78, v79
	v_lshlrev_b32_e32 v76, 16, v128
	v_and_b32_e32 v77, 0xffff0000, v128
	v_lshlrev_b32_e32 v78, 16, v129
	v_and_b32_e32 v79, 0xffff0000, v129
	v_cvt_pk_bf16_f32 v74, v74, v75
	v_cvt_pk_bf16_f32 v75, v80, v81
	v_lshlrev_b32_e32 v80, 16, v130
	v_and_b32_e32 v81, 0xffff0000, v130
	v_pk_add_f32 v[70:71], v[70:71], v[78:79]
	v_pk_add_f32 v[68:69], v[68:69], v[76:77]
	v_pk_add_f32 v[78:79], v[64:65], v[80:81]
	v_mul_f32_e32 v64, v69, v69
	v_mul_f32_e32 v65, v71, v71
	v_fmac_f32_e32 v64, v68, v68
	v_fmac_f32_e32 v65, v70, v70
	v_lshlrev_b32_e32 v82, 16, v131
	v_and_b32_e32 v83, 0xffff0000, v131
	v_add_f32_e32 v64, v64, v65
	v_mul_f32_e32 v65, v79, v79
	v_pk_add_f32 v[76:77], v[66:67], v[82:83]
	v_fmac_f32_e32 v65, v78, v78
	v_add_f32_e32 v64, v65, v64
	v_mul_f32_e32 v65, v77, v77
	v_fmac_f32_e32 v65, v76, v76
	v_add_f32_e32 v64, v65, v64
	v_add_f32_e32 v67, v84, v64
	ds_bpermute_b32 v82, v186, v67
	v_lshl_add_u64 v[64:65], s[14:15], 0, v[176:177]
	v_lshl_add_u64 v[80:81], v[168:169], 1, v[64:65]
	ds_bpermute_b32 v240, v253, v72
	ds_bpermute_b32 v241, v253, v73
	ds_bpermute_b32 v242, v253, v74
	ds_bpermute_b32 v243, v253, v75
	v_lshl_add_u64 v[236:237], v[80:81], 0, v[250:251]
	s_waitcnt lgkmcnt(4)
	global_store_dwordx4 v[238:239], v[244:247], off offset:256
	v_cvt_pk_bf16_f32 v66, v68, v69
	s_waitcnt lgkmcnt(0)
	v_add_f32_e32 v64, v67, v82
	ds_bpermute_b32 v65, v187, v64
	v_cvt_pk_bf16_f32 v67, v70, v71
	v_cvt_pk_bf16_f32 v68, v78, v79
	v_cvt_pk_bf16_f32 v69, v76, v77
	ds_bpermute_b32 v244, v253, v66
	ds_bpermute_b32 v245, v253, v67
	ds_bpermute_b32 v246, v253, v68
	ds_bpermute_b32 v247, v253, v69
	v_lshl_add_u64 v[238:239], v[80:81], 0, v[250:251]
	s_waitcnt lgkmcnt(4)
	global_store_dwordx4 v[236:237], v[240:243], off
	s_and_saveexec_b64 s[36:37], s[4:5]
	s_cbranch_execz .LBB0_1226
	v_lshlrev_b64 v[66:67], 6, v[174:175]
	v_lshl_add_u64 v[66:67], s[16:17], 0, v[66:67]
	v_lshl_add_u64 v[66:67], s[34:35], 2, v[66:67]
	s_lshl_b32 s8, s48, 2
	v_lshl_add_u64 v[66:67], v[66:67], 0, s[8:9]
	s_waitcnt lgkmcnt(0)
	v_add_f32_e32 v64, v64, v65
	global_store_dword v[66:67], v64, off
.LBB0_1226:
	s_or_b64 exec, exec, s[36:37]
	v_add_u32_e32 v100, 0x80, v172
	v_ashrrev_i32_e32 v101, 31, v100
	v_lshlrev_b64 v[110:111], 11, v[100:101]
	s_waitcnt lgkmcnt(0)
	v_lshl_add_u64 v[64:65], v[170:171], 0, v[110:111]
	global_load_dwordx4 v[102:105], v[64:65], off
	global_load_dwordx4 v[106:109], v[64:65], off offset:256
	v_add_u32_e32 v96, 0x90, v172
	v_add_u32_e32 v92, 0xa0, v172
	v_add_u32_e32 v88, 0xb0, v172
	v_ashrrev_i32_e32 v97, 31, v96
	v_ashrrev_i32_e32 v93, 31, v92
	v_ashrrev_i32_e32 v89, 31, v88
	v_lshlrev_b64 v[98:99], 11, v[96:97]
	v_lshlrev_b64 v[94:95], 11, v[92:93]
	v_lshlrev_b64 v[90:91], 11, v[88:89]
	v_lshl_add_u64 v[64:65], v[170:171], 0, v[98:99]
	v_lshl_add_u64 v[66:67], v[170:171], 0, v[94:95]
	v_lshl_add_u64 v[112:113], v[170:171], 0, v[90:91]
	global_load_dwordx4 v[84:87], v[64:65], off
	global_load_dwordx4 v[80:83], v[64:65], off offset:256
	global_load_dwordx4 v[76:79], v[66:67], off
	global_load_dwordx4 v[72:75], v[66:67], off offset:256
	global_load_dwordx4 v[68:71], v[112:113], off
	s_nop 0
	global_load_dwordx4 v[64:67], v[112:113], off offset:256
	s_waitcnt vmcnt(7)
	v_lshlrev_b32_e32 v112, 16, v102
	v_and_b32_e32 v113, 0xffff0000, v102
	v_lshlrev_b32_e32 v102, 16, v103
	v_and_b32_e32 v103, 0xffff0000, v103
	v_lshlrev_b32_e32 v114, 16, v104
	v_and_b32_e32 v115, 0xffff0000, v104
	v_lshlrev_b32_e32 v104, 16, v105
	v_and_b32_e32 v105, 0xffff0000, v105
	s_waitcnt vmcnt(6)
	v_lshlrev_b32_e32 v116, 16, v106
	v_and_b32_e32 v117, 0xffff0000, v106
	v_lshlrev_b32_e32 v106, 16, v107
	v_and_b32_e32 v107, 0xffff0000, v107
	v_lshlrev_b32_e32 v118, 16, v108
	v_and_b32_e32 v119, 0xffff0000, v108
	v_lshlrev_b32_e32 v108, 16, v109
	v_and_b32_e32 v109, 0xffff0000, v109
	v_pk_add_f32 v[62:63], v[62:63], v[102:103]
	v_pk_add_f32 v[60:61], v[60:61], v[112:113]
	v_pk_add_f32 v[58:59], v[58:59], v[104:105]
	v_pk_add_f32 v[56:57], v[56:57], v[114:115]
	v_pk_add_f32 v[54:55], v[54:55], v[106:107]
	v_pk_add_f32 v[52:53], v[52:53], v[116:117]
	v_pk_add_f32 v[102:103], v[50:51], v[108:109]
	v_pk_add_f32 v[104:105], v[48:49], v[118:119]
	v_mul_f32_e32 v106, v61, v61
	v_mul_f32_e32 v107, v63, v63
	v_mul_f32_e32 v108, v57, v57
	v_mul_f32_e32 v109, v59, v59
	v_cvt_pk_bf16_f32 v48, v60, v61
	v_cvt_pk_bf16_f32 v49, v62, v63
	v_cvt_pk_bf16_f32 v50, v56, v57
	v_cvt_pk_bf16_f32 v51, v58, v59
	v_mul_f32_e32 v57, v53, v53
	v_mul_f32_e32 v59, v55, v55
	v_mul_f32_e32 v61, v105, v105
	v_fmac_f32_e32 v106, v60, v60
	v_fmac_f32_e32 v107, v62, v62
	v_fmac_f32_e32 v57, v52, v52
	v_fmac_f32_e32 v59, v54, v54
	v_mul_f32_e32 v63, v103, v103
	v_fmac_f32_e32 v108, v56, v56
	v_fmac_f32_e32 v61, v104, v104
	v_add_f32_e32 v56, v106, v107
	v_add_f32_e32 v57, v57, v59
	v_fmac_f32_e32 v109, v58, v58
	v_fmac_f32_e32 v63, v102, v102
	v_add_f32_e32 v56, v108, v56
	v_add_f32_e32 v57, v61, v57
	v_add_f32_e32 v56, v109, v56
	v_add_f32_e32 v57, v63, v57
	v_add_f32_e32 v58, v56, v57
	ds_bpermute_b32 v59, v186, v58
	v_lshl_add_u64 v[56:57], s[14:15], 0, v[110:111]
	v_lshl_add_u64 v[56:57], v[168:169], 1, v[56:57]
	ds_bpermute_b32 v240, v253, v48
	ds_bpermute_b32 v241, v253, v49
	ds_bpermute_b32 v242, v253, v50
	ds_bpermute_b32 v243, v253, v51
	v_lshl_add_u64 v[236:237], v[56:57], 0, v[250:251]
	s_waitcnt lgkmcnt(4)
	global_store_dwordx4 v[238:239], v[244:247], off offset:256
	s_waitcnt lgkmcnt(0)
	s_nop 0
	v_add_f32_e32 v48, v58, v59
	ds_bpermute_b32 v49, v187, v48
	v_cvt_pk_bf16_f32 v50, v52, v53
	v_cvt_pk_bf16_f32 v51, v54, v55
	v_cvt_pk_bf16_f32 v52, v104, v105
	v_cvt_pk_bf16_f32 v53, v102, v103
	ds_bpermute_b32 v244, v253, v50
	ds_bpermute_b32 v245, v253, v51
	ds_bpermute_b32 v246, v253, v52
	ds_bpermute_b32 v247, v253, v53
	v_lshl_add_u64 v[238:239], v[56:57], 0, v[250:251]
	s_waitcnt lgkmcnt(4)
	global_store_dwordx4 v[236:237], v[240:243], off
	s_and_saveexec_b64 s[36:37], s[4:5]
	s_cbranch_execz .LBB0_1228
; __device__ __forceinline__ unsigned cvt_pk_bf16(float lo, float hi) { unsigned r; asm volatile("v_cvt_pk_bf16_f32 %0, %1, %2" : "=v"(r) : "v"(lo), "v"(hi)); return r; }
;     __device__ __forceinline__ void operator()(const f32x4 (&acc)[2][2][4][2], const Unit& u, int wr, int wc, int fr, int fq) const {
;     ...
;             for (int m = 0; m < 4; ++m) {
;                 const int row = row0 + ai * HALF + m * 16; const size_t off = (size_t)row * 1024 + col0;
;                 float ss = 0.f;
; #pragma unroll
;                 for (int bj = 0; bj < 2; ++bj) {
;                     f32x4 b0, b1;
;                     if (BASE_BF16) { const u32x4 w = bw[m][bj];
;                         b0 = (f32x4){__builtin_bit_cast(float, w.x << 16), __builtin_bit_cast(float, w.x & 0xffff0000u), __builtin_bit_cast(float, w.y << 16), __builtin_bit_cast(float, w.y & 0xffff0000u)};
;                         b1 = (f32x4){__builtin_bit_cast(float, w.z << 16), __builtin_bit_cast(float, w.z & 0xffff0000u), __builtin_bit_cast(float, w.w << 16), __builtin_bit_cast(float, w.w & 0xffff0000u)}; }
;                     else { b0 = bf[m][bj][0]; b1 = bf[m][bj][1]; }
;                     const f32x4 v0 = acc[ai][bj][m][0] + b0, v1 = acc[ai][bj][m][1] + b1;
;                     ss += (v0[0] * v0[0] + v0[1] * v0[1]) + (v0[2] * v0[2] + v0[3] * v0[3]) + (v1[0] * v1[0] + v1[1] * v1[1]) + (v1[2] * v1[2] + v1[3] * v1[3]);
;                     if (OUT_BF16) { u32x4 w; w.x = cvt_pk_bf16(v0[0], v0[1]); w.y = cvt_pk_bf16(v0[2], v0[3]); w.z = cvt_pk_bf16(v1[0], v1[1]); w.w = cvt_pk_bf16(v1[2], v1[3]);
;                         *(u32x4*)((bf16_t*)out + off + bj * HALF) = w; }
;                     else { *(f32x4*)((float*)out + off + bj * HALF) = v0; *(f32x4*)((float*)out + off + bj * HALF + 4) = v1; }
;                 }
;                 ss += __shfl_xor(ss, 16); ss += __shfl_xor(ss, 32);
;                 if (fq == 0) sspart[(size_t)row * 16 + u.pn * 4 + wc] = ss;
	v_lshlrev_b64 v[50:51], 6, v[100:101]
	v_lshl_add_u64 v[50:51], s[16:17], 0, v[50:51]
	v_lshl_add_u64 v[50:51], s[34:35], 2, v[50:51]
	s_lshl_b32 s8, s48, 2
	v_lshl_add_u64 v[50:51], v[50:51], 0, s[8:9]
	s_waitcnt lgkmcnt(0)
	v_add_f32_e32 v48, v48, v49
	global_store_dword v[50:51], v48, off
.LBB0_1228:
	s_or_b64 exec, exec, s[36:37]
	s_waitcnt vmcnt(7)
	v_lshlrev_b32_e32 v48, 16, v84
	s_waitcnt lgkmcnt(0)
	v_and_b32_e32 v49, 0xffff0000, v84
	v_lshlrev_b32_e32 v50, 16, v85
	v_and_b32_e32 v51, 0xffff0000, v85
	v_lshlrev_b32_e32 v52, 16, v86
	v_and_b32_e32 v53, 0xffff0000, v86
	v_lshlrev_b32_e32 v54, 16, v87
	v_and_b32_e32 v55, 0xffff0000, v87
	v_pk_add_f32 v[46:47], v[46:47], v[50:51]
	v_pk_add_f32 v[44:45], v[44:45], v[48:49]
	v_pk_add_f32 v[48:49], v[42:43], v[54:55]
	v_pk_add_f32 v[42:43], v[40:41], v[52:53]
	v_mul_f32_e32 v40, v45, v45
	v_mul_f32_e32 v41, v47, v47
	v_fmac_f32_e32 v40, v44, v44
	v_fmac_f32_e32 v41, v46, v46
	v_add_f32_e32 v40, v40, v41
	v_mul_f32_e32 v41, v43, v43
	v_fmac_f32_e32 v41, v42, v42
	v_add_f32_e32 v40, v41, v40
	v_mul_f32_e32 v41, v49, v49
	v_fmac_f32_e32 v41, v48, v48
	v_add_f32_e32 v52, v41, v40
	v_cvt_pk_bf16_f32 v40, v44, v45
	v_cvt_pk_bf16_f32 v41, v46, v47
	s_waitcnt vmcnt(6)
	v_lshlrev_b32_e32 v44, 16, v80
	v_and_b32_e32 v45, 0xffff0000, v80
	v_lshlrev_b32_e32 v46, 16, v81
	v_and_b32_e32 v47, 0xffff0000, v81
	v_cvt_pk_bf16_f32 v42, v42, v43
	v_cvt_pk_bf16_f32 v43, v48, v49
	v_lshlrev_b32_e32 v48, 16, v82
	v_and_b32_e32 v49, 0xffff0000, v82
	v_pk_add_f32 v[38:39], v[38:39], v[46:47]
	v_pk_add_f32 v[36:37], v[36:37], v[44:45]
	v_pk_add_f32 v[46:47], v[32:33], v[48:49]
	v_mul_f32_e32 v32, v37, v37
	v_mul_f32_e32 v33, v39, v39
	v_fmac_f32_e32 v32, v36, v36
	v_fmac_f32_e32 v33, v38, v38
	v_lshlrev_b32_e32 v50, 16, v83
	v_and_b32_e32 v51, 0xffff0000, v83
	v_add_f32_e32 v32, v32, v33
	v_mul_f32_e32 v33, v47, v47
	v_pk_add_f32 v[44:45], v[34:35], v[50:51]
	v_fmac_f32_e32 v33, v46, v46
	v_add_f32_e32 v32, v33, v32
	v_mul_f32_e32 v33, v45, v45
	v_fmac_f32_e32 v33, v44, v44
	v_add_f32_e32 v32, v33, v32
	v_add_f32_e32 v35, v52, v32
	ds_bpermute_b32 v50, v186, v35
	v_lshl_add_u64 v[32:33], s[14:15], 0, v[98:99]
	v_lshl_add_u64 v[48:49], v[168:169], 1, v[32:33]
	ds_bpermute_b32 v240, v253, v40
	ds_bpermute_b32 v241, v253, v41
	ds_bpermute_b32 v242, v253, v42
	ds_bpermute_b32 v243, v253, v43
	v_lshl_add_u64 v[236:237], v[48:49], 0, v[250:251]
	s_waitcnt lgkmcnt(4)
	global_store_dwordx4 v[238:239], v[244:247], off offset:256
	v_cvt_pk_bf16_f32 v34, v36, v37
	s_waitcnt lgkmcnt(0)
	v_add_f32_e32 v32, v35, v50
	ds_bpermute_b32 v33, v187, v32
	v_cvt_pk_bf16_f32 v35, v38, v39
	v_cvt_pk_bf16_f32 v36, v46, v47
	v_cvt_pk_bf16_f32 v37, v44, v45
	ds_bpermute_b32 v244, v253, v34
	ds_bpermute_b32 v245, v253, v35
	ds_bpermute_b32 v246, v253, v36
	ds_bpermute_b32 v247, v253, v37
	v_lshl_add_u64 v[238:239], v[48:49], 0, v[250:251]
	s_waitcnt lgkmcnt(4)
	global_store_dwordx4 v[236:237], v[240:243], off
	s_and_saveexec_b64 s[36:37], s[4:5]
	s_cbranch_execz .LBB0_1230
	v_lshlrev_b64 v[34:35], 6, v[96:97]
	v_lshl_add_u64 v[34:35], s[16:17], 0, v[34:35]
	v_lshl_add_u64 v[34:35], s[34:35], 2, v[34:35]
	s_lshl_b32 s8, s48, 2
	v_lshl_add_u64 v[34:35], v[34:35], 0, s[8:9]
	s_waitcnt lgkmcnt(0)
	v_add_f32_e32 v32, v32, v33
	global_store_dword v[34:35], v32, off
; __device__ __forceinline__ unsigned cvt_pk_bf16(float lo, float hi) { unsigned r; asm volatile("v_cvt_pk_bf16_f32 %0, %1, %2" : "=v"(r) : "v"(lo), "v"(hi)); return r; }
;     __device__ __forceinline__ void operator()(const f32x4 (&acc)[2][2][4][2], const Unit& u, int wr, int wc, int fr, int fq) const {
;     ...
;             for (int m = 0; m < 4; ++m) {
;                 const int row = row0 + ai * HALF + m * 16; const size_t off = (size_t)row * 1024 + col0;
;                 float ss = 0.f;
; #pragma unroll
;                 for (int bj = 0; bj < 2; ++bj) {
;                     f32x4 b0, b1;
;                     if (BASE_BF16) { const u32x4 w = bw[m][bj];
;                         b0 = (f32x4){__builtin_bit_cast(float, w.x << 16), __builtin_bit_cast(float, w.x & 0xffff0000u), __builtin_bit_cast(float, w.y << 16), __builtin_bit_cast(float, w.y & 0xffff0000u)};
;                         b1 = (f32x4){__builtin_bit_cast(float, w.z << 16), __builtin_bit_cast(float, w.z & 0xffff0000u), __builtin_bit_cast(float, w.w << 16), __builtin_bit_cast(float, w.w & 0xffff0000u)}; }
;                     else { b0 = bf[m][bj][0]; b1 = bf[m][bj][1]; }
;                     const f32x4 v0 = acc[ai][bj][m][0] + b0, v1 = acc[ai][bj][m][1] + b1;
;                     ss += (v0[0] * v0[0] + v0[1] * v0[1]) + (v0[2] * v0[2] + v0[3] * v0[3]) + (v1[0] * v1[0] + v1[1] * v1[1]) + (v1[2] * v1[2] + v1[3] * v1[3]);
;                     if (OUT_BF16) { u32x4 w; w.x = cvt_pk_bf16(v0[0], v0[1]); w.y = cvt_pk_bf16(v0[2], v0[3]); w.z = cvt_pk_bf16(v1[0], v1[1]); w.w = cvt_pk_bf16(v1[2], v1[3]);
;                         *(u32x4*)((bf16_t*)out + off + bj * HALF) = w; }
;                     else { *(f32x4*)((float*)out + off + bj * HALF) = v0; *(f32x4*)((float*)out + off + bj * HALF + 4) = v1; }
;                 }
;                 ss += __shfl_xor(ss, 16); ss += __shfl_xor(ss, 32);
;                 if (fq == 0) sspart[(size_t)row * 16 + u.pn * 4 + wc] = ss;
.LBB0_1230:
	s_or_b64 exec, exec, s[36:37]
	s_waitcnt vmcnt(7)
	v_lshlrev_b32_e32 v32, 16, v76
	s_waitcnt lgkmcnt(0)
	v_and_b32_e32 v33, 0xffff0000, v76
	v_lshlrev_b32_e32 v34, 16, v77
	v_and_b32_e32 v35, 0xffff0000, v77
	v_lshlrev_b32_e32 v36, 16, v78
	v_and_b32_e32 v37, 0xffff0000, v78
	v_lshlrev_b32_e32 v38, 16, v79
	v_and_b32_e32 v39, 0xffff0000, v79
	v_pk_add_f32 v[30:31], v[30:31], v[34:35]
	v_pk_add_f32 v[28:29], v[28:29], v[32:33]
	v_pk_add_f32 v[32:33], v[26:27], v[38:39]
	v_pk_add_f32 v[26:27], v[24:25], v[36:37]
	v_mul_f32_e32 v24, v29, v29
	v_mul_f32_e32 v25, v31, v31
	v_fmac_f32_e32 v24, v28, v28
	v_fmac_f32_e32 v25, v30, v30
	v_add_f32_e32 v24, v24, v25
	v_mul_f32_e32 v25, v27, v27
	v_fmac_f32_e32 v25, v26, v26
	v_add_f32_e32 v24, v25, v24
	v_mul_f32_e32 v25, v33, v33
	v_fmac_f32_e32 v25, v32, v32
	v_add_f32_e32 v36, v25, v24
	v_cvt_pk_bf16_f32 v24, v28, v29
	v_cvt_pk_bf16_f32 v25, v30, v31
	s_waitcnt vmcnt(6)
	v_lshlrev_b32_e32 v28, 16, v72
	v_and_b32_e32 v29, 0xffff0000, v72
	v_lshlrev_b32_e32 v30, 16, v73
	v_and_b32_e32 v31, 0xffff0000, v73
	v_cvt_pk_bf16_f32 v26, v26, v27
	v_cvt_pk_bf16_f32 v27, v32, v33
	v_lshlrev_b32_e32 v32, 16, v74
	v_and_b32_e32 v33, 0xffff0000, v74
	v_pk_add_f32 v[22:23], v[22:23], v[30:31]
	v_pk_add_f32 v[20:21], v[20:21], v[28:29]
	v_pk_add_f32 v[30:31], v[16:17], v[32:33]
	v_mul_f32_e32 v16, v21, v21
	v_mul_f32_e32 v17, v23, v23
	v_fmac_f32_e32 v16, v20, v20
	v_fmac_f32_e32 v17, v22, v22
	v_lshlrev_b32_e32 v34, 16, v75
	v_and_b32_e32 v35, 0xffff0000, v75
	v_add_f32_e32 v16, v16, v17
	v_mul_f32_e32 v17, v31, v31
	v_pk_add_f32 v[28:29], v[18:19], v[34:35]
	v_fmac_f32_e32 v17, v30, v30
	v_add_f32_e32 v16, v17, v16
	v_mul_f32_e32 v17, v29, v29
	v_fmac_f32_e32 v17, v28, v28
	v_add_f32_e32 v16, v17, v16
	v_add_f32_e32 v19, v36, v16
	ds_bpermute_b32 v34, v186, v19
	v_lshl_add_u64 v[16:17], s[14:15], 0, v[94:95]
	v_lshl_add_u64 v[32:33], v[168:169], 1, v[16:17]
	ds_bpermute_b32 v240, v253, v24
	ds_bpermute_b32 v241, v253, v25
	ds_bpermute_b32 v242, v253, v26
	ds_bpermute_b32 v243, v253, v27
	v_lshl_add_u64 v[236:237], v[32:33], 0, v[250:251]
	s_waitcnt lgkmcnt(4)
	global_store_dwordx4 v[238:239], v[244:247], off offset:256
	v_cvt_pk_bf16_f32 v18, v20, v21
	s_waitcnt lgkmcnt(0)
	v_add_f32_e32 v16, v19, v34
	ds_bpermute_b32 v17, v187, v16
	v_cvt_pk_bf16_f32 v19, v22, v23
	v_cvt_pk_bf16_f32 v20, v30, v31
	v_cvt_pk_bf16_f32 v21, v28, v29
	ds_bpermute_b32 v244, v253, v18
	ds_bpermute_b32 v245, v253, v19
	ds_bpermute_b32 v246, v253, v20
	ds_bpermute_b32 v247, v253, v21
	v_lshl_add_u64 v[238:239], v[32:33], 0, v[250:251]
	s_waitcnt lgkmcnt(4)
	global_store_dwordx4 v[236:237], v[240:243], off
	s_and_saveexec_b64 s[36:37], s[4:5]
	s_cbranch_execz .LBB0_1232
	v_lshlrev_b64 v[18:19], 6, v[92:93]
	v_lshl_add_u64 v[18:19], s[16:17], 0, v[18:19]
	v_lshl_add_u64 v[18:19], s[34:35], 2, v[18:19]
	s_lshl_b32 s8, s48, 2
	v_lshl_add_u64 v[18:19], v[18:19], 0, s[8:9]
	s_waitcnt lgkmcnt(0)
	v_add_f32_e32 v16, v16, v17
	global_store_dword v[18:19], v16, off
.LBB0_1232:
	s_or_b64 exec, exec, s[36:37]
	s_waitcnt vmcnt(7)
	v_lshlrev_b32_e32 v16, 16, v68
	s_waitcnt lgkmcnt(0)
	v_and_b32_e32 v17, 0xffff0000, v68
	v_lshlrev_b32_e32 v18, 16, v69
	v_and_b32_e32 v19, 0xffff0000, v69
	v_lshlrev_b32_e32 v20, 16, v70
	v_and_b32_e32 v21, 0xffff0000, v70
	v_lshlrev_b32_e32 v22, 16, v71
	v_and_b32_e32 v23, 0xffff0000, v71
	v_pk_add_f32 v[14:15], v[14:15], v[18:19]
	v_pk_add_f32 v[12:13], v[12:13], v[16:17]
	v_pk_add_f32 v[16:17], v[10:11], v[22:23]
	v_pk_add_f32 v[10:11], v[8:9], v[20:21]
	v_mul_f32_e32 v8, v13, v13
	v_mul_f32_e32 v9, v15, v15
	v_fmac_f32_e32 v8, v12, v12
	v_fmac_f32_e32 v9, v14, v14
	v_add_f32_e32 v8, v8, v9
	v_mul_f32_e32 v9, v11, v11
	v_fmac_f32_e32 v9, v10, v10
	v_add_f32_e32 v8, v9, v8
	v_mul_f32_e32 v9, v17, v17
	v_fmac_f32_e32 v9, v16, v16
	v_add_f32_e32 v20, v9, v8
	v_cvt_pk_bf16_f32 v8, v12, v13
	v_cvt_pk_bf16_f32 v9, v14, v15
	s_waitcnt vmcnt(6)
	v_lshlrev_b32_e32 v12, 16, v64
	v_and_b32_e32 v13, 0xffff0000, v64
	v_lshlrev_b32_e32 v14, 16, v65
	v_and_b32_e32 v15, 0xffff0000, v65
	v_cvt_pk_bf16_f32 v10, v10, v11
	v_cvt_pk_bf16_f32 v11, v16, v17
	v_lshlrev_b32_e32 v16, 16, v66
	v_and_b32_e32 v17, 0xffff0000, v66
	v_pk_add_f32 v[6:7], v[6:7], v[14:15]
	v_pk_add_f32 v[4:5], v[4:5], v[12:13]
	v_pk_add_f32 v[14:15], v[0:1], v[16:17]
	v_mul_f32_e32 v0, v5, v5
	v_mul_f32_e32 v1, v7, v7
	v_fmac_f32_e32 v0, v4, v4
	v_fmac_f32_e32 v1, v6, v6
	v_lshlrev_b32_e32 v18, 16, v67
	v_and_b32_e32 v19, 0xffff0000, v67
	v_add_f32_e32 v0, v0, v1
	v_mul_f32_e32 v1, v15, v15
	v_pk_add_f32 v[12:13], v[2:3], v[18:19]
	v_fmac_f32_e32 v1, v14, v14
	v_add_f32_e32 v0, v1, v0
	v_mul_f32_e32 v1, v13, v13
	v_fmac_f32_e32 v1, v12, v12
	v_add_f32_e32 v0, v1, v0
	v_add_f32_e32 v3, v20, v0
	ds_bpermute_b32 v18, v186, v3
	v_lshl_add_u64 v[0:1], s[14:15], 0, v[90:91]
	v_lshl_add_u64 v[16:17], v[168:169], 1, v[0:1]
	ds_bpermute_b32 v240, v253, v8
	ds_bpermute_b32 v241, v253, v9
	ds_bpermute_b32 v242, v253, v10
	ds_bpermute_b32 v243, v253, v11
	v_lshl_add_u64 v[236:237], v[16:17], 0, v[250:251]
	s_waitcnt lgkmcnt(4)
	global_store_dwordx4 v[238:239], v[244:247], off offset:256
	v_cvt_pk_bf16_f32 v2, v4, v5
	s_waitcnt lgkmcnt(0)
	v_add_f32_e32 v0, v3, v18
	ds_bpermute_b32 v1, v187, v0
	v_cvt_pk_bf16_f32 v3, v6, v7
	v_cvt_pk_bf16_f32 v4, v14, v15
	v_cvt_pk_bf16_f32 v5, v12, v13
	ds_bpermute_b32 v244, v253, v2
	ds_bpermute_b32 v245, v253, v3
	ds_bpermute_b32 v246, v253, v4
	ds_bpermute_b32 v247, v253, v5
	v_lshl_add_u64 v[238:239], v[16:17], 0, v[250:251]
	s_waitcnt lgkmcnt(4)
	global_store_dwordx4 v[236:237], v[240:243], off
	s_waitcnt lgkmcnt(0)
	global_store_dwordx4 v[238:239], v[244:247], off offset:256
	s_and_saveexec_b64 s[36:37], s[4:5]
	s_cbranch_execz .LBB0_1234
	v_lshlrev_b64 v[2:3], 6, v[88:89]
	v_lshl_add_u64 v[2:3], s[16:17], 0, v[2:3]
	v_lshl_add_u64 v[2:3], s[34:35], 2, v[2:3]
	s_lshl_b32 s8, s48, 2
	v_lshl_add_u64 v[2:3], v[2:3], 0, s[8:9]
	s_waitcnt lgkmcnt(0)
	v_add_f32_e32 v0, v0, v1
	global_store_dword v[2:3], v0, off

; __device__ __forceinline__ int mk_lane() { int l = (int)__builtin_amdgcn_mbcnt_hi(~0u, __builtin_amdgcn_mbcnt_lo(~0u, 0u)); asm volatile("" : "+v"(l)); return l; }
; #define LAS __attribute__((address_space(3)))
; #define PH(k) (IN(k) && ((MK_MASK >> (k)) & 1))
; #define REPS(k) for (int rep_ = 0; rep_ < (((MK_REP_MASK) >> (k)) & 1) + 1; ++rep_)
; template <class Sched> __device__ __forceinline__ void build_rstd_tables(LAS unsigned char* lds, const Sched& S, const float* sspart, float eps, int wave) {
;     const int lane = mk_lane(), tid = wave * 64 + lane;
;     LAS int* pml = (LAS int*)(lds + RING_BYTES + 1536); LAS float* tab = (LAS float*)(lds + RING_BYTES + 2048);
;     if (tid == 0) { int n = 0; pg8::Unit u; for (int i = 0; S.next(i, u); ++i) { bool f = false; for (int j = 0; j < n; ++j) f |= (pml[j] == u.pm); if (!f && n < 8) pml[n++] = u.pm; } pml[8] = n; }
; __global__ void __launch_bounds__(NWAVES * 64, 2) mk_fwd(Params P) {
;     ...
;     if (PH(8)) REPS(8) { pg8::Gemm g{H2B, Wup_t, M, FF, D}; pg8::StaticOrder S; S.init(M, FF, G, bx);
;         build_rstd_tables(lds, S, SS2, EPS, wave);
.LBB0_1290:
	s_cmp_lt_i32 s74, 9
	s_cselect_b64 s[0:1], -1, 0
	s_and_b64 s[36:37], s[0:1], s[4:5]
	s_andn2_b64 vcc, exec, s[36:37]
	s_cbranch_vccnz .LBB0_1388
	v_and_b32_e32 v248, 15, v212
	v_lshrrev_b32_e32 v249, 2, v212
	v_sub_u32_e32 v249, v249, v248
	v_lshrrev_b32_e32 v248, 4, v212
	v_and_b32_e32 v253, 3, v212
	v_sub_u32_e32 v248, v253, v248
	v_lshlrev_b32_e32 v248, 4, v248
	v_mul_i32_i24_e32 v250, 0x2000, v249
	v_add_u32_e32 v250, v250, v248
	v_ashrrev_i32_e32 v251, 31, v250
	v_lshlrev_b32_e32 v253, 4, v253
	v_lshrrev_b32_e32 v248, 2, v212
	v_add_u32_e32 v253, v253, v248
	v_lshlrev_b32_e32 v253, 2, v253
	s_and_b32 s20, s93, 0xffffffc0
	v_mov_b32_e32 v3, v212
	s_ashr_i32 s2, s82, 31
	v_add_u32_e32 v2, s20, v3
	s_ashr_i32 s3, s88, 31
	s_mov_b32 s21, 0
	v_cmp_eq_u32_e32 vcc, 0, v2
	s_and_saveexec_b64 s[38:39], vcc
	s_cbranch_execz .LBB0_1317
	s_waitcnt lgkmcnt(0)
	v_mov_b64_e32 v[0:1], 0x7ff
	s_add_i32 s33, 0, 0x20600
	s_mov_b32 s1, 0
	s_branch .LBB0_1295

; __device__ __forceinline__ unsigned cvt_pk_bf16(float lo, float hi) { unsigned r; asm volatile("v_cvt_pk_bf16_f32 %0, %1, %2" : "=v"(r) : "v"(lo), "v"(hi)); return r; }
; __device__ __forceinline__ float row_rstd(const float* part, int row, float eps) {
;     const f32x4* p = (const f32x4*)(part + (size_t)row * 16);
;     const f32x4 a = p[0], b = p[1], c = p[2], d = p[3];
;     const float s = ((a[0] + a[1]) + (a[2] + a[3])) + ((b[0] + b[1]) + (b[2] + b[3])) + ((c[0] + c[1]) + (c[2] + c[3])) + ((d[0] + d[1]) + (d[2] + d[3]));
;     return 1.0f / sqrtf(s * (1.0f / 1024.0f) + eps);
; }
;     __device__ __forceinline__ void operator()(const f32x4 (&acc)[2][2][4][2], const Unit& u, int wr, int wc, int fr, int fq) const {
;     ...
;                 const int row = row0 + ai * HALF + m * 16; bf16_t* rowp = O + (size_t)row * ldc + col0;
;                 const float r = (slot >= 0 ? tab[slot * 256 + (row - u.pm * BM)] : row_rstd(sspart, row, eps)) * sc;
; #pragma unroll
;                 for (int bj = 0; bj < 2; ++bj) {
;                     f32x4 v0 = acc[ai][bj][m][0] * r, v1 = acc[ai][bj][m][1] * r;
;                     if (ACT == 1) {
; #pragma unroll
;                         for (int e = 0; e < 4; ++e) { const float a = fmaxf(v0[e], 0.f), b = fmaxf(v1[e], 0.f); v0[e] = a * a; v1[e] = b * b; }
;                     }
;                     u32x4 w; w.x = cvt_pk_bf16(v0[0], v0[1]); w.y = cvt_pk_bf16(v0[2], v0[3]); w.z = cvt_pk_bf16(v1[0], v1[1]); w.w = cvt_pk_bf16(v1[2], v1[3]);
;                     *(u32x4*)(rowp + bj * HALF) = w;
.LBB0_1356:
	s_waitcnt lgkmcnt(0)
	v_pk_mul_f32 v[120:121], v[120:121], v[148:149] op_sel_hi:[1,0]
	v_pk_mul_f32 v[124:125], v[124:125], v[148:149] op_sel_hi:[1,0]
	v_pk_mul_f32 v[122:123], v[122:123], v[148:149] op_sel_hi:[1,0]
	v_max_f32_e32 v120, 0, v120
	v_lshl_or_b32 v146, s6, 8, v152
	v_lshlrev_b64 v[160:161], 13, v[144:145]
	v_pk_mul_f32 v[126:127], v[126:127], v[148:149] op_sel_hi:[1,0]
	v_mul_f32_e32 v145, v120, v120
	v_max_f32_e32 v120, 0, v125
	v_max_f32_e32 v121, 0, v121
	v_max_f32_e32 v122, 0, v122
	v_ashrrev_i32_e32 v147, 31, v146
	v_lshl_add_u64 v[160:161], s[14:15], 0, v[160:161]
	v_max_f32_e32 v124, 0, v124
	v_mul_f32_e32 v120, v120, v120
	v_mul_f32_e32 v125, v121, v121
	v_max_f32_e32 v121, 0, v126
	v_mul_f32_e32 v126, v122, v122
	v_max_f32_e32 v122, 0, v127
	v_max_f32_e32 v123, 0, v123
	v_pk_mul_f32 v[114:115], v[114:115], v[148:149] op_sel_hi:[1,0]
	v_pk_mul_f32 v[112:113], v[112:113], v[148:149] op_sel_hi:[1,0]
	v_lshl_add_u64 v[160:161], v[146:147], 1, v[160:161]
	v_mul_f32_e32 v124, v124, v124
	v_mul_f32_e32 v121, v121, v121
	v_mul_f32_e32 v122, v122, v122
	v_mul_f32_e32 v123, v123, v123
	v_cvt_pk_bf16_f32 v120, v124, v120
	v_pk_mul_f32 v[118:119], v[118:119], v[148:149] op_sel_hi:[1,0]
	v_pk_mul_f32 v[116:117], v[116:117], v[148:149] op_sel_hi:[1,0]
	v_max_f32_e32 v112, 0, v112
	v_max_f32_e32 v113, 0, v113
	v_max_f32_e32 v114, 0, v114
	v_cvt_pk_bf16_f32 v121, v121, v122
	v_cvt_pk_bf16_f32 v122, v145, v125
	v_cvt_pk_bf16_f32 v123, v126, v123
	ds_bpermute_b32 v240, v253, v120
	ds_bpermute_b32 v241, v253, v121
	ds_bpermute_b32 v242, v253, v122
	ds_bpermute_b32 v243, v253, v123
	v_lshl_add_u64 v[236:237], v[160:161], 0, v[250:251]
	v_max_f32_e32 v116, 0, v116
	v_max_f32_e32 v115, 0, v115
	v_mul_f32_e32 v120, v112, v112
	v_max_f32_e32 v112, 0, v117
	v_mul_f32_e32 v117, v113, v113
	v_max_f32_e32 v113, 0, v118
	v_mul_f32_e32 v118, v114, v114
	v_max_f32_e32 v114, 0, v119
	v_mul_f32_e32 v112, v112, v112
	v_mul_f32_e32 v113, v113, v113
	v_mul_f32_e32 v114, v114, v114
	v_mul_f32_e32 v116, v116, v116
	v_mul_f32_e32 v115, v115, v115
	v_cvt_pk_bf16_f32 v112, v116, v112
	v_cvt_pk_bf16_f32 v113, v113, v114
	v_cvt_pk_bf16_f32 v114, v120, v117
	v_cvt_pk_bf16_f32 v115, v118, v115
	ds_bpermute_b32 v244, v253, v112
	ds_bpermute_b32 v245, v253, v113
	ds_bpermute_b32 v246, v253, v114
	ds_bpermute_b32 v247, v253, v115
	v_lshl_add_u64 v[238:239], v[160:161], 0, v[250:251]
	s_waitcnt lgkmcnt(4)
	global_store_dwordx4 v[236:237], v[240:243], off
	s_andn2_b64 vcc, exec, s[8:9]
	s_mov_b64 s[0:1], -1
	v_or_b32_e32 v112, 16, v144
	v_cndmask_b32_e64 v114, 0, 1, s[8:9]
	v_ashrrev_i32_e32 v113, 31, v112
	v_cmp_ne_u32_e64 s[6:7], 1, v114
	s_cbranch_vccnz .LBB0_1358
	v_lshlrev_b64 v[114:115], 6, v[112:113]
	v_lshl_add_u64 v[126:127], s[10:11], 0, v[114:115]
	global_load_dwordx4 v[114:117], v[126:127], off
	global_load_dwordx4 v[118:121], v[126:127], off offset:16
	global_load_dwordx4 v[122:125], v[126:127], off offset:32
	global_load_dwordx4 v[160:163], v[126:127], off offset:48
	s_waitcnt vmcnt(0)
	v_mov_b32_e32 v126, v115
	v_mov_b32_e32 v127, v116
	v_mov_b32_e32 v115, v117
	v_mov_b32_e32 v116, v119
	v_mov_b32_e32 v117, v120
	v_mov_b32_e32 v119, v121
	v_pk_add_f32 v[114:115], v[126:127], v[114:115]
	v_pk_add_f32 v[116:117], v[116:117], v[118:119]
	v_pk_add_f32 v[114:115], v[114:115], v[114:115] op_sel:[0,1] op_sel_hi:[1,0]
	v_pk_add_f32 v[116:117], v[116:117], v[116:117] op_sel:[0,1] op_sel_hi:[1,0]
	v_add_f32_e32 v120, v122, v123
	v_add_f32_e32 v122, v124, v125
	v_mov_b32_e32 v121, v162
	v_mov_b32_e32 v123, v163
	v_mov_b32_e32 v115, v160
	v_mov_b32_e32 v117, v161
	v_pk_add_f32 v[118:119], v[120:121], v[122:123]
	v_pk_add_f32 v[114:115], v[114:115], v[116:117]
	s_nop 0
	v_pk_add_f32 v[114:115], v[114:115], v[118:119]
	s_nop 0
	v_add_f32_e32 v114, v114, v115
	v_fmamk_f32 v114, v114, 0x3a800000, v156
	v_mul_f32_e32 v115, 0x4f800000, v114
	v_cmp_gt_f32_e32 vcc, s55, v114
	s_nop 1
	v_cndmask_b32_e32 v114, v114, v115, vcc
	v_sqrt_f32_e32 v115, v114
	s_nop 0
	v_add_u32_e32 v116, -1, v115
	v_add_u32_e32 v117, 1, v115
	v_fma_f32 v118, -v116, v115, v114
	v_fma_f32 v119, -v117, v115, v114
	v_cmp_ge_f32_e64 s[0:1], 0, v118
	s_nop 1
	v_cndmask_b32_e64 v115, v115, v116, s[0:1]
	v_cmp_lt_f32_e64 s[0:1], 0, v119
	s_nop 1
	v_cndmask_b32_e64 v115, v115, v117, s[0:1]
	v_mul_f32_e32 v116, 0x37800000, v115
	v_cndmask_b32_e32 v115, v115, v116, vcc
	v_cmp_class_f32_e32 vcc, v114, v157
	s_nop 1
	v_cndmask_b32_e32 v114, v115, v114, vcc
	v_div_scale_f32 v115, s[0:1], v114, v114, 1.0
	v_rcp_f32_e32 v116, v115
	v_div_scale_f32 v117, vcc, 1.0, v114, 1.0
	s_mov_b64 s[0:1], 0
	v_fma_f32 v118, -v115, v116, 1.0
	v_fmac_f32_e32 v116, v118, v116
	v_mul_f32_e32 v118, v117, v116
	v_fma_f32 v119, -v115, v118, v117
	v_fmac_f32_e32 v118, v119, v116
	v_fma_f32 v115, -v115, v118, v117
	v_div_fmas_f32 v115, v115, v116, v118
	v_div_fixup_f32 v114, v115, v114, 1.0

; __device__ __forceinline__ unsigned cvt_pk_bf16(float lo, float hi) { unsigned r; asm volatile("v_cvt_pk_bf16_f32 %0, %1, %2" : "=v"(r) : "v"(lo), "v"(hi)); return r; }
; __device__ __forceinline__ float row_rstd(const float* part, int row, float eps) {
;     const f32x4* p = (const f32x4*)(part + (size_t)row * 16);
;     const f32x4 a = p[0], b = p[1], c = p[2], d = p[3];
;     const float s = ((a[0] + a[1]) + (a[2] + a[3])) + ((b[0] + b[1]) + (b[2] + b[3])) + ((c[0] + c[1]) + (c[2] + c[3])) + ((d[0] + d[1]) + (d[2] + d[3]));
;     return 1.0f / sqrtf(s * (1.0f / 1024.0f) + eps);
; }
;     __device__ __forceinline__ void operator()(const f32x4 (&acc)[2][2][4][2], const Unit& u, int wr, int wc, int fr, int fq) const {
;     ...
;                 const int row = row0 + ai * HALF + m * 16; bf16_t* rowp = O + (size_t)row * ldc + col0;
;                 const float r = (slot >= 0 ? tab[slot * 256 + (row - u.pm * BM)] : row_rstd(sspart, row, eps)) * sc;
; #pragma unroll
;                 for (int bj = 0; bj < 2; ++bj) {
;                     f32x4 v0 = acc[ai][bj][m][0] * r, v1 = acc[ai][bj][m][1] * r;
;                     if (ACT == 1) {
; #pragma unroll
;                         for (int e = 0; e < 4; ++e) { const float a = fmaxf(v0[e], 0.f), b = fmaxf(v1[e], 0.f); v0[e] = a * a; v1[e] = b * b; }
;                     }
;                     u32x4 w; w.x = cvt_pk_bf16(v0[0], v0[1]); w.y = cvt_pk_bf16(v0[2], v0[3]); w.z = cvt_pk_bf16(v1[0], v1[1]); w.w = cvt_pk_bf16(v1[2], v1[3]);
;                     *(u32x4*)(rowp + bj * HALF) = w;
.LBB0_1360:
	s_waitcnt lgkmcnt(0)
	v_pk_mul_f32 v[104:105], v[104:105], v[114:115] op_sel_hi:[1,0]
	v_pk_mul_f32 v[108:109], v[108:109], v[114:115] op_sel_hi:[1,0]
	v_pk_mul_f32 v[106:107], v[106:107], v[114:115] op_sel_hi:[1,0]
	v_max_f32_e32 v104, 0, v104
	v_lshlrev_b64 v[112:113], 13, v[112:113]
	v_pk_mul_f32 v[110:111], v[110:111], v[114:115] op_sel_hi:[1,0]
	v_mul_f32_e32 v115, v104, v104
	v_max_f32_e32 v104, 0, v109
	v_max_f32_e32 v105, 0, v105
	v_max_f32_e32 v106, 0, v106
	v_lshl_add_u64 v[112:113], s[14:15], 0, v[112:113]
	v_max_f32_e32 v108, 0, v108
	v_mul_f32_e32 v104, v104, v104
	v_mul_f32_e32 v109, v105, v105
	v_max_f32_e32 v105, 0, v110
	v_mul_f32_e32 v110, v106, v106
	v_max_f32_e32 v106, 0, v111
	v_max_f32_e32 v107, 0, v107
	v_pk_mul_f32 v[96:97], v[96:97], v[114:115] op_sel_hi:[1,0]
	v_lshl_add_u64 v[112:113], v[146:147], 1, v[112:113]
	v_mul_f32_e32 v108, v108, v108
	v_mul_f32_e32 v105, v105, v105
	v_mul_f32_e32 v106, v106, v106
	v_mul_f32_e32 v107, v107, v107
	v_cvt_pk_bf16_f32 v104, v108, v104
	v_pk_mul_f32 v[100:101], v[100:101], v[114:115] op_sel_hi:[1,0]
	v_pk_mul_f32 v[98:99], v[98:99], v[114:115] op_sel_hi:[1,0]
	v_max_f32_e32 v96, 0, v96
	v_cvt_pk_bf16_f32 v105, v105, v106
	v_cvt_pk_bf16_f32 v106, v115, v109
	v_cvt_pk_bf16_f32 v107, v110, v107
	ds_bpermute_b32 v240, v253, v104
	ds_bpermute_b32 v241, v253, v105
	ds_bpermute_b32 v242, v253, v106
	ds_bpermute_b32 v243, v253, v107
	v_lshl_add_u64 v[236:237], v[112:113], 0, v[250:251]
	s_waitcnt lgkmcnt(4)
	global_store_dwordx4 v[238:239], v[244:247], off offset:256
	v_pk_mul_f32 v[102:103], v[102:103], v[114:115] op_sel_hi:[1,0]
	v_max_f32_e32 v97, 0, v97
	v_mul_f32_e32 v104, v96, v96
	v_max_f32_e32 v96, 0, v101
	v_max_f32_e32 v98, 0, v98
	v_max_f32_e32 v100, 0, v100
	v_mul_f32_e32 v96, v96, v96
	v_mul_f32_e32 v101, v97, v97
	v_max_f32_e32 v97, 0, v102
	v_mul_f32_e32 v102, v98, v98
	v_max_f32_e32 v98, 0, v103
	v_max_f32_e32 v99, 0, v99
	v_mul_f32_e32 v100, v100, v100
	v_mul_f32_e32 v97, v97, v97
	v_mul_f32_e32 v98, v98, v98
	v_mul_f32_e32 v99, v99, v99
	v_cvt_pk_bf16_f32 v96, v100, v96
	v_cvt_pk_bf16_f32 v97, v97, v98
	v_cvt_pk_bf16_f32 v98, v104, v101
	v_cvt_pk_bf16_f32 v99, v102, v99
	ds_bpermute_b32 v244, v253, v96
	ds_bpermute_b32 v245, v253, v97
	ds_bpermute_b32 v246, v253, v98
	ds_bpermute_b32 v247, v253, v99
	v_lshl_add_u64 v[238:239], v[112:113], 0, v[250:251]
	s_waitcnt lgkmcnt(4)
	global_store_dwordx4 v[236:237], v[240:243], off
	s_and_b64 vcc, exec, s[6:7]
	s_mov_b64 s[0:1], -1
	v_or_b32_e32 v96, 32, v144
	v_ashrrev_i32_e32 v97, 31, v96
	s_cbranch_vccnz .LBB0_1362
	v_lshlrev_b64 v[98:99], 6, v[96:97]
	v_lshl_add_u64 v[110:111], s[10:11], 0, v[98:99]
	global_load_dwordx4 v[98:101], v[110:111], off
	global_load_dwordx4 v[102:105], v[110:111], off offset:16
	global_load_dwordx4 v[106:109], v[110:111], off offset:32
	s_nop 0
	global_load_dwordx4 v[110:113], v[110:111], off offset:48
	s_waitcnt vmcnt(0)
	v_mov_b32_e32 v114, v99
	v_mov_b32_e32 v115, v100
	v_mov_b32_e32 v99, v101
	v_mov_b32_e32 v100, v103
	v_mov_b32_e32 v101, v104
	v_mov_b32_e32 v103, v105
	v_pk_add_f32 v[98:99], v[114:115], v[98:99]
	v_pk_add_f32 v[100:101], v[100:101], v[102:103]
	v_pk_add_f32 v[98:99], v[98:99], v[98:99] op_sel:[0,1] op_sel_hi:[1,0]
	v_pk_add_f32 v[100:101], v[100:101], v[100:101] op_sel:[0,1] op_sel_hi:[1,0]
	v_add_f32_e32 v104, v106, v107
	v_add_f32_e32 v106, v108, v109
	v_mov_b32_e32 v105, v112
	v_mov_b32_e32 v107, v113
	v_mov_b32_e32 v99, v110
	v_mov_b32_e32 v101, v111
	v_pk_add_f32 v[102:103], v[104:105], v[106:107]
	v_pk_add_f32 v[98:99], v[98:99], v[100:101]
	s_nop 0
	v_pk_add_f32 v[98:99], v[98:99], v[102:103]
	s_nop 0
	v_add_f32_e32 v98, v98, v99
	v_fmamk_f32 v98, v98, 0x3a800000, v156
	v_mul_f32_e32 v99, 0x4f800000, v98
	v_cmp_gt_f32_e32 vcc, s55, v98
	s_nop 1
	v_cndmask_b32_e32 v98, v98, v99, vcc
	v_sqrt_f32_e32 v99, v98
	s_nop 0
	v_add_u32_e32 v100, -1, v99
	v_add_u32_e32 v101, 1, v99
	v_fma_f32 v102, -v100, v99, v98
	v_fma_f32 v103, -v101, v99, v98
	v_cmp_ge_f32_e64 s[0:1], 0, v102
	s_nop 1
	v_cndmask_b32_e64 v99, v99, v100, s[0:1]
	v_cmp_lt_f32_e64 s[0:1], 0, v103
	s_nop 1
	v_cndmask_b32_e64 v99, v99, v101, s[0:1]
	v_mul_f32_e32 v100, 0x37800000, v99
	v_cndmask_b32_e32 v99, v99, v100, vcc
	v_cmp_class_f32_e32 vcc, v98, v157
	s_nop 1
	v_cndmask_b32_e32 v98, v99, v98, vcc
	v_div_scale_f32 v99, s[0:1], v98, v98, 1.0
	v_rcp_f32_e32 v100, v99
	v_div_scale_f32 v101, vcc, 1.0, v98, 1.0
	s_mov_b64 s[0:1], 0
	v_fma_f32 v102, -v99, v100, 1.0
	v_fmac_f32_e32 v100, v102, v100
	v_mul_f32_e32 v102, v101, v100
	v_fma_f32 v103, -v99, v102, v101
	v_fmac_f32_e32 v102, v103, v100
	v_fma_f32 v99, -v99, v102, v101
	v_div_fmas_f32 v99, v99, v100, v102
	v_div_fixup_f32 v98, v99, v98, 1.0

; __device__ __forceinline__ unsigned cvt_pk_bf16(float lo, float hi) { unsigned r; asm volatile("v_cvt_pk_bf16_f32 %0, %1, %2" : "=v"(r) : "v"(lo), "v"(hi)); return r; }
; __device__ __forceinline__ float row_rstd(const float* part, int row, float eps) {
;     const f32x4* p = (const f32x4*)(part + (size_t)row * 16);
;     const f32x4 a = p[0], b = p[1], c = p[2], d = p[3];
;     const float s = ((a[0] + a[1]) + (a[2] + a[3])) + ((b[0] + b[1]) + (b[2] + b[3])) + ((c[0] + c[1]) + (c[2] + c[3])) + ((d[0] + d[1]) + (d[2] + d[3]));
;     return 1.0f / sqrtf(s * (1.0f / 1024.0f) + eps);
; }
;     __device__ __forceinline__ void operator()(const f32x4 (&acc)[2][2][4][2], const Unit& u, int wr, int wc, int fr, int fq) const {
;     ...
;                 const int row = row0 + ai * HALF + m * 16; bf16_t* rowp = O + (size_t)row * ldc + col0;
;                 const float r = (slot >= 0 ? tab[slot * 256 + (row - u.pm * BM)] : row_rstd(sspart, row, eps)) * sc;
; #pragma unroll
;                 for (int bj = 0; bj < 2; ++bj) {
;                     f32x4 v0 = acc[ai][bj][m][0] * r, v1 = acc[ai][bj][m][1] * r;
;                     if (ACT == 1) {
; #pragma unroll
;                         for (int e = 0; e < 4; ++e) { const float a = fmaxf(v0[e], 0.f), b = fmaxf(v1[e], 0.f); v0[e] = a * a; v1[e] = b * b; }
;                     }
;                     u32x4 w; w.x = cvt_pk_bf16(v0[0], v0[1]); w.y = cvt_pk_bf16(v0[2], v0[3]); w.z = cvt_pk_bf16(v1[0], v1[1]); w.w = cvt_pk_bf16(v1[2], v1[3]);
;                     *(u32x4*)(rowp + bj * HALF) = w;
.LBB0_1364:
	s_waitcnt lgkmcnt(0)
	v_pk_mul_f32 v[88:89], v[88:89], v[98:99] op_sel_hi:[1,0]
	v_pk_mul_f32 v[92:93], v[92:93], v[98:99] op_sel_hi:[1,0]
	v_pk_mul_f32 v[90:91], v[90:91], v[98:99] op_sel_hi:[1,0]
	v_max_f32_e32 v88, 0, v88
	v_lshlrev_b64 v[96:97], 13, v[96:97]
	v_pk_mul_f32 v[94:95], v[94:95], v[98:99] op_sel_hi:[1,0]
	v_mul_f32_e32 v99, v88, v88
	v_max_f32_e32 v88, 0, v93
	v_max_f32_e32 v89, 0, v89
	v_max_f32_e32 v90, 0, v90
	v_lshl_add_u64 v[96:97], s[14:15], 0, v[96:97]
	v_max_f32_e32 v92, 0, v92
	v_mul_f32_e32 v88, v88, v88
	v_mul_f32_e32 v93, v89, v89
	v_max_f32_e32 v89, 0, v94
	v_mul_f32_e32 v94, v90, v90
	v_max_f32_e32 v90, 0, v95
	v_max_f32_e32 v91, 0, v91
	v_pk_mul_f32 v[80:81], v[80:81], v[98:99] op_sel_hi:[1,0]
	v_lshl_add_u64 v[96:97], v[146:147], 1, v[96:97]
	v_mul_f32_e32 v92, v92, v92
	v_mul_f32_e32 v89, v89, v89
	v_mul_f32_e32 v90, v90, v90
	v_mul_f32_e32 v91, v91, v91
	v_cvt_pk_bf16_f32 v88, v92, v88
	v_pk_mul_f32 v[84:85], v[84:85], v[98:99] op_sel_hi:[1,0]
	v_pk_mul_f32 v[82:83], v[82:83], v[98:99] op_sel_hi:[1,0]
	v_max_f32_e32 v80, 0, v80
	v_cvt_pk_bf16_f32 v89, v89, v90
	v_cvt_pk_bf16_f32 v90, v99, v93
	v_cvt_pk_bf16_f32 v91, v94, v91
	ds_bpermute_b32 v240, v253, v88
	ds_bpermute_b32 v241, v253, v89
	ds_bpermute_b32 v242, v253, v90
	ds_bpermute_b32 v243, v253, v91
	v_lshl_add_u64 v[236:237], v[96:97], 0, v[250:251]
	s_waitcnt lgkmcnt(4)
	global_store_dwordx4 v[238:239], v[244:247], off offset:256
	v_pk_mul_f32 v[86:87], v[86:87], v[98:99] op_sel_hi:[1,0]
	v_max_f32_e32 v81, 0, v81
	v_mul_f32_e32 v88, v80, v80
	v_max_f32_e32 v80, 0, v85
	v_max_f32_e32 v82, 0, v82
	v_max_f32_e32 v84, 0, v84
	v_mul_f32_e32 v80, v80, v80
	v_mul_f32_e32 v85, v81, v81
	v_max_f32_e32 v81, 0, v86
	v_mul_f32_e32 v86, v82, v82
	v_max_f32_e32 v82, 0, v87
	v_max_f32_e32 v83, 0, v83
	v_mul_f32_e32 v84, v84, v84
	v_mul_f32_e32 v81, v81, v81
	v_mul_f32_e32 v82, v82, v82
	v_mul_f32_e32 v83, v83, v83
	v_cvt_pk_bf16_f32 v80, v84, v80
	v_cvt_pk_bf16_f32 v81, v81, v82
	v_cvt_pk_bf16_f32 v82, v88, v85
	v_cvt_pk_bf16_f32 v83, v86, v83
	ds_bpermute_b32 v244, v253, v80
	ds_bpermute_b32 v245, v253, v81
	ds_bpermute_b32 v246, v253, v82
	ds_bpermute_b32 v247, v253, v83
	v_lshl_add_u64 v[238:239], v[96:97], 0, v[250:251]
	s_waitcnt lgkmcnt(4)
	global_store_dwordx4 v[236:237], v[240:243], off
	s_and_b64 vcc, exec, s[6:7]
	s_mov_b64 s[0:1], -1
	v_or_b32_e32 v80, 48, v144
	v_ashrrev_i32_e32 v81, 31, v80
	s_cbranch_vccnz .LBB0_1366
	v_lshlrev_b64 v[82:83], 6, v[80:81]
	v_lshl_add_u64 v[94:95], s[10:11], 0, v[82:83]
	global_load_dwordx4 v[82:85], v[94:95], off
	global_load_dwordx4 v[86:89], v[94:95], off offset:16
	global_load_dwordx4 v[90:93], v[94:95], off offset:32
	s_nop 0
	global_load_dwordx4 v[94:97], v[94:95], off offset:48
	s_waitcnt vmcnt(0)
	v_mov_b32_e32 v98, v83
	v_mov_b32_e32 v99, v84
	v_mov_b32_e32 v83, v85
	v_mov_b32_e32 v84, v87
	v_mov_b32_e32 v85, v88
	v_mov_b32_e32 v87, v89
	v_pk_add_f32 v[82:83], v[98:99], v[82:83]
	v_pk_add_f32 v[84:85], v[84:85], v[86:87]
	v_pk_add_f32 v[82:83], v[82:83], v[82:83] op_sel:[0,1] op_sel_hi:[1,0]
	v_pk_add_f32 v[84:85], v[84:85], v[84:85] op_sel:[0,1] op_sel_hi:[1,0]
	v_add_f32_e32 v88, v90, v91
	v_add_f32_e32 v90, v92, v93
	v_mov_b32_e32 v89, v96
	v_mov_b32_e32 v91, v97
	v_mov_b32_e32 v83, v94
	v_mov_b32_e32 v85, v95
	v_pk_add_f32 v[86:87], v[88:89], v[90:91]
	v_pk_add_f32 v[82:83], v[82:83], v[84:85]
	s_nop 0
	v_pk_add_f32 v[82:83], v[82:83], v[86:87]
	s_nop 0
	v_add_f32_e32 v82, v82, v83
	v_fmamk_f32 v82, v82, 0x3a800000, v156
	v_mul_f32_e32 v83, 0x4f800000, v82
	v_cmp_gt_f32_e32 vcc, s55, v82
	s_nop 1
	v_cndmask_b32_e32 v82, v82, v83, vcc
	v_sqrt_f32_e32 v83, v82
	s_nop 0
	v_add_u32_e32 v84, -1, v83
	v_add_u32_e32 v85, 1, v83
	v_fma_f32 v86, -v84, v83, v82
	v_fma_f32 v87, -v85, v83, v82
	v_cmp_ge_f32_e64 s[0:1], 0, v86
	s_nop 1
	v_cndmask_b32_e64 v83, v83, v84, s[0:1]
	v_cmp_lt_f32_e64 s[0:1], 0, v87
	s_nop 1
	v_cndmask_b32_e64 v83, v83, v85, s[0:1]
	v_mul_f32_e32 v84, 0x37800000, v83
	v_cndmask_b32_e32 v83, v83, v84, vcc
	v_cmp_class_f32_e32 vcc, v82, v157
	s_nop 1
	v_cndmask_b32_e32 v82, v83, v82, vcc
	v_div_scale_f32 v83, s[0:1], v82, v82, 1.0
	v_rcp_f32_e32 v84, v83
	v_div_scale_f32 v85, vcc, 1.0, v82, 1.0
	s_mov_b64 s[0:1], 0
	v_fma_f32 v86, -v83, v84, 1.0
	v_fmac_f32_e32 v84, v86, v84
	v_mul_f32_e32 v86, v85, v84
	v_fma_f32 v87, -v83, v86, v85
	v_fmac_f32_e32 v86, v87, v84
	v_fma_f32 v83, -v83, v86, v85
	v_div_fmas_f32 v83, v83, v84, v86
	v_div_fixup_f32 v82, v83, v82, 1.0

; __device__ __forceinline__ unsigned cvt_pk_bf16(float lo, float hi) { unsigned r; asm volatile("v_cvt_pk_bf16_f32 %0, %1, %2" : "=v"(r) : "v"(lo), "v"(hi)); return r; }
; __device__ __forceinline__ float row_rstd(const float* part, int row, float eps) {
;     const f32x4* p = (const f32x4*)(part + (size_t)row * 16);
;     const f32x4 a = p[0], b = p[1], c = p[2], d = p[3];
;     const float s = ((a[0] + a[1]) + (a[2] + a[3])) + ((b[0] + b[1]) + (b[2] + b[3])) + ((c[0] + c[1]) + (c[2] + c[3])) + ((d[0] + d[1]) + (d[2] + d[3]));
;     return 1.0f / sqrtf(s * (1.0f / 1024.0f) + eps);
; }
;     __device__ __forceinline__ void operator()(const f32x4 (&acc)[2][2][4][2], const Unit& u, int wr, int wc, int fr, int fq) const {
;     ...
;                 const int row = row0 + ai * HALF + m * 16; bf16_t* rowp = O + (size_t)row * ldc + col0;
;                 const float r = (slot >= 0 ? tab[slot * 256 + (row - u.pm * BM)] : row_rstd(sspart, row, eps)) * sc;
; #pragma unroll
;                 for (int bj = 0; bj < 2; ++bj) {
;                     f32x4 v0 = acc[ai][bj][m][0] * r, v1 = acc[ai][bj][m][1] * r;
;                     if (ACT == 1) {
; #pragma unroll
;                         for (int e = 0; e < 4; ++e) { const float a = fmaxf(v0[e], 0.f), b = fmaxf(v1[e], 0.f); v0[e] = a * a; v1[e] = b * b; }
;                     }
;                     u32x4 w; w.x = cvt_pk_bf16(v0[0], v0[1]); w.y = cvt_pk_bf16(v0[2], v0[3]); w.z = cvt_pk_bf16(v1[0], v1[1]); w.w = cvt_pk_bf16(v1[2], v1[3]);
;                     *(u32x4*)(rowp + bj * HALF) = w;
.LBB0_1368:
	s_waitcnt lgkmcnt(0)
	v_pk_mul_f32 v[72:73], v[72:73], v[82:83] op_sel_hi:[1,0]
	v_pk_mul_f32 v[76:77], v[76:77], v[82:83] op_sel_hi:[1,0]
	v_pk_mul_f32 v[74:75], v[74:75], v[82:83] op_sel_hi:[1,0]
	v_max_f32_e32 v72, 0, v72
	v_lshlrev_b64 v[80:81], 13, v[80:81]
	v_pk_mul_f32 v[78:79], v[78:79], v[82:83] op_sel_hi:[1,0]
	v_mul_f32_e32 v83, v72, v72
	v_max_f32_e32 v72, 0, v77
	v_max_f32_e32 v73, 0, v73
	v_max_f32_e32 v74, 0, v74
	v_lshl_add_u64 v[80:81], s[14:15], 0, v[80:81]
	v_max_f32_e32 v76, 0, v76
	v_mul_f32_e32 v72, v72, v72
	v_mul_f32_e32 v77, v73, v73
	v_max_f32_e32 v73, 0, v78
	v_mul_f32_e32 v78, v74, v74
	v_max_f32_e32 v74, 0, v79
	v_max_f32_e32 v75, 0, v75
	v_pk_mul_f32 v[64:65], v[64:65], v[82:83] op_sel_hi:[1,0]
	v_lshl_add_u64 v[80:81], v[146:147], 1, v[80:81]
	v_mul_f32_e32 v76, v76, v76
	v_mul_f32_e32 v73, v73, v73
	v_mul_f32_e32 v74, v74, v74
	v_mul_f32_e32 v75, v75, v75
	v_cvt_pk_bf16_f32 v72, v76, v72
	v_pk_mul_f32 v[68:69], v[68:69], v[82:83] op_sel_hi:[1,0]
	v_pk_mul_f32 v[66:67], v[66:67], v[82:83] op_sel_hi:[1,0]
	v_max_f32_e32 v64, 0, v64
	v_cvt_pk_bf16_f32 v73, v73, v74
	v_cvt_pk_bf16_f32 v74, v83, v77
	v_cvt_pk_bf16_f32 v75, v78, v75
	ds_bpermute_b32 v240, v253, v72
	ds_bpermute_b32 v241, v253, v73
	ds_bpermute_b32 v242, v253, v74
	ds_bpermute_b32 v243, v253, v75
	v_lshl_add_u64 v[236:237], v[80:81], 0, v[250:251]
	s_waitcnt lgkmcnt(4)
	global_store_dwordx4 v[238:239], v[244:247], off offset:256
	v_pk_mul_f32 v[70:71], v[70:71], v[82:83] op_sel_hi:[1,0]
	v_max_f32_e32 v65, 0, v65
	v_mul_f32_e32 v72, v64, v64
	v_max_f32_e32 v64, 0, v69
	v_max_f32_e32 v66, 0, v66
	v_max_f32_e32 v68, 0, v68
	v_mul_f32_e32 v64, v64, v64
	v_mul_f32_e32 v69, v65, v65
	v_max_f32_e32 v65, 0, v70
	v_mul_f32_e32 v70, v66, v66
	v_max_f32_e32 v66, 0, v71
	v_max_f32_e32 v67, 0, v67
	v_mul_f32_e32 v68, v68, v68
	v_mul_f32_e32 v65, v65, v65
	v_mul_f32_e32 v66, v66, v66
	v_mul_f32_e32 v67, v67, v67
	v_cvt_pk_bf16_f32 v64, v68, v64
	v_cvt_pk_bf16_f32 v65, v65, v66
	v_cvt_pk_bf16_f32 v66, v72, v69
	v_cvt_pk_bf16_f32 v67, v70, v67
	ds_bpermute_b32 v244, v253, v64
	ds_bpermute_b32 v245, v253, v65
	ds_bpermute_b32 v246, v253, v66
	ds_bpermute_b32 v247, v253, v67
	v_lshl_add_u64 v[238:239], v[80:81], 0, v[250:251]
	s_waitcnt lgkmcnt(4)
	global_store_dwordx4 v[236:237], v[240:243], off
	s_and_b64 vcc, exec, s[6:7]
	s_mov_b64 s[0:1], -1
	v_add_u32_e32 v64, 0x80, v144
	v_ashrrev_i32_e32 v65, 31, v64
	s_cbranch_vccnz .LBB0_1370
	v_lshlrev_b64 v[66:67], 6, v[64:65]
	v_lshl_add_u64 v[78:79], s[10:11], 0, v[66:67]
	global_load_dwordx4 v[66:69], v[78:79], off
	global_load_dwordx4 v[70:73], v[78:79], off offset:16
	global_load_dwordx4 v[74:77], v[78:79], off offset:32
	s_nop 0
	global_load_dwordx4 v[78:81], v[78:79], off offset:48
	s_waitcnt vmcnt(0)
	v_mov_b32_e32 v82, v67
	v_mov_b32_e32 v83, v68
	v_mov_b32_e32 v67, v69
	v_mov_b32_e32 v68, v71
	v_mov_b32_e32 v69, v72
	v_mov_b32_e32 v71, v73
	v_pk_add_f32 v[66:67], v[82:83], v[66:67]
	v_pk_add_f32 v[68:69], v[68:69], v[70:71]
	v_pk_add_f32 v[66:67], v[66:67], v[66:67] op_sel:[0,1] op_sel_hi:[1,0]
	v_pk_add_f32 v[68:69], v[68:69], v[68:69] op_sel:[0,1] op_sel_hi:[1,0]
	v_add_f32_e32 v72, v74, v75
	v_add_f32_e32 v74, v76, v77
	v_mov_b32_e32 v73, v80
	v_mov_b32_e32 v75, v81
	v_mov_b32_e32 v67, v78
	v_mov_b32_e32 v69, v79
	v_pk_add_f32 v[70:71], v[72:73], v[74:75]
	v_pk_add_f32 v[66:67], v[66:67], v[68:69]
	s_nop 0
	v_pk_add_f32 v[66:67], v[66:67], v[70:71]
	s_nop 0
	v_add_f32_e32 v66, v66, v67
	v_fmamk_f32 v66, v66, 0x3a800000, v156
	v_mul_f32_e32 v67, 0x4f800000, v66
	v_cmp_gt_f32_e32 vcc, s55, v66
	s_nop 1
	v_cndmask_b32_e32 v66, v66, v67, vcc
	v_sqrt_f32_e32 v67, v66
	s_nop 0
	v_add_u32_e32 v68, -1, v67
	v_add_u32_e32 v69, 1, v67
	v_fma_f32 v70, -v68, v67, v66
	v_fma_f32 v71, -v69, v67, v66
	v_cmp_ge_f32_e64 s[0:1], 0, v70
	s_nop 1
	v_cndmask_b32_e64 v67, v67, v68, s[0:1]
	v_cmp_lt_f32_e64 s[0:1], 0, v71
	s_nop 1
	v_cndmask_b32_e64 v67, v67, v69, s[0:1]
	v_mul_f32_e32 v68, 0x37800000, v67
	v_cndmask_b32_e32 v67, v67, v68, vcc
	v_cmp_class_f32_e32 vcc, v66, v157
	s_nop 1
	v_cndmask_b32_e32 v66, v67, v66, vcc
	v_div_scale_f32 v67, s[0:1], v66, v66, 1.0
	v_rcp_f32_e32 v68, v67
	v_div_scale_f32 v69, vcc, 1.0, v66, 1.0
	s_mov_b64 s[0:1], 0
	v_fma_f32 v70, -v67, v68, 1.0
	v_fmac_f32_e32 v68, v70, v68
	v_mul_f32_e32 v70, v69, v68
	v_fma_f32 v71, -v67, v70, v69
	v_fmac_f32_e32 v70, v71, v68
	v_fma_f32 v67, -v67, v70, v69
	v_div_fmas_f32 v67, v67, v68, v70
	v_div_fixup_f32 v66, v67, v66, 1.0

; __device__ __forceinline__ unsigned cvt_pk_bf16(float lo, float hi) { unsigned r; asm volatile("v_cvt_pk_bf16_f32 %0, %1, %2" : "=v"(r) : "v"(lo), "v"(hi)); return r; }
; __device__ __forceinline__ float row_rstd(const float* part, int row, float eps) {
;     const f32x4* p = (const f32x4*)(part + (size_t)row * 16);
;     const f32x4 a = p[0], b = p[1], c = p[2], d = p[3];
;     const float s = ((a[0] + a[1]) + (a[2] + a[3])) + ((b[0] + b[1]) + (b[2] + b[3])) + ((c[0] + c[1]) + (c[2] + c[3])) + ((d[0] + d[1]) + (d[2] + d[3]));
;     return 1.0f / sqrtf(s * (1.0f / 1024.0f) + eps);
; }
;     __device__ __forceinline__ void operator()(const f32x4 (&acc)[2][2][4][2], const Unit& u, int wr, int wc, int fr, int fq) const {
;     ...
;                 const int row = row0 + ai * HALF + m * 16; bf16_t* rowp = O + (size_t)row * ldc + col0;
;                 const float r = (slot >= 0 ? tab[slot * 256 + (row - u.pm * BM)] : row_rstd(sspart, row, eps)) * sc;
; #pragma unroll
;                 for (int bj = 0; bj < 2; ++bj) {
;                     f32x4 v0 = acc[ai][bj][m][0] * r, v1 = acc[ai][bj][m][1] * r;
;                     if (ACT == 1) {
; #pragma unroll
;                         for (int e = 0; e < 4; ++e) { const float a = fmaxf(v0[e], 0.f), b = fmaxf(v1[e], 0.f); v0[e] = a * a; v1[e] = b * b; }
;                     }
;                     u32x4 w; w.x = cvt_pk_bf16(v0[0], v0[1]); w.y = cvt_pk_bf16(v0[2], v0[3]); w.z = cvt_pk_bf16(v1[0], v1[1]); w.w = cvt_pk_bf16(v1[2], v1[3]);
;                     *(u32x4*)(rowp + bj * HALF) = w;
.LBB0_1372:
	s_waitcnt lgkmcnt(0)
	v_pk_mul_f32 v[56:57], v[56:57], v[66:67] op_sel_hi:[1,0]
	v_pk_mul_f32 v[60:61], v[60:61], v[66:67] op_sel_hi:[1,0]
	v_pk_mul_f32 v[58:59], v[58:59], v[66:67] op_sel_hi:[1,0]
	v_max_f32_e32 v56, 0, v56
	v_lshlrev_b64 v[64:65], 13, v[64:65]
	v_pk_mul_f32 v[62:63], v[62:63], v[66:67] op_sel_hi:[1,0]
	v_mul_f32_e32 v67, v56, v56
	v_max_f32_e32 v56, 0, v61
	v_max_f32_e32 v57, 0, v57
	v_max_f32_e32 v58, 0, v58
	v_lshl_add_u64 v[64:65], s[14:15], 0, v[64:65]
	v_max_f32_e32 v60, 0, v60
	v_mul_f32_e32 v56, v56, v56
	v_mul_f32_e32 v61, v57, v57
	v_max_f32_e32 v57, 0, v62
	v_mul_f32_e32 v62, v58, v58
	v_max_f32_e32 v58, 0, v63
	v_max_f32_e32 v59, 0, v59
	v_pk_mul_f32 v[48:49], v[48:49], v[66:67] op_sel_hi:[1,0]
	v_lshl_add_u64 v[64:65], v[146:147], 1, v[64:65]
	v_mul_f32_e32 v60, v60, v60
	v_mul_f32_e32 v57, v57, v57
	v_mul_f32_e32 v58, v58, v58
	v_mul_f32_e32 v59, v59, v59
	v_cvt_pk_bf16_f32 v56, v60, v56
	v_pk_mul_f32 v[52:53], v[52:53], v[66:67] op_sel_hi:[1,0]
	v_pk_mul_f32 v[50:51], v[50:51], v[66:67] op_sel_hi:[1,0]
	v_max_f32_e32 v48, 0, v48
	v_cvt_pk_bf16_f32 v57, v57, v58
	v_cvt_pk_bf16_f32 v58, v67, v61
	v_cvt_pk_bf16_f32 v59, v62, v59
	ds_bpermute_b32 v240, v253, v56
	ds_bpermute_b32 v241, v253, v57
	ds_bpermute_b32 v242, v253, v58
	ds_bpermute_b32 v243, v253, v59
	v_lshl_add_u64 v[236:237], v[64:65], 0, v[250:251]
	s_waitcnt lgkmcnt(4)
	global_store_dwordx4 v[238:239], v[244:247], off offset:256
	v_pk_mul_f32 v[54:55], v[54:55], v[66:67] op_sel_hi:[1,0]
	v_max_f32_e32 v49, 0, v49
	v_mul_f32_e32 v56, v48, v48
	v_max_f32_e32 v48, 0, v53
	v_max_f32_e32 v50, 0, v50
	v_max_f32_e32 v52, 0, v52
	v_mul_f32_e32 v48, v48, v48
	v_mul_f32_e32 v53, v49, v49
	v_max_f32_e32 v49, 0, v54
	v_mul_f32_e32 v54, v50, v50
	v_max_f32_e32 v50, 0, v55
	v_max_f32_e32 v51, 0, v51
	v_mul_f32_e32 v52, v52, v52
	v_mul_f32_e32 v49, v49, v49
	v_mul_f32_e32 v50, v50, v50
	v_mul_f32_e32 v51, v51, v51
	v_cvt_pk_bf16_f32 v48, v52, v48
	v_cvt_pk_bf16_f32 v49, v49, v50
	v_cvt_pk_bf16_f32 v50, v56, v53
	v_cvt_pk_bf16_f32 v51, v54, v51
	ds_bpermute_b32 v244, v253, v48
	ds_bpermute_b32 v245, v253, v49
	ds_bpermute_b32 v246, v253, v50
	ds_bpermute_b32 v247, v253, v51
	v_lshl_add_u64 v[238:239], v[64:65], 0, v[250:251]
	s_waitcnt lgkmcnt(4)
	global_store_dwordx4 v[236:237], v[240:243], off
	s_and_b64 vcc, exec, s[6:7]
	s_mov_b64 s[0:1], -1
	v_add_u32_e32 v48, 0x90, v144
	v_ashrrev_i32_e32 v49, 31, v48
	s_cbranch_vccnz .LBB0_1374
	v_lshlrev_b64 v[50:51], 6, v[48:49]
	v_lshl_add_u64 v[62:63], s[10:11], 0, v[50:51]
	global_load_dwordx4 v[50:53], v[62:63], off
	global_load_dwordx4 v[54:57], v[62:63], off offset:16
	global_load_dwordx4 v[58:61], v[62:63], off offset:32
	s_nop 0
	global_load_dwordx4 v[62:65], v[62:63], off offset:48
	s_waitcnt vmcnt(0)
	v_mov_b32_e32 v66, v51
	v_mov_b32_e32 v67, v52
	v_mov_b32_e32 v51, v53
	v_mov_b32_e32 v52, v55
	v_mov_b32_e32 v53, v56
	v_mov_b32_e32 v55, v57
	v_pk_add_f32 v[50:51], v[66:67], v[50:51]
	v_pk_add_f32 v[52:53], v[52:53], v[54:55]
	v_pk_add_f32 v[50:51], v[50:51], v[50:51] op_sel:[0,1] op_sel_hi:[1,0]
	v_pk_add_f32 v[52:53], v[52:53], v[52:53] op_sel:[0,1] op_sel_hi:[1,0]
	v_add_f32_e32 v56, v58, v59
	v_add_f32_e32 v58, v60, v61
	v_mov_b32_e32 v57, v64
	v_mov_b32_e32 v59, v65
	v_mov_b32_e32 v51, v62
	v_mov_b32_e32 v53, v63
	v_pk_add_f32 v[54:55], v[56:57], v[58:59]
	v_pk_add_f32 v[50:51], v[50:51], v[52:53]
	s_nop 0
	v_pk_add_f32 v[50:51], v[50:51], v[54:55]
	s_nop 0
	v_add_f32_e32 v50, v50, v51
	v_fmamk_f32 v50, v50, 0x3a800000, v156
	v_mul_f32_e32 v51, 0x4f800000, v50
	v_cmp_gt_f32_e32 vcc, s55, v50
	s_nop 1
	v_cndmask_b32_e32 v50, v50, v51, vcc
	v_sqrt_f32_e32 v51, v50
	s_nop 0
	v_add_u32_e32 v52, -1, v51
	v_add_u32_e32 v53, 1, v51
	v_fma_f32 v54, -v52, v51, v50
	v_fma_f32 v55, -v53, v51, v50
	v_cmp_ge_f32_e64 s[0:1], 0, v54
	s_nop 1
	v_cndmask_b32_e64 v51, v51, v52, s[0:1]
	v_cmp_lt_f32_e64 s[0:1], 0, v55
	s_nop 1
	v_cndmask_b32_e64 v51, v51, v53, s[0:1]
	v_mul_f32_e32 v52, 0x37800000, v51
	v_cndmask_b32_e32 v51, v51, v52, vcc
	v_cmp_class_f32_e32 vcc, v50, v157
	s_nop 1
	v_cndmask_b32_e32 v50, v51, v50, vcc
	v_div_scale_f32 v51, s[0:1], v50, v50, 1.0
	v_rcp_f32_e32 v52, v51
	v_div_scale_f32 v53, vcc, 1.0, v50, 1.0
	s_mov_b64 s[0:1], 0
	v_fma_f32 v54, -v51, v52, 1.0
	v_fmac_f32_e32 v52, v54, v52
	v_mul_f32_e32 v54, v53, v52
	v_fma_f32 v55, -v51, v54, v53
	v_fmac_f32_e32 v54, v55, v52
	v_fma_f32 v51, -v51, v54, v53
	v_div_fmas_f32 v51, v51, v52, v54
	v_div_fixup_f32 v50, v51, v50, 1.0

; __device__ __forceinline__ unsigned cvt_pk_bf16(float lo, float hi) { unsigned r; asm volatile("v_cvt_pk_bf16_f32 %0, %1, %2" : "=v"(r) : "v"(lo), "v"(hi)); return r; }
; __device__ __forceinline__ float row_rstd(const float* part, int row, float eps) {
;     const f32x4* p = (const f32x4*)(part + (size_t)row * 16);
;     const f32x4 a = p[0], b = p[1], c = p[2], d = p[3];
;     const float s = ((a[0] + a[1]) + (a[2] + a[3])) + ((b[0] + b[1]) + (b[2] + b[3])) + ((c[0] + c[1]) + (c[2] + c[3])) + ((d[0] + d[1]) + (d[2] + d[3]));
;     return 1.0f / sqrtf(s * (1.0f / 1024.0f) + eps);
; }
;     __device__ __forceinline__ void operator()(const f32x4 (&acc)[2][2][4][2], const Unit& u, int wr, int wc, int fr, int fq) const {
;     ...
;                 const int row = row0 + ai * HALF + m * 16; bf16_t* rowp = O + (size_t)row * ldc + col0;
;                 const float r = (slot >= 0 ? tab[slot * 256 + (row - u.pm * BM)] : row_rstd(sspart, row, eps)) * sc;
; #pragma unroll
;                 for (int bj = 0; bj < 2; ++bj) {
;                     f32x4 v0 = acc[ai][bj][m][0] * r, v1 = acc[ai][bj][m][1] * r;
;                     if (ACT == 1) {
; #pragma unroll
;                         for (int e = 0; e < 4; ++e) { const float a = fmaxf(v0[e], 0.f), b = fmaxf(v1[e], 0.f); v0[e] = a * a; v1[e] = b * b; }
;                     }
;                     u32x4 w; w.x = cvt_pk_bf16(v0[0], v0[1]); w.y = cvt_pk_bf16(v0[2], v0[3]); w.z = cvt_pk_bf16(v1[0], v1[1]); w.w = cvt_pk_bf16(v1[2], v1[3]);
;                     *(u32x4*)(rowp + bj * HALF) = w;
.LBB0_1376:
	s_waitcnt lgkmcnt(0)
	v_pk_mul_f32 v[40:41], v[40:41], v[50:51] op_sel_hi:[1,0]
	v_pk_mul_f32 v[44:45], v[44:45], v[50:51] op_sel_hi:[1,0]
	v_pk_mul_f32 v[42:43], v[42:43], v[50:51] op_sel_hi:[1,0]
	v_max_f32_e32 v40, 0, v40
	v_lshlrev_b64 v[48:49], 13, v[48:49]
	v_pk_mul_f32 v[46:47], v[46:47], v[50:51] op_sel_hi:[1,0]
	v_mul_f32_e32 v51, v40, v40
	v_max_f32_e32 v40, 0, v45
	v_max_f32_e32 v41, 0, v41
	v_max_f32_e32 v42, 0, v42
	v_lshl_add_u64 v[48:49], s[14:15], 0, v[48:49]
	v_max_f32_e32 v44, 0, v44
	v_mul_f32_e32 v40, v40, v40
	v_mul_f32_e32 v45, v41, v41
	v_max_f32_e32 v41, 0, v46
	v_mul_f32_e32 v46, v42, v42
	v_max_f32_e32 v42, 0, v47
	v_max_f32_e32 v43, 0, v43
	v_pk_mul_f32 v[32:33], v[32:33], v[50:51] op_sel_hi:[1,0]
	v_lshl_add_u64 v[48:49], v[146:147], 1, v[48:49]
	v_mul_f32_e32 v44, v44, v44
	v_mul_f32_e32 v41, v41, v41
	v_mul_f32_e32 v42, v42, v42
	v_mul_f32_e32 v43, v43, v43
	v_cvt_pk_bf16_f32 v40, v44, v40
	v_pk_mul_f32 v[36:37], v[36:37], v[50:51] op_sel_hi:[1,0]
	v_pk_mul_f32 v[34:35], v[34:35], v[50:51] op_sel_hi:[1,0]
	v_max_f32_e32 v32, 0, v32
	v_cvt_pk_bf16_f32 v41, v41, v42
	v_cvt_pk_bf16_f32 v42, v51, v45
	v_cvt_pk_bf16_f32 v43, v46, v43
	ds_bpermute_b32 v240, v253, v40
	ds_bpermute_b32 v241, v253, v41
	ds_bpermute_b32 v242, v253, v42
	ds_bpermute_b32 v243, v253, v43
	v_lshl_add_u64 v[236:237], v[48:49], 0, v[250:251]
	s_waitcnt lgkmcnt(4)
	global_store_dwordx4 v[238:239], v[244:247], off offset:256
	v_pk_mul_f32 v[38:39], v[38:39], v[50:51] op_sel_hi:[1,0]
	v_max_f32_e32 v33, 0, v33
	v_mul_f32_e32 v40, v32, v32
	v_max_f32_e32 v32, 0, v37
	v_max_f32_e32 v34, 0, v34
	v_max_f32_e32 v36, 0, v36
	v_mul_f32_e32 v32, v32, v32
	v_mul_f32_e32 v37, v33, v33
	v_max_f32_e32 v33, 0, v38
	v_mul_f32_e32 v38, v34, v34
	v_max_f32_e32 v34, 0, v39
	v_max_f32_e32 v35, 0, v35
	v_mul_f32_e32 v36, v36, v36
	v_mul_f32_e32 v33, v33, v33
	v_mul_f32_e32 v34, v34, v34
	v_mul_f32_e32 v35, v35, v35
	v_cvt_pk_bf16_f32 v32, v36, v32
	v_cvt_pk_bf16_f32 v33, v33, v34
	v_cvt_pk_bf16_f32 v34, v40, v37
	v_cvt_pk_bf16_f32 v35, v38, v35
	ds_bpermute_b32 v244, v253, v32
	ds_bpermute_b32 v245, v253, v33
	ds_bpermute_b32 v246, v253, v34
	ds_bpermute_b32 v247, v253, v35
	v_lshl_add_u64 v[238:239], v[48:49], 0, v[250:251]
	s_waitcnt lgkmcnt(4)
	global_store_dwordx4 v[236:237], v[240:243], off
	s_and_b64 vcc, exec, s[6:7]
	s_mov_b64 s[0:1], -1
	v_add_u32_e32 v32, 0xa0, v144
	v_ashrrev_i32_e32 v33, 31, v32
	s_cbranch_vccnz .LBB0_1378
	v_lshlrev_b64 v[34:35], 6, v[32:33]
	v_lshl_add_u64 v[46:47], s[10:11], 0, v[34:35]
	global_load_dwordx4 v[34:37], v[46:47], off
	global_load_dwordx4 v[38:41], v[46:47], off offset:16
	global_load_dwordx4 v[42:45], v[46:47], off offset:32
	s_nop 0
	global_load_dwordx4 v[46:49], v[46:47], off offset:48
	s_waitcnt vmcnt(0)
	v_mov_b32_e32 v50, v35
	v_mov_b32_e32 v51, v36
	v_mov_b32_e32 v35, v37
	v_mov_b32_e32 v36, v39
	v_mov_b32_e32 v37, v40
	v_mov_b32_e32 v39, v41
	v_pk_add_f32 v[34:35], v[50:51], v[34:35]
	v_pk_add_f32 v[36:37], v[36:37], v[38:39]
	v_pk_add_f32 v[34:35], v[34:35], v[34:35] op_sel:[0,1] op_sel_hi:[1,0]
	v_pk_add_f32 v[36:37], v[36:37], v[36:37] op_sel:[0,1] op_sel_hi:[1,0]
	v_add_f32_e32 v40, v42, v43
	v_add_f32_e32 v42, v44, v45
	v_mov_b32_e32 v41, v48
	v_mov_b32_e32 v43, v49
	v_mov_b32_e32 v35, v46
	v_mov_b32_e32 v37, v47
	v_pk_add_f32 v[38:39], v[40:41], v[42:43]
	v_pk_add_f32 v[34:35], v[34:35], v[36:37]
	s_nop 0
	v_pk_add_f32 v[34:35], v[34:35], v[38:39]
	s_nop 0
	v_add_f32_e32 v34, v34, v35
	v_fmamk_f32 v34, v34, 0x3a800000, v156
	v_mul_f32_e32 v35, 0x4f800000, v34
	v_cmp_gt_f32_e32 vcc, s55, v34
	s_nop 1
	v_cndmask_b32_e32 v34, v34, v35, vcc
	v_sqrt_f32_e32 v35, v34
	s_nop 0
	v_add_u32_e32 v36, -1, v35
	v_add_u32_e32 v37, 1, v35
	v_fma_f32 v38, -v36, v35, v34
	v_fma_f32 v39, -v37, v35, v34
	v_cmp_ge_f32_e64 s[0:1], 0, v38
	s_nop 1
	v_cndmask_b32_e64 v35, v35, v36, s[0:1]
	v_cmp_lt_f32_e64 s[0:1], 0, v39
	s_nop 1
	v_cndmask_b32_e64 v35, v35, v37, s[0:1]
	v_mul_f32_e32 v36, 0x37800000, v35
	v_cndmask_b32_e32 v35, v35, v36, vcc
	v_cmp_class_f32_e32 vcc, v34, v157
	s_nop 1
	v_cndmask_b32_e32 v34, v35, v34, vcc
	v_div_scale_f32 v35, s[0:1], v34, v34, 1.0
	v_rcp_f32_e32 v36, v35
	v_div_scale_f32 v37, vcc, 1.0, v34, 1.0
	s_mov_b64 s[0:1], 0
	v_fma_f32 v38, -v35, v36, 1.0
	v_fmac_f32_e32 v36, v38, v36
	v_mul_f32_e32 v38, v37, v36
	v_fma_f32 v39, -v35, v38, v37
	v_fmac_f32_e32 v38, v39, v36
	v_fma_f32 v35, -v35, v38, v37
	v_div_fmas_f32 v35, v35, v36, v38
	v_div_fixup_f32 v34, v35, v34, 1.0

; __device__ __forceinline__ unsigned cvt_pk_bf16(float lo, float hi) { unsigned r; asm volatile("v_cvt_pk_bf16_f32 %0, %1, %2" : "=v"(r) : "v"(lo), "v"(hi)); return r; }
; __device__ __forceinline__ float row_rstd(const float* part, int row, float eps) {
;     const f32x4* p = (const f32x4*)(part + (size_t)row * 16);
;     const f32x4 a = p[0], b = p[1], c = p[2], d = p[3];
;     const float s = ((a[0] + a[1]) + (a[2] + a[3])) + ((b[0] + b[1]) + (b[2] + b[3])) + ((c[0] + c[1]) + (c[2] + c[3])) + ((d[0] + d[1]) + (d[2] + d[3]));
;     return 1.0f / sqrtf(s * (1.0f / 1024.0f) + eps);
; }
;     __device__ __forceinline__ void operator()(const f32x4 (&acc)[2][2][4][2], const Unit& u, int wr, int wc, int fr, int fq) const {
;     ...
;                 const int row = row0 + ai * HALF + m * 16; bf16_t* rowp = O + (size_t)row * ldc + col0;
;                 const float r = (slot >= 0 ? tab[slot * 256 + (row - u.pm * BM)] : row_rstd(sspart, row, eps)) * sc;
; #pragma unroll
;                 for (int bj = 0; bj < 2; ++bj) {
;                     f32x4 v0 = acc[ai][bj][m][0] * r, v1 = acc[ai][bj][m][1] * r;
;                     if (ACT == 1) {
; #pragma unroll
;                         for (int e = 0; e < 4; ++e) { const float a = fmaxf(v0[e], 0.f), b = fmaxf(v1[e], 0.f); v0[e] = a * a; v1[e] = b * b; }
;                     }
;                     u32x4 w; w.x = cvt_pk_bf16(v0[0], v0[1]); w.y = cvt_pk_bf16(v0[2], v0[3]); w.z = cvt_pk_bf16(v1[0], v1[1]); w.w = cvt_pk_bf16(v1[2], v1[3]);
;                     *(u32x4*)(rowp + bj * HALF) = w;
.LBB0_1380:
	s_waitcnt lgkmcnt(0)
	v_pk_mul_f32 v[24:25], v[24:25], v[34:35] op_sel_hi:[1,0]
	v_pk_mul_f32 v[28:29], v[28:29], v[34:35] op_sel_hi:[1,0]
	v_pk_mul_f32 v[26:27], v[26:27], v[34:35] op_sel_hi:[1,0]
	v_max_f32_e32 v24, 0, v24
	v_lshlrev_b64 v[32:33], 13, v[32:33]
	v_pk_mul_f32 v[30:31], v[30:31], v[34:35] op_sel_hi:[1,0]
	v_mul_f32_e32 v35, v24, v24
	v_max_f32_e32 v24, 0, v29
	v_max_f32_e32 v25, 0, v25
	v_max_f32_e32 v26, 0, v26
	v_lshl_add_u64 v[32:33], s[14:15], 0, v[32:33]
	v_max_f32_e32 v28, 0, v28
	v_mul_f32_e32 v24, v24, v24
	v_mul_f32_e32 v29, v25, v25
	v_max_f32_e32 v25, 0, v30
	v_mul_f32_e32 v30, v26, v26
	v_max_f32_e32 v26, 0, v31
	v_max_f32_e32 v27, 0, v27
	v_pk_mul_f32 v[16:17], v[16:17], v[34:35] op_sel_hi:[1,0]
	v_lshl_add_u64 v[32:33], v[146:147], 1, v[32:33]
	v_mul_f32_e32 v28, v28, v28
	v_mul_f32_e32 v25, v25, v25
	v_mul_f32_e32 v26, v26, v26
	v_mul_f32_e32 v27, v27, v27
	v_cvt_pk_bf16_f32 v24, v28, v24
	v_pk_mul_f32 v[20:21], v[20:21], v[34:35] op_sel_hi:[1,0]
	v_pk_mul_f32 v[18:19], v[18:19], v[34:35] op_sel_hi:[1,0]
	v_max_f32_e32 v16, 0, v16
	v_cvt_pk_bf16_f32 v25, v25, v26
	v_cvt_pk_bf16_f32 v26, v35, v29
	v_cvt_pk_bf16_f32 v27, v30, v27
	ds_bpermute_b32 v240, v253, v24
	ds_bpermute_b32 v241, v253, v25
	ds_bpermute_b32 v242, v253, v26
	ds_bpermute_b32 v243, v253, v27
	v_lshl_add_u64 v[236:237], v[32:33], 0, v[250:251]
	s_waitcnt lgkmcnt(4)
	global_store_dwordx4 v[238:239], v[244:247], off offset:256
	v_pk_mul_f32 v[22:23], v[22:23], v[34:35] op_sel_hi:[1,0]
	v_max_f32_e32 v17, 0, v17
	v_mul_f32_e32 v24, v16, v16
	v_max_f32_e32 v16, 0, v21
	v_max_f32_e32 v18, 0, v18
	v_max_f32_e32 v20, 0, v20
	v_mul_f32_e32 v16, v16, v16
	v_mul_f32_e32 v21, v17, v17
	v_max_f32_e32 v17, 0, v22
	v_mul_f32_e32 v22, v18, v18
	v_max_f32_e32 v18, 0, v23
	v_max_f32_e32 v19, 0, v19
	v_mul_f32_e32 v20, v20, v20
	v_mul_f32_e32 v17, v17, v17
	v_mul_f32_e32 v18, v18, v18
	v_mul_f32_e32 v19, v19, v19
	v_cvt_pk_bf16_f32 v16, v20, v16
	v_cvt_pk_bf16_f32 v17, v17, v18
	v_cvt_pk_bf16_f32 v18, v24, v21
	v_cvt_pk_bf16_f32 v19, v22, v19
	ds_bpermute_b32 v244, v253, v16
	ds_bpermute_b32 v245, v253, v17
	ds_bpermute_b32 v246, v253, v18
	ds_bpermute_b32 v247, v253, v19
	v_lshl_add_u64 v[238:239], v[32:33], 0, v[250:251]
	s_waitcnt lgkmcnt(4)
	global_store_dwordx4 v[236:237], v[240:243], off
	s_and_b64 vcc, exec, s[6:7]
	s_mov_b64 s[0:1], -1
	v_add_u32_e32 v16, 0xb0, v144
	v_ashrrev_i32_e32 v17, 31, v16
	s_cbranch_vccnz .LBB0_1382
	v_lshlrev_b64 v[18:19], 6, v[16:17]
	v_lshl_add_u64 v[30:31], s[10:11], 0, v[18:19]
	global_load_dwordx4 v[18:21], v[30:31], off
	global_load_dwordx4 v[22:25], v[30:31], off offset:16
	global_load_dwordx4 v[26:29], v[30:31], off offset:32
	s_nop 0
	global_load_dwordx4 v[30:33], v[30:31], off offset:48
	s_waitcnt vmcnt(0)
	v_mov_b32_e32 v34, v19
	v_mov_b32_e32 v35, v20
	v_mov_b32_e32 v19, v21
	v_mov_b32_e32 v20, v23
	v_mov_b32_e32 v21, v24
	v_mov_b32_e32 v23, v25
	v_pk_add_f32 v[18:19], v[34:35], v[18:19]
	v_pk_add_f32 v[20:21], v[20:21], v[22:23]
	v_pk_add_f32 v[18:19], v[18:19], v[18:19] op_sel:[0,1] op_sel_hi:[1,0]
	v_pk_add_f32 v[20:21], v[20:21], v[20:21] op_sel:[0,1] op_sel_hi:[1,0]
	v_add_f32_e32 v24, v26, v27
	v_add_f32_e32 v26, v28, v29
	v_mov_b32_e32 v25, v32
	v_mov_b32_e32 v27, v33
	v_mov_b32_e32 v19, v30
	v_mov_b32_e32 v21, v31
	v_pk_add_f32 v[22:23], v[24:25], v[26:27]
	v_pk_add_f32 v[18:19], v[18:19], v[20:21]
	s_nop 0
	v_pk_add_f32 v[18:19], v[18:19], v[22:23]
	s_nop 0
	v_add_f32_e32 v18, v18, v19
	v_fmamk_f32 v18, v18, 0x3a800000, v156
	v_mul_f32_e32 v19, 0x4f800000, v18
	v_cmp_gt_f32_e32 vcc, s55, v18
	s_nop 1
	v_cndmask_b32_e32 v18, v18, v19, vcc
	v_sqrt_f32_e32 v19, v18
	s_nop 0
	v_add_u32_e32 v20, -1, v19
	v_add_u32_e32 v21, 1, v19
	v_fma_f32 v22, -v20, v19, v18
	v_fma_f32 v23, -v21, v19, v18
	v_cmp_ge_f32_e64 s[0:1], 0, v22
	s_nop 1
	v_cndmask_b32_e64 v19, v19, v20, s[0:1]
	v_cmp_lt_f32_e64 s[0:1], 0, v23
	s_nop 1
	v_cndmask_b32_e64 v19, v19, v21, s[0:1]
	v_mul_f32_e32 v20, 0x37800000, v19
	v_cndmask_b32_e32 v19, v19, v20, vcc
	v_cmp_class_f32_e32 vcc, v18, v157
	s_nop 1
	v_cndmask_b32_e32 v18, v19, v18, vcc
	v_div_scale_f32 v19, s[0:1], v18, v18, 1.0
	v_rcp_f32_e32 v20, v19
	v_div_scale_f32 v21, vcc, 1.0, v18, 1.0
	s_mov_b64 s[0:1], 0
	v_fma_f32 v22, -v19, v20, 1.0
	v_fmac_f32_e32 v20, v22, v20
	v_mul_f32_e32 v22, v21, v20
	v_fma_f32 v23, -v19, v22, v21
	v_fmac_f32_e32 v22, v23, v20
	v_fma_f32 v19, -v19, v22, v21
	v_div_fmas_f32 v19, v19, v20, v22
	v_div_fixup_f32 v18, v19, v18, 1.0

; __device__ __forceinline__ unsigned cvt_pk_bf16(float lo, float hi) { unsigned r; asm volatile("v_cvt_pk_bf16_f32 %0, %1, %2" : "=v"(r) : "v"(lo), "v"(hi)); return r; }
; #define PG8_BAR __builtin_amdgcn_s_barrier()
;     __device__ __forceinline__ void operator()(const f32x4 (&acc)[2][2][4][2], const Unit& u, int wr, int wc, int fr, int fq) const {
;     ...
;                 const int row = row0 + ai * HALF + m * 16; bf16_t* rowp = O + (size_t)row * ldc + col0;
;                 const float r = (slot >= 0 ? tab[slot * 256 + (row - u.pm * BM)] : row_rstd(sspart, row, eps)) * sc;
; #pragma unroll
;                 for (int bj = 0; bj < 2; ++bj) {
;                     f32x4 v0 = acc[ai][bj][m][0] * r, v1 = acc[ai][bj][m][1] * r;
;                     if (ACT == 1) {
; #pragma unroll
;                         for (int e = 0; e < 4; ++e) { const float a = fmaxf(v0[e], 0.f), b = fmaxf(v1[e], 0.f); v0[e] = a * a; v1[e] = b * b; }
;                     }
;                     u32x4 w; w.x = cvt_pk_bf16(v0[0], v0[1]); w.y = cvt_pk_bf16(v0[2], v0[3]); w.z = cvt_pk_bf16(v1[0], v1[1]); w.w = cvt_pk_bf16(v1[2], v1[3]);
;                     *(u32x4*)(rowp + bj * HALF) = w;
; template <class Epi, class Sched, bool ALIGN_EPI = false, bool SP2 = false>
; __device__ __forceinline__ void gemm_phase(PG8_LAS unsigned char* lds, const Gemm g, const Sched& S, const Epi& E, const int wv  ) {
;     ...
;         if (!has_next) break;
; #pragma unroll
;         for (int a = 0; a < 2; ++a)
; #pragma unroll
;             for (int b = 0; b < 2; ++b)
; #pragma unroll
;                 for (int m = 0; m < 4; ++m)
; #pragma unroll
;                     for (int n = 0; n < 2; ++n) acc[a][b][m][n] = (f32x4){0.f, 0.f, 0.f, 0.f};
;         cur = nxt; cA = nA; cB = nB; ++ui;
;         if constexpr (ALIGN_EPI) { if (wr == 1) PG8_BAR; }
.LBB0_1384:
	s_waitcnt lgkmcnt(0)
	v_pk_mul_f32 v[8:9], v[8:9], v[18:19] op_sel_hi:[1,0]
	v_pk_mul_f32 v[12:13], v[12:13], v[18:19] op_sel_hi:[1,0]
	v_pk_mul_f32 v[10:11], v[10:11], v[18:19] op_sel_hi:[1,0]
	v_max_f32_e32 v8, 0, v8
	v_lshlrev_b64 v[16:17], 13, v[16:17]
	v_pk_mul_f32 v[14:15], v[14:15], v[18:19] op_sel_hi:[1,0]
	v_mul_f32_e32 v19, v8, v8
	v_max_f32_e32 v8, 0, v13
	v_max_f32_e32 v9, 0, v9
	v_max_f32_e32 v10, 0, v10
	v_lshl_add_u64 v[16:17], s[14:15], 0, v[16:17]
	v_max_f32_e32 v12, 0, v12
	v_mul_f32_e32 v8, v8, v8
	v_mul_f32_e32 v13, v9, v9
	v_max_f32_e32 v9, 0, v14
	v_mul_f32_e32 v14, v10, v10
	v_max_f32_e32 v10, 0, v15
	v_max_f32_e32 v11, 0, v11
	v_pk_mul_f32 v[2:3], v[2:3], v[18:19] op_sel_hi:[1,0]
	v_pk_mul_f32 v[0:1], v[0:1], v[18:19] op_sel_hi:[1,0]
	v_lshl_add_u64 v[16:17], v[146:147], 1, v[16:17]
	v_mul_f32_e32 v12, v12, v12
	v_mul_f32_e32 v9, v9, v9
	v_mul_f32_e32 v10, v10, v10
	v_mul_f32_e32 v11, v11, v11
	v_cvt_pk_bf16_f32 v8, v12, v8
	v_pk_mul_f32 v[6:7], v[6:7], v[18:19] op_sel_hi:[1,0]
	v_pk_mul_f32 v[4:5], v[4:5], v[18:19] op_sel_hi:[1,0]
	v_max_f32_e32 v0, 0, v0
	v_max_f32_e32 v1, 0, v1
	v_max_f32_e32 v2, 0, v2
	v_cvt_pk_bf16_f32 v9, v9, v10
	v_cvt_pk_bf16_f32 v10, v19, v13
	v_cvt_pk_bf16_f32 v11, v14, v11
	ds_bpermute_b32 v240, v253, v8
	ds_bpermute_b32 v241, v253, v9
	ds_bpermute_b32 v242, v253, v10
	ds_bpermute_b32 v243, v253, v11
	v_lshl_add_u64 v[236:237], v[16:17], 0, v[250:251]
	s_waitcnt lgkmcnt(4)
	global_store_dwordx4 v[238:239], v[244:247], off offset:256
	v_max_f32_e32 v3, 0, v3
	v_max_f32_e32 v4, 0, v4
	v_mul_f32_e32 v8, v0, v0
	v_max_f32_e32 v0, 0, v5
	v_mul_f32_e32 v5, v1, v1
	v_max_f32_e32 v1, 0, v6
	v_mul_f32_e32 v6, v2, v2
	v_max_f32_e32 v2, 0, v7
	v_mul_f32_e32 v0, v0, v0
	v_mul_f32_e32 v1, v1, v1
	v_mul_f32_e32 v2, v2, v2
	v_mul_f32_e32 v3, v3, v3
	s_andn2_b64 vcc, exec, s[4:5]
	s_mov_b64 s[0:1], -1
	v_mul_f32_e32 v4, v4, v4
	v_cvt_pk_bf16_f32 v0, v4, v0
	v_cvt_pk_bf16_f32 v1, v1, v2
	v_cvt_pk_bf16_f32 v2, v8, v5
	v_cvt_pk_bf16_f32 v3, v6, v3
	ds_bpermute_b32 v244, v253, v0
	ds_bpermute_b32 v245, v253, v1
	ds_bpermute_b32 v246, v253, v2
	ds_bpermute_b32 v247, v253, v3
	v_lshl_add_u64 v[238:239], v[16:17], 0, v[250:251]
	s_waitcnt lgkmcnt(4)
	global_store_dwordx4 v[236:237], v[240:243], off
	s_waitcnt lgkmcnt(0)
	global_store_dwordx4 v[238:239], v[244:247], off offset:256
	s_cbranch_vccnz .LBB0_1327
	s_andn2_b64 vcc, exec, s[12:13]
	s_cbranch_vccnz .LBB0_1326
	s_barrier
	s_branch .LBB0_1326

; #define PH(k) (IN(k) && ((MK_MASK >> (k)) & 1))
; #define REPS(k) for (int rep_ = 0; rep_ < (((MK_REP_MASK) >> (k)) & 1) + 1; ++rep_)
;     __host__ __device__ __forceinline__ bool next(int i, Unit& u) const {
;         const long L = (long)i * G + c; if (L >= nwg) return false;
;         int wgid = (int)L; { const int q = nwg / NXCD, r = nwg % NXCD, xcd = wgid % NXCD, off = wgid / NXCD; wgid = (xcd < r ? xcd * (q + 1) : r * (q + 1) + (xcd - r) * q) + off; }
;         const int nig = WGM * nN, gid = wgid / nig, fm = gid * WGM, gsz = (nM - fm) < WGM ? (nM - fm) : WGM;
;         u.pm = fm + ((wgid % nig) % gsz); u.pn = (wgid % nig) / gsz; if (rev) u.pm = nM - 1 - u.pm; return true;
; __global__ void __launch_bounds__(NWAVES * 64, 2) mk_fwd(Params P) {
;     ...
;     if (PH(9)) REPS(9) { pg8::Gemm g{ZH, Wdn_t, M, D, FF}; pg8::StaticOrder S; S.init(M, D, G, bx); S.rev = true;
;         pg8::EpiRes2<true, true> E{H2B, H1B  , SS3};
;         pg8::gemm_phase<pg8::EpiRes2<true, true>, pg8::StaticOrder, true, true>(lds, g, S, E, wave); }
.LBB0_1440:
	s_cmp_lt_i32 s74, 10
	s_cselect_b64 s[2:3], -1, 0
	s_and_b64 s[0:1], s[2:3], s[0:1]
	s_andn2_b64 vcc, exec, s[0:1]
	s_cbranch_vccnz .LBB0_1479
	v_and_b32_e32 v248, 15, v212
	v_lshrrev_b32_e32 v249, 2, v212
	v_sub_u32_e32 v249, v249, v248
	v_lshrrev_b32_e32 v248, 4, v212
	v_and_b32_e32 v253, 3, v212
	v_sub_u32_e32 v248, v253, v248
	v_lshlrev_b32_e32 v248, 4, v248
	v_mul_i32_i24_e32 v250, 0x800, v249
	v_add_u32_e32 v250, v250, v248
	v_ashrrev_i32_e32 v251, 31, v250
	v_lshlrev_b32_e32 v253, 4, v253
	v_lshrrev_b32_e32 v248, 2, v212
	v_add_u32_e32 v253, v253, v248
	v_lshlrev_b32_e32 v253, 2, v253
	s_and_b32 s2, s93, 0xffffffc0
	v_mov_b32_e32 v8, v212
	s_cmpk_lt_i32 s88, 0x200
	s_cselect_b64 s[4:5], -1, 0
	v_add_u32_e32 v0, s2, v8
	s_cmpk_gt_i32 s88, 0x1ff
	v_readfirstlane_b32 s6, v0
	s_cbranch_scc1 .LBB0_1443
	s_ashr_i32 s2, s88, 31
	s_lshr_b32 s2, s2, 29
	s_add_i32 s2, s88, s2
	s_ashr_i32 s3, s2, 3
	s_and_b32 s2, s2, -8
	s_sub_i32 s2, s88, s2
	s_lshl_b32 s8, s2, 6
	s_mul_i32 s7, s2, 0x41
	s_cmp_lt_i32 s2, 0
	s_cselect_b32 s2, s7, s8
	s_add_i32 s2, s2, s3
	s_ashr_i32 s3, s2, 31
	s_lshr_b32 s3, s3, 27
	s_add_i32 s3, s2, s3
	s_ashr_i32 s7, s3, 5
	s_andn2_b32 s3, s3, 31
	s_sub_i32 s2, s2, s3
	s_bfe_i32 s3, s2, 0x80000
	s_bfe_u32 s3, s3, 0x3000c
	s_add_i32 s3, s2, s3
	s_bfe_i32 s8, s3, 0x80000
	s_and_b32 s3, s3, 0xf8
	s_sub_i32 s2, s3, s2
	s_sext_i32_i8 s2, s2
	s_lshl_b32 s3, s7, 3
	s_sext_i32_i16 s8, s8
	s_sub_i32 s2, s2, s3
	s_ashr_i32 s8, s8, 3
	s_add_i32 s34, s2, 0x7f
